# MLA loop: K-fragment LDS wait split (lgkmcnt(6) at tile start, rest before MFMA 6) on top of V reads behind the barrier
# speedup vs baseline: 1.0055x; 1.0055x over previous
.Lmy_A_entry:
	s_mov_b32 s30, 0x20000
	s_mov_b32 s31, 0
	s_mov_b32 s12, 0x1000
	s_mov_b32 s13, 0
	s_lshr_b32 s71, s24, 1
	s_lshr_b32 s79, s25, 2
	s_add_i32 s79, s79, -1
	s_barrier
	s_mov_b32 s0, 0x60000
	s_mov_b32 s1, 0
	v_lshl_add_u64 v[24:25], v[16:17], 0, s[0:1]
	s_add_u32 m0, s40, 0x9000
	s_mov_b32 s0, 0x3000
	global_load_lds_dwordx4 v[24:25], off
	v_lshl_add_u64 v[30:31], v[222:223], 0, s[0:1]
	s_add_u32 m0, s43, 0x9000
	s_nop 0
	global_load_lds_dwordx4 v[30:31], off
	s_mov_b32 s0, 0x80000
	s_mov_b32 s1, 0
	v_lshl_add_u64 v[24:25], v[16:17], 0, s[0:1]
	s_mov_b32 s0, 0x60000
	v_lshl_add_u64 v[28:29], v[224:225], 0, s[0:1]
	s_mov_b32 s0, 0x4000
	v_lshl_add_u64 v[30:31], v[222:223], 0, s[0:1]
	s_waitcnt lgkmcnt(0)
	v_mfma_f32_32x32x16_bf16 v[82:97], v[218:221], v[4:7], v[66:81]
	v_mfma_f32_32x32x16_bf16 v[98:113], v[214:217], v[4:7], v[66:81]
	v_mfma_f32_32x32x16_bf16 v[82:97], v[210:213], v[8:11], v[82:97]
	v_mfma_f32_32x32x16_bf16 v[98:113], v[206:209], v[8:11], v[98:113]
	v_mfma_f32_32x32x16_bf16 v[82:97], v[202:205], v[12:15], v[82:97]
	v_mfma_f32_32x32x16_bf16 v[98:113], v[198:201], v[12:15], v[98:113]
	v_mfma_f32_32x32x16_bf16 v[82:97], v[194:197], v[130:133], v[82:97]
	v_mfma_f32_32x32x16_bf16 v[98:113], v[190:193], v[130:133], v[98:113]
	v_mfma_f32_32x32x16_bf16 v[82:97], v[186:189], v[134:137], v[82:97]
	v_mfma_f32_32x32x16_bf16 v[98:113], v[182:185], v[134:137], v[98:113]
	v_mfma_f32_32x32x16_bf16 v[82:97], v[178:181], v[138:141], v[82:97]
	v_mfma_f32_32x32x16_bf16 v[98:113], v[174:177], v[138:141], v[98:113]
	v_add_u32_e32 v2, 0x3000, v238
	ds_read_b128 v[218:221], v2
	ds_read_b128 v[214:217], v2 offset:512
	ds_read_b128 v[210:213], v2 offset:2048
	ds_read_b128 v[206:209], v2 offset:2560
	ds_read_b128 v[202:205], v2 offset:4096
	ds_read_b128 v[198:201], v2 offset:4608
	ds_read_b128 v[194:197], v2 offset:6144
	ds_read_b128 v[190:193], v2 offset:6656
	ds_read_b128 v[186:189], v2 offset:8192
	ds_read_b128 v[182:185], v2 offset:8704
	ds_read_b128 v[178:181], v2 offset:10240
	ds_read_b128 v[174:177], v2 offset:10752
	s_nop 7
	v_max3_f32 v19, v82, v83, v84
	v_max3_f32 v26, v85, v86, v87
	v_max3_f32 v19, v19, v88, v89
	v_max3_f32 v26, v26, v90, v91
	v_max3_f32 v19, v19, v92, v93
	v_max3_f32 v26, v26, v94, v95
	v_max3_f32 v19, v19, v96, v97
	v_max3_f32 v26, v26, v98, v99
	v_max3_f32 v19, v19, v100, v101
	v_max3_f32 v26, v26, v102, v103
	v_max3_f32 v19, v19, v104, v105
	v_max3_f32 v26, v26, v106, v107
	v_max3_f32 v19, v19, v108, v109
	v_max3_f32 v26, v26, v110, v111
	v_max3_f32 v19, v19, v112, v113
	v_max_f32_e32 v19, v19, v26
	v_mov_b32_e32 v26, v19
	s_nop 1
	v_permlane32_swap_b32_e32 v19, v26
	v_max_f32_e32 v19, v19, v26
	v_max_f32_e32 v19, v19, v19
	v_mov_b32_e32 v239, v19
	v_xor_b32_e32 v66, 0x80000000, v19
	v_mov_b32_e32 v67, v66
	v_mov_b32_e32 v68, v66
	v_mov_b32_e32 v69, v66
	v_mov_b32_e32 v70, v66
	v_mov_b32_e32 v71, v66
	v_mov_b32_e32 v72, v66
	v_mov_b32_e32 v73, v66
	v_mov_b32_e32 v74, v66
	v_mov_b32_e32 v75, v66
	v_mov_b32_e32 v76, v66
	v_mov_b32_e32 v77, v66
	v_mov_b32_e32 v78, v66
	v_mov_b32_e32 v79, v66
	v_mov_b32_e32 v80, v66
	v_mov_b32_e32 v81, v66
	v_sub_f32_e32 v82, v82, v19
	v_sub_f32_e32 v83, v83, v19
	v_sub_f32_e32 v84, v84, v19
	v_sub_f32_e32 v85, v85, v19
	v_sub_f32_e32 v86, v86, v19
	v_sub_f32_e32 v87, v87, v19
	v_sub_f32_e32 v88, v88, v19
	v_sub_f32_e32 v89, v89, v19
	v_sub_f32_e32 v90, v90, v19
	v_sub_f32_e32 v91, v91, v19
	v_sub_f32_e32 v92, v92, v19
	v_sub_f32_e32 v93, v93, v19
	v_sub_f32_e32 v94, v94, v19
	v_sub_f32_e32 v95, v95, v19
	v_sub_f32_e32 v96, v96, v19
	v_sub_f32_e32 v97, v97, v19
	v_sub_f32_e32 v98, v98, v19
	v_sub_f32_e32 v99, v99, v19
	v_sub_f32_e32 v100, v100, v19
	v_sub_f32_e32 v101, v101, v19
	v_sub_f32_e32 v102, v102, v19
	v_sub_f32_e32 v103, v103, v19
	v_sub_f32_e32 v104, v104, v19
	v_sub_f32_e32 v105, v105, v19
	v_sub_f32_e32 v106, v106, v19
	v_sub_f32_e32 v107, v107, v19
	v_sub_f32_e32 v108, v108, v19
	v_sub_f32_e32 v109, v109, v19
	v_sub_f32_e32 v110, v110, v19
	v_sub_f32_e32 v111, v111, v19
	v_sub_f32_e32 v112, v112, v19
	v_sub_f32_e32 v113, v113, v19
	s_cmp_lt_i32 s79, 1
	s_cbranch_scc1 .Lmy_A_tail
	s_waitcnt lgkmcnt(6)
	v_mov_b32_e32 v2, v237
	v_mfma_f32_32x32x16_bf16 v[142:157], v[218:221], v[4:7], v[66:81]
	v_exp_f32_e32 v82, v82
	v_exp_f32_e32 v83, v83
	v_exp_f32_e32 v84, v84
	v_add_f32_e32 v27, v82, v83
	v_exp_f32_e32 v85, v85
	v_mfma_f32_32x32x16_bf16 v[158:173], v[214:217], v[4:7], v[66:81]
	v_exp_f32_e32 v86, v86
	v_add_f32_e32 v27, v27, v84
	v_exp_f32_e32 v87, v87
	v_add_f32_e32 v27, v27, v85
	v_exp_f32_e32 v88, v88
	v_mfma_f32_32x32x16_bf16 v[142:157], v[210:213], v[8:11], v[142:157]
	v_add_f32_e32 v27, v27, v86
	v_exp_f32_e32 v89, v89
	v_add_f32_e32 v27, v27, v87
	v_add_f32_e32 v27, v27, v88
	v_add_f32_e32 v27, v27, v89
	v_mfma_f32_32x32x16_bf16 v[158:173], v[206:209], v[8:11], v[158:173]
	v_cvt_pk_bf16_f32 v82, v82, v83
	v_cvt_pk_bf16_f32 v83, v84, v85
	v_cvt_pk_bf16_f32 v84, v86, v87
	v_cvt_pk_bf16_f32 v85, v88, v89
	v_mfma_f32_32x32x16_bf16 v[142:157], v[202:205], v[12:15], v[142:157]
	v_exp_f32_e32 v90, v90
	v_exp_f32_e32 v91, v91
	v_exp_f32_e32 v92, v92
	v_add_f32_e32 v27, v27, v90
	v_exp_f32_e32 v93, v93
	v_mfma_f32_32x32x16_bf16 v[158:173], v[198:201], v[12:15], v[158:173]
	v_add_f32_e32 v27, v27, v91
	v_exp_f32_e32 v94, v94
	v_add_f32_e32 v27, v27, v92
	v_exp_f32_e32 v95, v95
	v_add_f32_e32 v27, v27, v93
	s_waitcnt lgkmcnt(0)
	s_waitcnt vmcnt(3)
	s_barrier
	v_mfma_f32_32x32x16_bf16 v[142:157], v[194:197], v[130:133], v[142:157]
	s_add_u32 m0, s57, 0x6000
	v_exp_f32_e32 v96, v96
	v_add_f32_e32 v27, v27, v94
	global_load_lds_dwordx4 v[28:29], off
	v_lshl_add_u64 v[28:29], v[28:29], 0, s[30:31]
	v_exp_f32_e32 v97, v97
	v_add_f32_e32 v27, v27, v95
	v_add_f32_e32 v27, v27, v96
	ds_read_b64_tr_b16 v[114:115], v2 offset:49152
	ds_read_b64_tr_b16 v[116:117], v2 offset:49664
	ds_read_b64_tr_b16 v[118:119], v2 offset:50176
	ds_read_b64_tr_b16 v[120:121], v2 offset:50688
	v_mfma_f32_32x32x16_bf16 v[158:173], v[190:193], v[130:133], v[158:173]
	s_add_u32 m0, s40, 0x0
	v_add_f32_e32 v27, v27, v97
	v_cvt_pk_bf16_f32 v90, v90, v91
	global_load_lds_dwordx4 v[24:25], off
	v_lshl_add_u64 v[24:25], v[24:25], 0, s[30:31]
	v_cvt_pk_bf16_f32 v91, v92, v93
	v_cvt_pk_bf16_f32 v92, v94, v95
	v_cvt_pk_bf16_f32 v93, v96, v97
	ds_read_b64_tr_b16 v[122:123], v2 offset:51200
	ds_read_b64_tr_b16 v[124:125], v2 offset:51712
	ds_read_b64_tr_b16 v[126:127], v2 offset:52224
	ds_read_b64_tr_b16 v[128:129], v2 offset:52736
	v_mfma_f32_32x32x16_bf16 v[142:157], v[186:189], v[134:137], v[142:157]
	s_add_u32 m0, s43, 0x0
	v_exp_f32_e32 v98, v98
	v_exp_f32_e32 v99, v99
	global_load_lds_dwordx4 v[30:31], off
	v_lshl_add_u64 v[30:31], v[30:31], 0, s[12:13]
	v_exp_f32_e32 v100, v100
	v_add_f32_e32 v27, v27, v98
	v_exp_f32_e32 v101, v101
	ds_read_b64_tr_b16 v[240:241], v2 offset:53248
	ds_read_b64_tr_b16 v[242:243], v2 offset:53760
	ds_read_b64_tr_b16 v[244:245], v2 offset:54272
	ds_read_b64_tr_b16 v[246:247], v2 offset:54784
	v_mfma_f32_32x32x16_bf16 v[158:173], v[182:185], v[134:137], v[158:173]
	s_add_u32 m0, s40, 0x3000
	v_add_f32_e32 v27, v27, v99
	v_exp_f32_e32 v102, v102
	global_load_lds_dwordx4 v[24:25], off
	v_lshl_add_u64 v[24:25], v[24:25], 0, s[30:31]
	v_add_f32_e32 v27, v27, v100
	v_exp_f32_e32 v103, v103
	v_add_f32_e32 v27, v27, v101
	ds_read_b64_tr_b16 v[248:249], v2 offset:55296
	ds_read_b64_tr_b16 v[250:251], v2 offset:55808
	ds_read_b64_tr_b16 v[20:21], v2 offset:56320
	ds_read_b64_tr_b16 v[22:23], v2 offset:56832
	v_mfma_f32_32x32x16_bf16 v[142:157], v[178:181], v[138:141], v[142:157]
	s_add_u32 m0, s43, 0x3000
	v_exp_f32_e32 v104, v104
	v_add_f32_e32 v27, v27, v102
	global_load_lds_dwordx4 v[30:31], off
	v_lshl_add_u64 v[30:31], v[30:31], 0, s[12:13]
	v_exp_f32_e32 v105, v105
	v_add_f32_e32 v27, v27, v103
	v_add_f32_e32 v27, v27, v104
	v_mfma_f32_32x32x16_bf16 v[158:173], v[174:177], v[138:141], v[158:173]
	v_add_f32_e32 v27, v27, v105
	v_cvt_pk_bf16_f32 v98, v98, v99
	v_cvt_pk_bf16_f32 v99, v100, v101
	v_cvt_pk_bf16_f32 v100, v102, v103
	v_cvt_pk_bf16_f32 v101, v104, v105
	s_waitcnt lgkmcnt(0)
	v_add_u32_e32 v2, 0x6000, v238
	v_mfma_f32_32x32x16_bf16 v[34:49], v[82:85], v[114:117], v[34:49]
	v_exp_f32_e32 v106, v106
	v_exp_f32_e32 v107, v107
	v_exp_f32_e32 v108, v108
	v_add_f32_e32 v27, v27, v106
	v_exp_f32_e32 v109, v109
	ds_read_b128 v[218:221], v2
	ds_read_b128 v[214:217], v2 offset:512
	ds_read_b128 v[210:213], v2 offset:2048
	v_mfma_f32_32x32x16_bf16 v[50:65], v[82:85], v[240:243], v[50:65]
	v_add_f32_e32 v27, v27, v107
	v_exp_f32_e32 v110, v110
	v_add_f32_e32 v27, v27, v108
	v_exp_f32_e32 v111, v111
	v_add_f32_e32 v27, v27, v109
	ds_read_b128 v[206:209], v2 offset:2560
	ds_read_b128 v[202:205], v2 offset:4096
	ds_read_b128 v[198:201], v2 offset:4608
	v_mfma_f32_32x32x16_bf16 v[34:49], v[90:93], v[118:121], v[34:49]
	v_exp_f32_e32 v112, v112
	v_add_f32_e32 v27, v27, v110
	v_exp_f32_e32 v113, v113
	v_add_f32_e32 v27, v27, v111
	v_add_f32_e32 v27, v27, v112
	ds_read_b128 v[194:197], v2 offset:6144
	ds_read_b128 v[190:193], v2 offset:6656
	ds_read_b128 v[186:189], v2 offset:8192
	v_mfma_f32_32x32x16_bf16 v[50:65], v[90:93], v[244:247], v[50:65]
	v_add_f32_e32 v27, v27, v113
	v_cvt_pk_bf16_f32 v106, v106, v107
	v_cvt_pk_bf16_f32 v107, v108, v109
	v_cvt_pk_bf16_f32 v108, v110, v111
	v_cvt_pk_bf16_f32 v109, v112, v113
	v_add_f32_e32 v236, v236, v27
	ds_read_b128 v[182:185], v2 offset:8704
	ds_read_b128 v[178:181], v2 offset:10240
	ds_read_b128 v[174:177], v2 offset:10752
	v_mfma_f32_32x32x16_bf16 v[34:49], v[98:101], v[122:125], v[34:49]
	v_max3_f32 v19, v142, v143, v144
	v_max3_f32 v26, v145, v146, v147
	v_max3_f32 v19, v19, v148, v149
	v_max3_f32 v26, v26, v150, v151
	v_mfma_f32_32x32x16_bf16 v[50:65], v[98:101], v[248:251], v[50:65]
	v_max3_f32 v19, v19, v152, v153
	v_max3_f32 v26, v26, v154, v155
	v_max3_f32 v19, v19, v156, v157
	v_max3_f32 v26, v26, v158, v159
	v_mfma_f32_32x32x16_bf16 v[34:49], v[106:109], v[126:129], v[34:49]
	v_max3_f32 v19, v19, v160, v161
	v_max3_f32 v26, v26, v162, v163
	v_max3_f32 v19, v19, v164, v165
	v_max3_f32 v26, v26, v166, v167
	v_mfma_f32_32x32x16_bf16 v[50:65], v[106:109], v[20:23], v[50:65]
	v_max3_f32 v19, v19, v168, v169
	v_max3_f32 v26, v26, v170, v171
	v_max3_f32 v19, v19, v172, v173
	v_max_f32_e32 v19, v19, v26
	v_cmp_lt_f32_e32 vcc, s41, v19
	s_cbranch_vccz .Lmy_nors_1
	s_nop 15
	s_nop 15
	v_mov_b32_e32 v26, v19
	s_nop 1
	v_permlane32_swap_b32_e32 v19, v26
	v_max_f32_e32 v19, v19, v26
	v_max_f32_e32 v19, v19, v19
	v_max_f32_e32 v90, 0, v19
	v_exp_f32_e64 v91, -v90
	v_add_f32_e32 v239, v239, v90
	v_xor_b32_e32 v66, 0x80000000, v239
	v_mov_b32_e32 v67, v66
	v_mov_b32_e32 v68, v66
	v_mov_b32_e32 v69, v66
	v_mov_b32_e32 v70, v66
	v_mov_b32_e32 v71, v66
	v_mov_b32_e32 v72, v66
	v_mov_b32_e32 v73, v66
	v_mov_b32_e32 v74, v66
	v_mov_b32_e32 v75, v66
	v_mov_b32_e32 v76, v66
	v_mov_b32_e32 v77, v66
	v_mov_b32_e32 v78, v66
	v_mov_b32_e32 v79, v66
	v_mov_b32_e32 v80, v66
	v_mov_b32_e32 v81, v66
	v_sub_f32_e32 v142, v142, v90
	v_sub_f32_e32 v143, v143, v90
	v_sub_f32_e32 v144, v144, v90
	v_sub_f32_e32 v145, v145, v90
	v_sub_f32_e32 v146, v146, v90
	v_sub_f32_e32 v147, v147, v90
	v_sub_f32_e32 v148, v148, v90
	v_sub_f32_e32 v149, v149, v90
	v_sub_f32_e32 v150, v150, v90
	v_sub_f32_e32 v151, v151, v90
	v_sub_f32_e32 v152, v152, v90
	v_sub_f32_e32 v153, v153, v90
	v_sub_f32_e32 v154, v154, v90
	v_sub_f32_e32 v155, v155, v90
	v_sub_f32_e32 v156, v156, v90
	v_sub_f32_e32 v157, v157, v90
	v_sub_f32_e32 v158, v158, v90
	v_sub_f32_e32 v159, v159, v90
	v_sub_f32_e32 v160, v160, v90
	v_sub_f32_e32 v161, v161, v90
	v_sub_f32_e32 v162, v162, v90
	v_sub_f32_e32 v163, v163, v90
	v_sub_f32_e32 v164, v164, v90
	v_sub_f32_e32 v165, v165, v90
	v_sub_f32_e32 v166, v166, v90
	v_sub_f32_e32 v167, v167, v90
	v_sub_f32_e32 v168, v168, v90
	v_sub_f32_e32 v169, v169, v90
	v_sub_f32_e32 v170, v170, v90
	v_sub_f32_e32 v171, v171, v90
	v_sub_f32_e32 v172, v172, v90
	v_sub_f32_e32 v173, v173, v90
	v_mul_f32_e32 v236, v236, v91
	s_mov_b64 s[96:97], exec
	s_and_b64 exec, exec, s[8:9]
	ds_write_b32 v235, v91
	s_mov_b64 exec, s[96:97]
	v_lshl_add_u32 v2, v228, 4, s47
	ds_read_b128 v[94:97], v2 offset:0
	s_waitcnt lgkmcnt(0)
	v_mul_f32_e32 v34, v34, v94
	v_mul_f32_e32 v50, v50, v94
	v_mul_f32_e32 v35, v35, v95
	v_mul_f32_e32 v51, v51, v95
	v_mul_f32_e32 v36, v36, v96
	v_mul_f32_e32 v52, v52, v96
	v_mul_f32_e32 v37, v37, v97
	v_mul_f32_e32 v53, v53, v97
	ds_read_b128 v[94:97], v2 offset:32
	s_waitcnt lgkmcnt(0)
	v_mul_f32_e32 v38, v38, v94
	v_mul_f32_e32 v54, v54, v94
	v_mul_f32_e32 v39, v39, v95
	v_mul_f32_e32 v55, v55, v95
	v_mul_f32_e32 v40, v40, v96
	v_mul_f32_e32 v56, v56, v96
	v_mul_f32_e32 v41, v41, v97
	v_mul_f32_e32 v57, v57, v97
	ds_read_b128 v[94:97], v2 offset:64
	s_waitcnt lgkmcnt(0)
	v_mul_f32_e32 v42, v42, v94
	v_mul_f32_e32 v58, v58, v94
	v_mul_f32_e32 v43, v43, v95
	v_mul_f32_e32 v59, v59, v95
	v_mul_f32_e32 v44, v44, v96
	v_mul_f32_e32 v60, v60, v96
	v_mul_f32_e32 v45, v45, v97
	v_mul_f32_e32 v61, v61, v97
	ds_read_b128 v[94:97], v2 offset:96
	s_waitcnt lgkmcnt(0)
	v_mul_f32_e32 v46, v46, v94
	v_mul_f32_e32 v62, v62, v94
	v_mul_f32_e32 v47, v47, v95
	v_mul_f32_e32 v63, v63, v95
	v_mul_f32_e32 v48, v48, v96
	v_mul_f32_e32 v64, v64, v96
	v_mul_f32_e32 v49, v49, v97
	v_mul_f32_e32 v65, v65, v97
.Lmy_nors_1:
	s_waitcnt lgkmcnt(6)
	v_add_u32_e32 v2, 0x2000, v237
	v_mfma_f32_32x32x16_bf16 v[82:97], v[218:221], v[4:7], v[66:81]
	v_exp_f32_e32 v142, v142
	v_exp_f32_e32 v143, v143
	v_exp_f32_e32 v144, v144
	v_add_f32_e32 v27, v142, v143
	v_exp_f32_e32 v145, v145
	v_mfma_f32_32x32x16_bf16 v[98:113], v[214:217], v[4:7], v[66:81]
	v_exp_f32_e32 v146, v146
	v_add_f32_e32 v27, v27, v144
	v_exp_f32_e32 v147, v147
	v_add_f32_e32 v27, v27, v145
	v_exp_f32_e32 v148, v148
	v_mfma_f32_32x32x16_bf16 v[82:97], v[210:213], v[8:11], v[82:97]
	v_add_f32_e32 v27, v27, v146
	v_exp_f32_e32 v149, v149
	v_add_f32_e32 v27, v27, v147
	v_add_f32_e32 v27, v27, v148
	v_add_f32_e32 v27, v27, v149
	v_mfma_f32_32x32x16_bf16 v[98:113], v[206:209], v[8:11], v[98:113]
	v_cvt_pk_bf16_f32 v142, v142, v143
	v_cvt_pk_bf16_f32 v143, v144, v145
	v_cvt_pk_bf16_f32 v144, v146, v147
	v_cvt_pk_bf16_f32 v145, v148, v149
	v_mfma_f32_32x32x16_bf16 v[82:97], v[202:205], v[12:15], v[82:97]
	v_exp_f32_e32 v150, v150
	v_exp_f32_e32 v151, v151
	v_exp_f32_e32 v152, v152
	v_add_f32_e32 v27, v27, v150
	v_exp_f32_e32 v153, v153
	v_mfma_f32_32x32x16_bf16 v[98:113], v[198:201], v[12:15], v[98:113]
	v_add_f32_e32 v27, v27, v151
	v_exp_f32_e32 v154, v154
	v_add_f32_e32 v27, v27, v152
	v_exp_f32_e32 v155, v155
	v_add_f32_e32 v27, v27, v153
	s_waitcnt lgkmcnt(0)
	s_waitcnt vmcnt(5)
	s_barrier
	v_mfma_f32_32x32x16_bf16 v[82:97], v[194:197], v[130:133], v[82:97]
	s_add_u32 m0, s57, 0x0
	v_exp_f32_e32 v156, v156
	v_add_f32_e32 v27, v27, v154
	global_load_lds_dwordx4 v[28:29], off
	v_lshl_add_u64 v[28:29], v[28:29], 0, s[30:31]
	v_exp_f32_e32 v157, v157
	v_add_f32_e32 v27, v27, v155
	v_add_f32_e32 v27, v27, v156
	ds_read_b64_tr_b16 v[114:115], v2 offset:49152
	ds_read_b64_tr_b16 v[116:117], v2 offset:49664
	ds_read_b64_tr_b16 v[118:119], v2 offset:50176
	ds_read_b64_tr_b16 v[120:121], v2 offset:50688
	v_mfma_f32_32x32x16_bf16 v[98:113], v[190:193], v[130:133], v[98:113]
	s_add_u32 m0, s40, 0x6000
	v_add_f32_e32 v27, v27, v157
	v_cvt_pk_bf16_f32 v150, v150, v151
	global_load_lds_dwordx4 v[24:25], off
	v_lshl_add_u64 v[24:25], v[24:25], 0, s[30:31]
	v_cvt_pk_bf16_f32 v151, v152, v153
	v_cvt_pk_bf16_f32 v152, v154, v155
	v_cvt_pk_bf16_f32 v153, v156, v157
	ds_read_b64_tr_b16 v[122:123], v2 offset:51200
	ds_read_b64_tr_b16 v[124:125], v2 offset:51712
	ds_read_b64_tr_b16 v[126:127], v2 offset:52224
	ds_read_b64_tr_b16 v[128:129], v2 offset:52736
	v_mfma_f32_32x32x16_bf16 v[82:97], v[186:189], v[134:137], v[82:97]
	s_add_u32 m0, s43, 0x6000
	v_exp_f32_e32 v158, v158
	v_exp_f32_e32 v159, v159
	global_load_lds_dwordx4 v[30:31], off
	v_lshl_add_u64 v[30:31], v[30:31], 0, s[12:13]
	v_exp_f32_e32 v160, v160
	v_add_f32_e32 v27, v27, v158
	v_exp_f32_e32 v161, v161
	ds_read_b64_tr_b16 v[240:241], v2 offset:53248
	ds_read_b64_tr_b16 v[242:243], v2 offset:53760
	ds_read_b64_tr_b16 v[244:245], v2 offset:54272
	ds_read_b64_tr_b16 v[246:247], v2 offset:54784
	v_mfma_f32_32x32x16_bf16 v[98:113], v[182:185], v[134:137], v[98:113]
	v_add_f32_e32 v27, v27, v159
	v_exp_f32_e32 v162, v162
	v_add_f32_e32 v27, v27, v160
	v_exp_f32_e32 v163, v163
	v_add_f32_e32 v27, v27, v161
	ds_read_b64_tr_b16 v[248:249], v2 offset:55296
	ds_read_b64_tr_b16 v[250:251], v2 offset:55808
	ds_read_b64_tr_b16 v[20:21], v2 offset:56320
	ds_read_b64_tr_b16 v[22:23], v2 offset:56832
	v_mfma_f32_32x32x16_bf16 v[82:97], v[178:181], v[138:141], v[82:97]
	v_exp_f32_e32 v164, v164
	v_add_f32_e32 v27, v27, v162
	v_exp_f32_e32 v165, v165
	v_add_f32_e32 v27, v27, v163
	v_add_f32_e32 v27, v27, v164
	v_mfma_f32_32x32x16_bf16 v[98:113], v[174:177], v[138:141], v[98:113]
	v_add_f32_e32 v27, v27, v165
	v_cvt_pk_bf16_f32 v158, v158, v159
	v_cvt_pk_bf16_f32 v159, v160, v161
	v_cvt_pk_bf16_f32 v160, v162, v163
	v_cvt_pk_bf16_f32 v161, v164, v165
	s_waitcnt lgkmcnt(0)
	v_add_u32_e32 v2, 0x9000, v238
	v_mfma_f32_32x32x16_bf16 v[34:49], v[142:145], v[114:117], v[34:49]
	v_exp_f32_e32 v166, v166
	v_exp_f32_e32 v167, v167
	v_exp_f32_e32 v168, v168
	v_add_f32_e32 v27, v27, v166
	v_exp_f32_e32 v169, v169
	ds_read_b128 v[218:221], v2
	ds_read_b128 v[214:217], v2 offset:512
	ds_read_b128 v[210:213], v2 offset:2048
	v_mfma_f32_32x32x16_bf16 v[50:65], v[142:145], v[240:243], v[50:65]
	v_add_f32_e32 v27, v27, v167
	v_exp_f32_e32 v170, v170
	v_add_f32_e32 v27, v27, v168
	v_exp_f32_e32 v171, v171
	v_add_f32_e32 v27, v27, v169
	ds_read_b128 v[206:209], v2 offset:2560
	ds_read_b128 v[202:205], v2 offset:4096
	ds_read_b128 v[198:201], v2 offset:4608
	v_mfma_f32_32x32x16_bf16 v[34:49], v[150:153], v[118:121], v[34:49]
	v_exp_f32_e32 v172, v172
	v_add_f32_e32 v27, v27, v170
	v_exp_f32_e32 v173, v173
	v_add_f32_e32 v27, v27, v171
	v_add_f32_e32 v27, v27, v172
	ds_read_b128 v[194:197], v2 offset:6144
	ds_read_b128 v[190:193], v2 offset:6656
	ds_read_b128 v[186:189], v2 offset:8192
	v_mfma_f32_32x32x16_bf16 v[50:65], v[150:153], v[244:247], v[50:65]
	v_add_f32_e32 v27, v27, v173
	v_cvt_pk_bf16_f32 v166, v166, v167
	v_cvt_pk_bf16_f32 v167, v168, v169
	v_cvt_pk_bf16_f32 v168, v170, v171
	v_cvt_pk_bf16_f32 v169, v172, v173
	v_add_f32_e32 v236, v236, v27
	ds_read_b128 v[182:185], v2 offset:8704
	ds_read_b128 v[178:181], v2 offset:10240
	ds_read_b128 v[174:177], v2 offset:10752
	v_mfma_f32_32x32x16_bf16 v[34:49], v[158:161], v[122:125], v[34:49]
	v_max3_f32 v19, v82, v83, v84
	v_max3_f32 v26, v85, v86, v87
	v_max3_f32 v19, v19, v88, v89
	v_max3_f32 v26, v26, v90, v91
	v_mfma_f32_32x32x16_bf16 v[50:65], v[158:161], v[248:251], v[50:65]
	v_max3_f32 v19, v19, v92, v93
	v_max3_f32 v26, v26, v94, v95
	v_max3_f32 v19, v19, v96, v97
	v_max3_f32 v26, v26, v98, v99
	v_mfma_f32_32x32x16_bf16 v[34:49], v[166:169], v[126:129], v[34:49]
	v_max3_f32 v19, v19, v100, v101
	v_max3_f32 v26, v26, v102, v103
	v_max3_f32 v19, v19, v104, v105
	v_max3_f32 v26, v26, v106, v107
	v_mfma_f32_32x32x16_bf16 v[50:65], v[166:169], v[20:23], v[50:65]
	v_max3_f32 v19, v19, v108, v109
	v_max3_f32 v26, v26, v110, v111
	v_max3_f32 v19, v19, v112, v113
	v_max_f32_e32 v19, v19, v26
	v_cmp_lt_f32_e32 vcc, s41, v19
	s_cbranch_vccz .Lmy_nors_2
	s_nop 15
	s_nop 15
	v_mov_b32_e32 v26, v19
	s_nop 1
	v_permlane32_swap_b32_e32 v19, v26
	v_max_f32_e32 v19, v19, v26
	v_max_f32_e32 v19, v19, v19
	v_max_f32_e32 v150, 0, v19
	v_exp_f32_e64 v151, -v150
	v_add_f32_e32 v239, v239, v150
	v_xor_b32_e32 v66, 0x80000000, v239
	v_mov_b32_e32 v67, v66
	v_mov_b32_e32 v68, v66
	v_mov_b32_e32 v69, v66
	v_mov_b32_e32 v70, v66
	v_mov_b32_e32 v71, v66
	v_mov_b32_e32 v72, v66
	v_mov_b32_e32 v73, v66
	v_mov_b32_e32 v74, v66
	v_mov_b32_e32 v75, v66
	v_mov_b32_e32 v76, v66
	v_mov_b32_e32 v77, v66
	v_mov_b32_e32 v78, v66
	v_mov_b32_e32 v79, v66
	v_mov_b32_e32 v80, v66
	v_mov_b32_e32 v81, v66
	v_sub_f32_e32 v82, v82, v150
	v_sub_f32_e32 v83, v83, v150
	v_sub_f32_e32 v84, v84, v150
	v_sub_f32_e32 v85, v85, v150
	v_sub_f32_e32 v86, v86, v150
	v_sub_f32_e32 v87, v87, v150
	v_sub_f32_e32 v88, v88, v150
	v_sub_f32_e32 v89, v89, v150
	v_sub_f32_e32 v90, v90, v150
	v_sub_f32_e32 v91, v91, v150
	v_sub_f32_e32 v92, v92, v150
	v_sub_f32_e32 v93, v93, v150
	v_sub_f32_e32 v94, v94, v150
	v_sub_f32_e32 v95, v95, v150
	v_sub_f32_e32 v96, v96, v150
	v_sub_f32_e32 v97, v97, v150
	v_sub_f32_e32 v98, v98, v150
	v_sub_f32_e32 v99, v99, v150
	v_sub_f32_e32 v100, v100, v150
	v_sub_f32_e32 v101, v101, v150
	v_sub_f32_e32 v102, v102, v150
	v_sub_f32_e32 v103, v103, v150
	v_sub_f32_e32 v104, v104, v150
	v_sub_f32_e32 v105, v105, v150
	v_sub_f32_e32 v106, v106, v150
	v_sub_f32_e32 v107, v107, v150
	v_sub_f32_e32 v108, v108, v150
	v_sub_f32_e32 v109, v109, v150
	v_sub_f32_e32 v110, v110, v150
	v_sub_f32_e32 v111, v111, v150
	v_sub_f32_e32 v112, v112, v150
	v_sub_f32_e32 v113, v113, v150
	v_mul_f32_e32 v236, v236, v151
	s_mov_b64 s[96:97], exec
	s_and_b64 exec, exec, s[8:9]
	ds_write_b32 v235, v151
	s_mov_b64 exec, s[96:97]
	v_lshl_add_u32 v2, v228, 4, s47
	ds_read_b128 v[154:157], v2 offset:0
	s_waitcnt lgkmcnt(0)
	v_mul_f32_e32 v34, v34, v154
	v_mul_f32_e32 v50, v50, v154
	v_mul_f32_e32 v35, v35, v155
	v_mul_f32_e32 v51, v51, v155
	v_mul_f32_e32 v36, v36, v156
	v_mul_f32_e32 v52, v52, v156
	v_mul_f32_e32 v37, v37, v157
	v_mul_f32_e32 v53, v53, v157
	ds_read_b128 v[154:157], v2 offset:32
	s_waitcnt lgkmcnt(0)
	v_mul_f32_e32 v38, v38, v154
	v_mul_f32_e32 v54, v54, v154
	v_mul_f32_e32 v39, v39, v155
	v_mul_f32_e32 v55, v55, v155
	v_mul_f32_e32 v40, v40, v156
	v_mul_f32_e32 v56, v56, v156
	v_mul_f32_e32 v41, v41, v157
	v_mul_f32_e32 v57, v57, v157
	ds_read_b128 v[154:157], v2 offset:64
	s_waitcnt lgkmcnt(0)
	v_mul_f32_e32 v42, v42, v154
	v_mul_f32_e32 v58, v58, v154
	v_mul_f32_e32 v43, v43, v155
	v_mul_f32_e32 v59, v59, v155
	v_mul_f32_e32 v44, v44, v156
	v_mul_f32_e32 v60, v60, v156
	v_mul_f32_e32 v45, v45, v157
	v_mul_f32_e32 v61, v61, v157
	ds_read_b128 v[154:157], v2 offset:96
	s_waitcnt lgkmcnt(0)
	v_mul_f32_e32 v46, v46, v154
	v_mul_f32_e32 v62, v62, v154
	v_mul_f32_e32 v47, v47, v155
	v_mul_f32_e32 v63, v63, v155
	v_mul_f32_e32 v48, v48, v156
	v_mul_f32_e32 v64, v64, v156
	v_mul_f32_e32 v49, v49, v157
	v_mul_f32_e32 v65, v65, v157
.Lmy_nors_2:
	s_waitcnt lgkmcnt(6)
	v_add_u32_e32 v2, 0x4000, v237
	v_mfma_f32_32x32x16_bf16 v[142:157], v[218:221], v[4:7], v[66:81]
	v_exp_f32_e32 v82, v82
	v_exp_f32_e32 v83, v83
	v_exp_f32_e32 v84, v84
	v_add_f32_e32 v27, v82, v83
	v_exp_f32_e32 v85, v85
	v_mfma_f32_32x32x16_bf16 v[158:173], v[214:217], v[4:7], v[66:81]
	v_exp_f32_e32 v86, v86
	v_add_f32_e32 v27, v27, v84
	v_exp_f32_e32 v87, v87
	v_add_f32_e32 v27, v27, v85
	v_exp_f32_e32 v88, v88
	v_mfma_f32_32x32x16_bf16 v[142:157], v[210:213], v[8:11], v[142:157]
	v_add_f32_e32 v27, v27, v86
	v_exp_f32_e32 v89, v89
	v_add_f32_e32 v27, v27, v87
	v_add_f32_e32 v27, v27, v88
	v_add_f32_e32 v27, v27, v89
	v_mfma_f32_32x32x16_bf16 v[158:173], v[206:209], v[8:11], v[158:173]
	v_cvt_pk_bf16_f32 v82, v82, v83
	v_cvt_pk_bf16_f32 v83, v84, v85
	v_cvt_pk_bf16_f32 v84, v86, v87
	v_cvt_pk_bf16_f32 v85, v88, v89
	v_mfma_f32_32x32x16_bf16 v[142:157], v[202:205], v[12:15], v[142:157]
	v_exp_f32_e32 v90, v90
	v_exp_f32_e32 v91, v91
	v_exp_f32_e32 v92, v92
	v_add_f32_e32 v27, v27, v90
	v_exp_f32_e32 v93, v93
	v_mfma_f32_32x32x16_bf16 v[158:173], v[198:201], v[12:15], v[158:173]
	v_add_f32_e32 v27, v27, v91
	v_exp_f32_e32 v94, v94
	v_add_f32_e32 v27, v27, v92
	v_exp_f32_e32 v95, v95
	v_add_f32_e32 v27, v27, v93
	s_waitcnt lgkmcnt(0)
	s_waitcnt vmcnt(5)
	s_barrier
	v_mfma_f32_32x32x16_bf16 v[142:157], v[194:197], v[130:133], v[142:157]
	s_add_u32 m0, s57, 0x2000
	v_exp_f32_e32 v96, v96
	v_add_f32_e32 v27, v27, v94
	global_load_lds_dwordx4 v[28:29], off
	v_lshl_add_u64 v[28:29], v[28:29], 0, s[30:31]
	v_exp_f32_e32 v97, v97
	v_add_f32_e32 v27, v27, v95
	v_add_f32_e32 v27, v27, v96
	ds_read_b64_tr_b16 v[114:115], v2 offset:49152
	ds_read_b64_tr_b16 v[116:117], v2 offset:49664
	ds_read_b64_tr_b16 v[118:119], v2 offset:50176
	ds_read_b64_tr_b16 v[120:121], v2 offset:50688
	v_mfma_f32_32x32x16_bf16 v[158:173], v[190:193], v[130:133], v[158:173]
	s_add_u32 m0, s40, 0x9000
	v_add_f32_e32 v27, v27, v97
	v_cvt_pk_bf16_f32 v90, v90, v91
	global_load_lds_dwordx4 v[24:25], off
	v_lshl_add_u64 v[24:25], v[24:25], 0, s[30:31]
	v_cvt_pk_bf16_f32 v91, v92, v93
	v_cvt_pk_bf16_f32 v92, v94, v95
	v_cvt_pk_bf16_f32 v93, v96, v97
	ds_read_b64_tr_b16 v[122:123], v2 offset:51200
	ds_read_b64_tr_b16 v[124:125], v2 offset:51712
	ds_read_b64_tr_b16 v[126:127], v2 offset:52224
	ds_read_b64_tr_b16 v[128:129], v2 offset:52736
	v_mfma_f32_32x32x16_bf16 v[142:157], v[186:189], v[134:137], v[142:157]
	s_add_u32 m0, s43, 0x9000
	v_exp_f32_e32 v98, v98
	v_exp_f32_e32 v99, v99
	global_load_lds_dwordx4 v[30:31], off
	v_lshl_add_u64 v[30:31], v[30:31], 0, s[12:13]
	v_exp_f32_e32 v100, v100
	v_add_f32_e32 v27, v27, v98
	v_exp_f32_e32 v101, v101
	ds_read_b64_tr_b16 v[240:241], v2 offset:53248
	ds_read_b64_tr_b16 v[242:243], v2 offset:53760
	ds_read_b64_tr_b16 v[244:245], v2 offset:54272
	ds_read_b64_tr_b16 v[246:247], v2 offset:54784
	v_mfma_f32_32x32x16_bf16 v[158:173], v[182:185], v[134:137], v[158:173]
	v_add_f32_e32 v27, v27, v99
	v_exp_f32_e32 v102, v102
	v_add_f32_e32 v27, v27, v100
	v_exp_f32_e32 v103, v103
	v_add_f32_e32 v27, v27, v101
	ds_read_b64_tr_b16 v[248:249], v2 offset:55296
	ds_read_b64_tr_b16 v[250:251], v2 offset:55808
	ds_read_b64_tr_b16 v[20:21], v2 offset:56320
	ds_read_b64_tr_b16 v[22:23], v2 offset:56832
	v_mfma_f32_32x32x16_bf16 v[142:157], v[178:181], v[138:141], v[142:157]
	v_exp_f32_e32 v104, v104
	v_add_f32_e32 v27, v27, v102
	v_exp_f32_e32 v105, v105
	v_add_f32_e32 v27, v27, v103
	v_add_f32_e32 v27, v27, v104
	v_mfma_f32_32x32x16_bf16 v[158:173], v[174:177], v[138:141], v[158:173]
	v_add_f32_e32 v27, v27, v105
	v_cvt_pk_bf16_f32 v98, v98, v99
	v_cvt_pk_bf16_f32 v99, v100, v101
	v_cvt_pk_bf16_f32 v100, v102, v103
	v_cvt_pk_bf16_f32 v101, v104, v105
	s_waitcnt lgkmcnt(0)
	v_mov_b32_e32 v2, v238
	v_mfma_f32_32x32x16_bf16 v[34:49], v[82:85], v[114:117], v[34:49]
	v_exp_f32_e32 v106, v106
	v_exp_f32_e32 v107, v107
	v_exp_f32_e32 v108, v108
	v_add_f32_e32 v27, v27, v106
	v_exp_f32_e32 v109, v109
	ds_read_b128 v[218:221], v2
	ds_read_b128 v[214:217], v2 offset:512
	ds_read_b128 v[210:213], v2 offset:2048
	v_mfma_f32_32x32x16_bf16 v[50:65], v[82:85], v[240:243], v[50:65]
	v_add_f32_e32 v27, v27, v107
	v_exp_f32_e32 v110, v110
	v_add_f32_e32 v27, v27, v108
	v_exp_f32_e32 v111, v111
	v_add_f32_e32 v27, v27, v109
	ds_read_b128 v[206:209], v2 offset:2560
	ds_read_b128 v[202:205], v2 offset:4096
	ds_read_b128 v[198:201], v2 offset:4608
	v_mfma_f32_32x32x16_bf16 v[34:49], v[90:93], v[118:121], v[34:49]
	v_exp_f32_e32 v112, v112
	v_add_f32_e32 v27, v27, v110
	v_exp_f32_e32 v113, v113
	v_add_f32_e32 v27, v27, v111
	v_add_f32_e32 v27, v27, v112
	ds_read_b128 v[194:197], v2 offset:6144
	ds_read_b128 v[190:193], v2 offset:6656
	ds_read_b128 v[186:189], v2 offset:8192
	v_mfma_f32_32x32x16_bf16 v[50:65], v[90:93], v[244:247], v[50:65]
	v_add_f32_e32 v27, v27, v113
	v_cvt_pk_bf16_f32 v106, v106, v107
	v_cvt_pk_bf16_f32 v107, v108, v109
	v_cvt_pk_bf16_f32 v108, v110, v111
	v_cvt_pk_bf16_f32 v109, v112, v113
	v_add_f32_e32 v236, v236, v27
	ds_read_b128 v[182:185], v2 offset:8704
	ds_read_b128 v[178:181], v2 offset:10240
	ds_read_b128 v[174:177], v2 offset:10752
	v_mfma_f32_32x32x16_bf16 v[34:49], v[98:101], v[122:125], v[34:49]
	v_max3_f32 v19, v142, v143, v144
	v_max3_f32 v26, v145, v146, v147
	v_max3_f32 v19, v19, v148, v149
	v_max3_f32 v26, v26, v150, v151
	v_mfma_f32_32x32x16_bf16 v[50:65], v[98:101], v[248:251], v[50:65]
	v_max3_f32 v19, v19, v152, v153
	v_max3_f32 v26, v26, v154, v155
	v_max3_f32 v19, v19, v156, v157
	v_max3_f32 v26, v26, v158, v159
	v_mfma_f32_32x32x16_bf16 v[34:49], v[106:109], v[126:129], v[34:49]
	v_max3_f32 v19, v19, v160, v161
	v_max3_f32 v26, v26, v162, v163
	v_max3_f32 v19, v19, v164, v165
	v_max3_f32 v26, v26, v166, v167
	v_mfma_f32_32x32x16_bf16 v[50:65], v[106:109], v[20:23], v[50:65]
	v_max3_f32 v19, v19, v168, v169
	v_max3_f32 v26, v26, v170, v171
	v_max3_f32 v19, v19, v172, v173
	v_max_f32_e32 v19, v19, v26
	v_cmp_lt_f32_e32 vcc, s41, v19
	s_cbranch_vccz .Lmy_nors_3
	s_nop 15
	s_nop 15
	v_mov_b32_e32 v26, v19
	s_nop 1
	v_permlane32_swap_b32_e32 v19, v26
	v_max_f32_e32 v19, v19, v26
	v_max_f32_e32 v19, v19, v19
	v_max_f32_e32 v90, 0, v19
	v_exp_f32_e64 v91, -v90
	v_add_f32_e32 v239, v239, v90
	v_xor_b32_e32 v66, 0x80000000, v239
	v_mov_b32_e32 v67, v66
	v_mov_b32_e32 v68, v66
	v_mov_b32_e32 v69, v66
	v_mov_b32_e32 v70, v66
	v_mov_b32_e32 v71, v66
	v_mov_b32_e32 v72, v66
	v_mov_b32_e32 v73, v66
	v_mov_b32_e32 v74, v66
	v_mov_b32_e32 v75, v66
	v_mov_b32_e32 v76, v66
	v_mov_b32_e32 v77, v66
	v_mov_b32_e32 v78, v66
	v_mov_b32_e32 v79, v66
	v_mov_b32_e32 v80, v66
	v_mov_b32_e32 v81, v66
	v_sub_f32_e32 v142, v142, v90
	v_sub_f32_e32 v143, v143, v90
	v_sub_f32_e32 v144, v144, v90
	v_sub_f32_e32 v145, v145, v90
	v_sub_f32_e32 v146, v146, v90
	v_sub_f32_e32 v147, v147, v90
	v_sub_f32_e32 v148, v148, v90
	v_sub_f32_e32 v149, v149, v90
	v_sub_f32_e32 v150, v150, v90
	v_sub_f32_e32 v151, v151, v90
	v_sub_f32_e32 v152, v152, v90
	v_sub_f32_e32 v153, v153, v90
	v_sub_f32_e32 v154, v154, v90
	v_sub_f32_e32 v155, v155, v90
	v_sub_f32_e32 v156, v156, v90
	v_sub_f32_e32 v157, v157, v90
	v_sub_f32_e32 v158, v158, v90
	v_sub_f32_e32 v159, v159, v90
	v_sub_f32_e32 v160, v160, v90
	v_sub_f32_e32 v161, v161, v90
	v_sub_f32_e32 v162, v162, v90
	v_sub_f32_e32 v163, v163, v90
	v_sub_f32_e32 v164, v164, v90
	v_sub_f32_e32 v165, v165, v90
	v_sub_f32_e32 v166, v166, v90
	v_sub_f32_e32 v167, v167, v90
	v_sub_f32_e32 v168, v168, v90
	v_sub_f32_e32 v169, v169, v90
	v_sub_f32_e32 v170, v170, v90
	v_sub_f32_e32 v171, v171, v90
	v_sub_f32_e32 v172, v172, v90
	v_sub_f32_e32 v173, v173, v90
	v_mul_f32_e32 v236, v236, v91
	s_mov_b64 s[96:97], exec
	s_and_b64 exec, exec, s[8:9]
	ds_write_b32 v235, v91
	s_mov_b64 exec, s[96:97]
	v_lshl_add_u32 v2, v228, 4, s47
	ds_read_b128 v[94:97], v2 offset:0
	s_waitcnt lgkmcnt(0)
	v_mul_f32_e32 v34, v34, v94
	v_mul_f32_e32 v50, v50, v94
	v_mul_f32_e32 v35, v35, v95
	v_mul_f32_e32 v51, v51, v95
	v_mul_f32_e32 v36, v36, v96
	v_mul_f32_e32 v52, v52, v96
	v_mul_f32_e32 v37, v37, v97
	v_mul_f32_e32 v53, v53, v97
	ds_read_b128 v[94:97], v2 offset:32
	s_waitcnt lgkmcnt(0)
	v_mul_f32_e32 v38, v38, v94
	v_mul_f32_e32 v54, v54, v94
	v_mul_f32_e32 v39, v39, v95
	v_mul_f32_e32 v55, v55, v95
	v_mul_f32_e32 v40, v40, v96
	v_mul_f32_e32 v56, v56, v96
	v_mul_f32_e32 v41, v41, v97
	v_mul_f32_e32 v57, v57, v97
	ds_read_b128 v[94:97], v2 offset:64
	s_waitcnt lgkmcnt(0)
	v_mul_f32_e32 v42, v42, v94
	v_mul_f32_e32 v58, v58, v94
	v_mul_f32_e32 v43, v43, v95
	v_mul_f32_e32 v59, v59, v95
	v_mul_f32_e32 v44, v44, v96
	v_mul_f32_e32 v60, v60, v96
	v_mul_f32_e32 v45, v45, v97
	v_mul_f32_e32 v61, v61, v97
	ds_read_b128 v[94:97], v2 offset:96
	s_waitcnt lgkmcnt(0)
	v_mul_f32_e32 v46, v46, v94
	v_mul_f32_e32 v62, v62, v94
	v_mul_f32_e32 v47, v47, v95
	v_mul_f32_e32 v63, v63, v95
	v_mul_f32_e32 v48, v48, v96
	v_mul_f32_e32 v64, v64, v96
	v_mul_f32_e32 v49, v49, v97
	v_mul_f32_e32 v65, v65, v97
.Lmy_nors_3:
	s_waitcnt lgkmcnt(6)
	v_add_u32_e32 v2, 0x6000, v237
	v_mfma_f32_32x32x16_bf16 v[82:97], v[218:221], v[4:7], v[66:81]
	v_exp_f32_e32 v142, v142
	v_exp_f32_e32 v143, v143
	v_exp_f32_e32 v144, v144
	v_add_f32_e32 v27, v142, v143
	v_exp_f32_e32 v145, v145
	v_mfma_f32_32x32x16_bf16 v[98:113], v[214:217], v[4:7], v[66:81]
	v_exp_f32_e32 v146, v146
	v_add_f32_e32 v27, v27, v144
	v_exp_f32_e32 v147, v147
	v_add_f32_e32 v27, v27, v145
	v_exp_f32_e32 v148, v148
	v_mfma_f32_32x32x16_bf16 v[82:97], v[210:213], v[8:11], v[82:97]
	v_add_f32_e32 v27, v27, v146
	v_exp_f32_e32 v149, v149
	v_add_f32_e32 v27, v27, v147
	v_add_f32_e32 v27, v27, v148
	v_add_f32_e32 v27, v27, v149
	v_mfma_f32_32x32x16_bf16 v[98:113], v[206:209], v[8:11], v[98:113]
	v_cvt_pk_bf16_f32 v142, v142, v143
	v_cvt_pk_bf16_f32 v143, v144, v145
	v_cvt_pk_bf16_f32 v144, v146, v147
	v_cvt_pk_bf16_f32 v145, v148, v149
	v_mfma_f32_32x32x16_bf16 v[82:97], v[202:205], v[12:15], v[82:97]
	v_exp_f32_e32 v150, v150
	v_exp_f32_e32 v151, v151
	v_exp_f32_e32 v152, v152
	v_add_f32_e32 v27, v27, v150
	v_exp_f32_e32 v153, v153
	v_mfma_f32_32x32x16_bf16 v[98:113], v[198:201], v[12:15], v[98:113]
	v_add_f32_e32 v27, v27, v151
	v_exp_f32_e32 v154, v154
	v_add_f32_e32 v27, v27, v152
	v_exp_f32_e32 v155, v155
	v_add_f32_e32 v27, v27, v153
	s_waitcnt lgkmcnt(0)
	s_waitcnt vmcnt(6)
	s_barrier
	v_mfma_f32_32x32x16_bf16 v[82:97], v[194:197], v[130:133], v[82:97]
	s_add_u32 m0, s57, 0x4000
	v_exp_f32_e32 v156, v156
	v_add_f32_e32 v27, v27, v154
	global_load_lds_dwordx4 v[28:29], off
	v_lshl_add_u64 v[28:29], v[28:29], 0, s[30:31]
	v_exp_f32_e32 v157, v157
	v_add_f32_e32 v27, v27, v155
	v_add_f32_e32 v27, v27, v156
	ds_read_b64_tr_b16 v[114:115], v2 offset:49152
	ds_read_b64_tr_b16 v[116:117], v2 offset:49664
	ds_read_b64_tr_b16 v[118:119], v2 offset:50176
	ds_read_b64_tr_b16 v[120:121], v2 offset:50688
	v_mfma_f32_32x32x16_bf16 v[98:113], v[190:193], v[130:133], v[98:113]
	s_cmp_eq_u32 s79, 1
	s_cbranch_scc1 .Lmy_gl_4
	s_add_u32 m0, s40, 0x0
	s_nop 0
	global_load_lds_dwordx4 v[24:25], off
	v_lshl_add_u64 v[24:25], v[24:25], 0, s[30:31]

.Lmy_A_loop:
	s_waitcnt lgkmcnt(6)
	v_mov_b32_e32 v2, v237
	v_mfma_f32_32x32x16_bf16 v[142:157], v[218:221], v[4:7], v[66:81]
	v_exp_f32_e32 v82, v82
	v_exp_f32_e32 v83, v83
	v_exp_f32_e32 v84, v84
	v_add_f32_e32 v27, v82, v83
	v_exp_f32_e32 v85, v85
	v_mfma_f32_32x32x16_bf16 v[158:173], v[214:217], v[4:7], v[66:81]
	v_exp_f32_e32 v86, v86
	v_add_f32_e32 v27, v27, v84
	v_exp_f32_e32 v87, v87
	v_add_f32_e32 v27, v27, v85
	v_exp_f32_e32 v88, v88
	v_mfma_f32_32x32x16_bf16 v[142:157], v[210:213], v[8:11], v[142:157]
	v_add_f32_e32 v27, v27, v86
	v_exp_f32_e32 v89, v89
	v_add_f32_e32 v27, v27, v87
	v_add_f32_e32 v27, v27, v88
	v_add_f32_e32 v27, v27, v89
	v_mfma_f32_32x32x16_bf16 v[158:173], v[206:209], v[8:11], v[158:173]
	v_cvt_pk_bf16_f32 v82, v82, v83
	v_cvt_pk_bf16_f32 v83, v84, v85
	v_cvt_pk_bf16_f32 v84, v86, v87
	v_cvt_pk_bf16_f32 v85, v88, v89
	v_mfma_f32_32x32x16_bf16 v[142:157], v[202:205], v[12:15], v[142:157]
	v_exp_f32_e32 v90, v90
	v_exp_f32_e32 v91, v91
	v_exp_f32_e32 v92, v92
	v_add_f32_e32 v27, v27, v90
	v_exp_f32_e32 v93, v93
	v_mfma_f32_32x32x16_bf16 v[158:173], v[198:201], v[12:15], v[158:173]
	v_add_f32_e32 v27, v27, v91
	v_exp_f32_e32 v94, v94
	v_add_f32_e32 v27, v27, v92
	v_exp_f32_e32 v95, v95
	v_add_f32_e32 v27, v27, v93
	s_waitcnt lgkmcnt(0)
	s_waitcnt vmcnt(6)
	s_barrier
	v_mfma_f32_32x32x16_bf16 v[142:157], v[194:197], v[130:133], v[142:157]
	s_add_u32 m0, s57, 0x6000
	v_exp_f32_e32 v96, v96
	v_add_f32_e32 v27, v27, v94
	global_load_lds_dwordx4 v[28:29], off
	v_lshl_add_u64 v[28:29], v[28:29], 0, s[30:31]
	v_exp_f32_e32 v97, v97
	v_add_f32_e32 v27, v27, v95
	v_add_f32_e32 v27, v27, v96
	ds_read_b64_tr_b16 v[114:115], v2 offset:49152
	ds_read_b64_tr_b16 v[116:117], v2 offset:49664
	ds_read_b64_tr_b16 v[118:119], v2 offset:50176
	ds_read_b64_tr_b16 v[120:121], v2 offset:50688
	v_mfma_f32_32x32x16_bf16 v[158:173], v[190:193], v[130:133], v[158:173]
	s_add_u32 m0, s40, 0x3000
	v_add_f32_e32 v27, v27, v97
	v_cvt_pk_bf16_f32 v90, v90, v91
	global_load_lds_dwordx4 v[24:25], off
	v_lshl_add_u64 v[24:25], v[24:25], 0, s[30:31]
	v_cvt_pk_bf16_f32 v91, v92, v93
	v_cvt_pk_bf16_f32 v92, v94, v95
	v_cvt_pk_bf16_f32 v93, v96, v97
	ds_read_b64_tr_b16 v[122:123], v2 offset:51200
	ds_read_b64_tr_b16 v[124:125], v2 offset:51712
	ds_read_b64_tr_b16 v[126:127], v2 offset:52224
	ds_read_b64_tr_b16 v[128:129], v2 offset:52736
	v_mfma_f32_32x32x16_bf16 v[142:157], v[186:189], v[134:137], v[142:157]
	s_add_u32 m0, s43, 0x3000
	v_exp_f32_e32 v98, v98
	v_exp_f32_e32 v99, v99
	global_load_lds_dwordx4 v[30:31], off
	v_lshl_add_u64 v[30:31], v[30:31], 0, s[12:13]
	v_exp_f32_e32 v100, v100
	v_add_f32_e32 v27, v27, v98
	v_exp_f32_e32 v101, v101
	ds_read_b64_tr_b16 v[240:241], v2 offset:53248
	ds_read_b64_tr_b16 v[242:243], v2 offset:53760
	ds_read_b64_tr_b16 v[244:245], v2 offset:54272
	ds_read_b64_tr_b16 v[246:247], v2 offset:54784
	v_mfma_f32_32x32x16_bf16 v[158:173], v[182:185], v[134:137], v[158:173]
	v_add_f32_e32 v27, v27, v99
	v_exp_f32_e32 v102, v102
	v_add_f32_e32 v27, v27, v100
	v_exp_f32_e32 v103, v103
	v_add_f32_e32 v27, v27, v101
	ds_read_b64_tr_b16 v[248:249], v2 offset:55296
	ds_read_b64_tr_b16 v[250:251], v2 offset:55808
	ds_read_b64_tr_b16 v[20:21], v2 offset:56320
	ds_read_b64_tr_b16 v[22:23], v2 offset:56832
	v_mfma_f32_32x32x16_bf16 v[142:157], v[178:181], v[138:141], v[142:157]
	v_exp_f32_e32 v104, v104
	v_add_f32_e32 v27, v27, v102
	v_exp_f32_e32 v105, v105
	v_add_f32_e32 v27, v27, v103
	v_add_f32_e32 v27, v27, v104
	v_mfma_f32_32x32x16_bf16 v[158:173], v[174:177], v[138:141], v[158:173]
	v_add_f32_e32 v27, v27, v105
	v_cvt_pk_bf16_f32 v98, v98, v99
	v_cvt_pk_bf16_f32 v99, v100, v101
	v_cvt_pk_bf16_f32 v100, v102, v103
	v_cvt_pk_bf16_f32 v101, v104, v105
	s_waitcnt lgkmcnt(0)
	v_add_u32_e32 v2, 0x6000, v238
	v_mfma_f32_32x32x16_bf16 v[34:49], v[82:85], v[114:117], v[34:49]
	v_exp_f32_e32 v106, v106
	v_exp_f32_e32 v107, v107
	v_exp_f32_e32 v108, v108
	v_add_f32_e32 v27, v27, v106
	v_exp_f32_e32 v109, v109
	ds_read_b128 v[218:221], v2
	ds_read_b128 v[214:217], v2 offset:512
	ds_read_b128 v[210:213], v2 offset:2048
	v_mfma_f32_32x32x16_bf16 v[50:65], v[82:85], v[240:243], v[50:65]
	v_add_f32_e32 v27, v27, v107
	v_exp_f32_e32 v110, v110
	v_add_f32_e32 v27, v27, v108
	v_exp_f32_e32 v111, v111
	v_add_f32_e32 v27, v27, v109
	ds_read_b128 v[206:209], v2 offset:2560
	ds_read_b128 v[202:205], v2 offset:4096
	ds_read_b128 v[198:201], v2 offset:4608
	v_mfma_f32_32x32x16_bf16 v[34:49], v[90:93], v[118:121], v[34:49]
	v_exp_f32_e32 v112, v112
	v_add_f32_e32 v27, v27, v110
	v_exp_f32_e32 v113, v113
	v_add_f32_e32 v27, v27, v111
	v_add_f32_e32 v27, v27, v112
	ds_read_b128 v[194:197], v2 offset:6144
	ds_read_b128 v[190:193], v2 offset:6656
	ds_read_b128 v[186:189], v2 offset:8192
	v_mfma_f32_32x32x16_bf16 v[50:65], v[90:93], v[244:247], v[50:65]
	v_add_f32_e32 v27, v27, v113
	v_cvt_pk_bf16_f32 v106, v106, v107
	v_cvt_pk_bf16_f32 v107, v108, v109
	v_cvt_pk_bf16_f32 v108, v110, v111
	v_cvt_pk_bf16_f32 v109, v112, v113
	v_add_f32_e32 v236, v236, v27
	ds_read_b128 v[182:185], v2 offset:8704
	ds_read_b128 v[178:181], v2 offset:10240
	ds_read_b128 v[174:177], v2 offset:10752
	v_mfma_f32_32x32x16_bf16 v[34:49], v[98:101], v[122:125], v[34:49]
	v_max3_f32 v19, v142, v143, v144
	v_max3_f32 v26, v145, v146, v147
	v_max3_f32 v19, v19, v148, v149
	v_max3_f32 v26, v26, v150, v151
	v_mfma_f32_32x32x16_bf16 v[50:65], v[98:101], v[248:251], v[50:65]
	v_max3_f32 v19, v19, v152, v153
	v_max3_f32 v26, v26, v154, v155
	v_max3_f32 v19, v19, v156, v157
	v_max3_f32 v26, v26, v158, v159
	v_mfma_f32_32x32x16_bf16 v[34:49], v[106:109], v[126:129], v[34:49]
	v_max3_f32 v19, v19, v160, v161
	v_max3_f32 v26, v26, v162, v163
	v_max3_f32 v19, v19, v164, v165
	v_max3_f32 v26, v26, v166, v167
	v_mfma_f32_32x32x16_bf16 v[50:65], v[106:109], v[20:23], v[50:65]
	v_max3_f32 v19, v19, v168, v169
	v_max3_f32 v26, v26, v170, v171
	v_max3_f32 v19, v19, v172, v173
	v_max_f32_e32 v19, v19, v26
	v_cmp_lt_f32_e32 vcc, s41, v19
	s_cbranch_vccz .Lmy_nors_7
	s_nop 15
	s_nop 15
	v_mov_b32_e32 v26, v19
	s_nop 1
	v_permlane32_swap_b32_e32 v19, v26
	v_max_f32_e32 v19, v19, v26
	v_max_f32_e32 v19, v19, v19
	v_max_f32_e32 v90, 0, v19
	v_exp_f32_e64 v91, -v90
	v_add_f32_e32 v239, v239, v90
	v_xor_b32_e32 v66, 0x80000000, v239
	v_mov_b32_e32 v67, v66
	v_mov_b32_e32 v68, v66
	v_mov_b32_e32 v69, v66
	v_mov_b32_e32 v70, v66
	v_mov_b32_e32 v71, v66
	v_mov_b32_e32 v72, v66
	v_mov_b32_e32 v73, v66
	v_mov_b32_e32 v74, v66
	v_mov_b32_e32 v75, v66
	v_mov_b32_e32 v76, v66
	v_mov_b32_e32 v77, v66
	v_mov_b32_e32 v78, v66
	v_mov_b32_e32 v79, v66
	v_mov_b32_e32 v80, v66
	v_mov_b32_e32 v81, v66
	v_sub_f32_e32 v142, v142, v90
	v_sub_f32_e32 v143, v143, v90
	v_sub_f32_e32 v144, v144, v90
	v_sub_f32_e32 v145, v145, v90
	v_sub_f32_e32 v146, v146, v90
	v_sub_f32_e32 v147, v147, v90
	v_sub_f32_e32 v148, v148, v90
	v_sub_f32_e32 v149, v149, v90
	v_sub_f32_e32 v150, v150, v90
	v_sub_f32_e32 v151, v151, v90
	v_sub_f32_e32 v152, v152, v90
	v_sub_f32_e32 v153, v153, v90
	v_sub_f32_e32 v154, v154, v90
	v_sub_f32_e32 v155, v155, v90
	v_sub_f32_e32 v156, v156, v90
	v_sub_f32_e32 v157, v157, v90
	v_sub_f32_e32 v158, v158, v90
	v_sub_f32_e32 v159, v159, v90
	v_sub_f32_e32 v160, v160, v90
	v_sub_f32_e32 v161, v161, v90
	v_sub_f32_e32 v162, v162, v90
	v_sub_f32_e32 v163, v163, v90
	v_sub_f32_e32 v164, v164, v90
	v_sub_f32_e32 v165, v165, v90
	v_sub_f32_e32 v166, v166, v90
	v_sub_f32_e32 v167, v167, v90
	v_sub_f32_e32 v168, v168, v90
	v_sub_f32_e32 v169, v169, v90
	v_sub_f32_e32 v170, v170, v90
	v_sub_f32_e32 v171, v171, v90
	v_sub_f32_e32 v172, v172, v90
	v_sub_f32_e32 v173, v173, v90
	v_mul_f32_e32 v236, v236, v91
	s_mov_b64 s[96:97], exec
	s_and_b64 exec, exec, s[8:9]
	ds_write_b32 v235, v91
	s_mov_b64 exec, s[96:97]
	v_lshl_add_u32 v2, v228, 4, s47
	ds_read_b128 v[94:97], v2 offset:0
	s_waitcnt lgkmcnt(0)
	v_mul_f32_e32 v34, v34, v94
	v_mul_f32_e32 v50, v50, v94
	v_mul_f32_e32 v35, v35, v95
	v_mul_f32_e32 v51, v51, v95
	v_mul_f32_e32 v36, v36, v96
	v_mul_f32_e32 v52, v52, v96
	v_mul_f32_e32 v37, v37, v97
	v_mul_f32_e32 v53, v53, v97
	ds_read_b128 v[94:97], v2 offset:32
	s_waitcnt lgkmcnt(0)
	v_mul_f32_e32 v38, v38, v94
	v_mul_f32_e32 v54, v54, v94
	v_mul_f32_e32 v39, v39, v95
	v_mul_f32_e32 v55, v55, v95
	v_mul_f32_e32 v40, v40, v96
	v_mul_f32_e32 v56, v56, v96
	v_mul_f32_e32 v41, v41, v97
	v_mul_f32_e32 v57, v57, v97
	ds_read_b128 v[94:97], v2 offset:64
	s_waitcnt lgkmcnt(0)
	v_mul_f32_e32 v42, v42, v94
	v_mul_f32_e32 v58, v58, v94
	v_mul_f32_e32 v43, v43, v95
	v_mul_f32_e32 v59, v59, v95
	v_mul_f32_e32 v44, v44, v96
	v_mul_f32_e32 v60, v60, v96
	v_mul_f32_e32 v45, v45, v97
	v_mul_f32_e32 v61, v61, v97
	ds_read_b128 v[94:97], v2 offset:96
	s_waitcnt lgkmcnt(0)
	v_mul_f32_e32 v46, v46, v94
	v_mul_f32_e32 v62, v62, v94
	v_mul_f32_e32 v47, v47, v95
	v_mul_f32_e32 v63, v63, v95
	v_mul_f32_e32 v48, v48, v96
	v_mul_f32_e32 v64, v64, v96
	v_mul_f32_e32 v49, v49, v97
	v_mul_f32_e32 v65, v65, v97
.Lmy_nors_7:
	s_waitcnt lgkmcnt(6)
	v_add_u32_e32 v2, 0x2000, v237
	v_mfma_f32_32x32x16_bf16 v[82:97], v[218:221], v[4:7], v[66:81]
	v_exp_f32_e32 v142, v142
	v_exp_f32_e32 v143, v143
	v_exp_f32_e32 v144, v144
	v_add_f32_e32 v27, v142, v143
	v_exp_f32_e32 v145, v145
	v_mfma_f32_32x32x16_bf16 v[98:113], v[214:217], v[4:7], v[66:81]
	v_exp_f32_e32 v146, v146
	v_add_f32_e32 v27, v27, v144
	v_exp_f32_e32 v147, v147
	v_add_f32_e32 v27, v27, v145
	v_exp_f32_e32 v148, v148
	v_mfma_f32_32x32x16_bf16 v[82:97], v[210:213], v[8:11], v[82:97]
	v_add_f32_e32 v27, v27, v146
	v_exp_f32_e32 v149, v149
	v_add_f32_e32 v27, v27, v147
	v_add_f32_e32 v27, v27, v148
	v_add_f32_e32 v27, v27, v149
	v_mfma_f32_32x32x16_bf16 v[98:113], v[206:209], v[8:11], v[98:113]
	v_cvt_pk_bf16_f32 v142, v142, v143
	v_cvt_pk_bf16_f32 v143, v144, v145
	v_cvt_pk_bf16_f32 v144, v146, v147
	v_cvt_pk_bf16_f32 v145, v148, v149
	v_mfma_f32_32x32x16_bf16 v[82:97], v[202:205], v[12:15], v[82:97]
	v_exp_f32_e32 v150, v150
	v_exp_f32_e32 v151, v151
	v_exp_f32_e32 v152, v152
	v_add_f32_e32 v27, v27, v150
	v_exp_f32_e32 v153, v153
	v_mfma_f32_32x32x16_bf16 v[98:113], v[198:201], v[12:15], v[98:113]
	v_add_f32_e32 v27, v27, v151
	v_exp_f32_e32 v154, v154
	v_add_f32_e32 v27, v27, v152
	v_exp_f32_e32 v155, v155
	v_add_f32_e32 v27, v27, v153
	s_waitcnt lgkmcnt(0)
	s_waitcnt vmcnt(6)
	s_barrier
	v_mfma_f32_32x32x16_bf16 v[82:97], v[194:197], v[130:133], v[82:97]
	s_add_u32 m0, s57, 0x0
	v_exp_f32_e32 v156, v156
	v_add_f32_e32 v27, v27, v154
	global_load_lds_dwordx4 v[28:29], off
	v_lshl_add_u64 v[28:29], v[28:29], 0, s[30:31]
	v_exp_f32_e32 v157, v157
	v_add_f32_e32 v27, v27, v155
	v_add_f32_e32 v27, v27, v156
	ds_read_b64_tr_b16 v[114:115], v2 offset:49152
	ds_read_b64_tr_b16 v[116:117], v2 offset:49664
	ds_read_b64_tr_b16 v[118:119], v2 offset:50176
	ds_read_b64_tr_b16 v[120:121], v2 offset:50688
	v_mfma_f32_32x32x16_bf16 v[98:113], v[190:193], v[130:133], v[98:113]
	s_add_u32 m0, s40, 0x6000
	v_add_f32_e32 v27, v27, v157
	v_cvt_pk_bf16_f32 v150, v150, v151
	global_load_lds_dwordx4 v[24:25], off
	v_lshl_add_u64 v[24:25], v[24:25], 0, s[30:31]
	v_cvt_pk_bf16_f32 v151, v152, v153
	v_cvt_pk_bf16_f32 v152, v154, v155
	v_cvt_pk_bf16_f32 v153, v156, v157
	ds_read_b64_tr_b16 v[122:123], v2 offset:51200
	ds_read_b64_tr_b16 v[124:125], v2 offset:51712
	ds_read_b64_tr_b16 v[126:127], v2 offset:52224
	ds_read_b64_tr_b16 v[128:129], v2 offset:52736
	v_mfma_f32_32x32x16_bf16 v[82:97], v[186:189], v[134:137], v[82:97]
	s_add_u32 m0, s43, 0x6000
	v_exp_f32_e32 v158, v158
	v_exp_f32_e32 v159, v159
	global_load_lds_dwordx4 v[30:31], off
	v_lshl_add_u64 v[30:31], v[30:31], 0, s[12:13]
	v_exp_f32_e32 v160, v160
	v_add_f32_e32 v27, v27, v158
	v_exp_f32_e32 v161, v161
	ds_read_b64_tr_b16 v[240:241], v2 offset:53248
	ds_read_b64_tr_b16 v[242:243], v2 offset:53760
	ds_read_b64_tr_b16 v[244:245], v2 offset:54272
	ds_read_b64_tr_b16 v[246:247], v2 offset:54784
	v_mfma_f32_32x32x16_bf16 v[98:113], v[182:185], v[134:137], v[98:113]
	v_add_f32_e32 v27, v27, v159
	v_exp_f32_e32 v162, v162
	v_add_f32_e32 v27, v27, v160
	v_exp_f32_e32 v163, v163
	v_add_f32_e32 v27, v27, v161
	ds_read_b64_tr_b16 v[248:249], v2 offset:55296
	ds_read_b64_tr_b16 v[250:251], v2 offset:55808
	ds_read_b64_tr_b16 v[20:21], v2 offset:56320
	ds_read_b64_tr_b16 v[22:23], v2 offset:56832
	v_mfma_f32_32x32x16_bf16 v[82:97], v[178:181], v[138:141], v[82:97]
	v_exp_f32_e32 v164, v164
	v_add_f32_e32 v27, v27, v162
	v_exp_f32_e32 v165, v165
	v_add_f32_e32 v27, v27, v163
	v_add_f32_e32 v27, v27, v164
	v_mfma_f32_32x32x16_bf16 v[98:113], v[174:177], v[138:141], v[98:113]
	v_add_f32_e32 v27, v27, v165
	v_cvt_pk_bf16_f32 v158, v158, v159
	v_cvt_pk_bf16_f32 v159, v160, v161
	v_cvt_pk_bf16_f32 v160, v162, v163
	v_cvt_pk_bf16_f32 v161, v164, v165
	s_waitcnt lgkmcnt(0)
	v_add_u32_e32 v2, 0x9000, v238
	v_mfma_f32_32x32x16_bf16 v[34:49], v[142:145], v[114:117], v[34:49]
	v_exp_f32_e32 v166, v166
	v_exp_f32_e32 v167, v167
	v_exp_f32_e32 v168, v168
	v_add_f32_e32 v27, v27, v166
	v_exp_f32_e32 v169, v169
	ds_read_b128 v[218:221], v2
	ds_read_b128 v[214:217], v2 offset:512
	ds_read_b128 v[210:213], v2 offset:2048
	v_mfma_f32_32x32x16_bf16 v[50:65], v[142:145], v[240:243], v[50:65]
	v_add_f32_e32 v27, v27, v167
	v_exp_f32_e32 v170, v170
	v_add_f32_e32 v27, v27, v168
	v_exp_f32_e32 v171, v171
	v_add_f32_e32 v27, v27, v169
	ds_read_b128 v[206:209], v2 offset:2560
	ds_read_b128 v[202:205], v2 offset:4096
	ds_read_b128 v[198:201], v2 offset:4608
	v_mfma_f32_32x32x16_bf16 v[34:49], v[150:153], v[118:121], v[34:49]
	v_exp_f32_e32 v172, v172
	v_add_f32_e32 v27, v27, v170
	v_exp_f32_e32 v173, v173
	v_add_f32_e32 v27, v27, v171
	v_add_f32_e32 v27, v27, v172
	ds_read_b128 v[194:197], v2 offset:6144
	ds_read_b128 v[190:193], v2 offset:6656
	ds_read_b128 v[186:189], v2 offset:8192
	v_mfma_f32_32x32x16_bf16 v[50:65], v[150:153], v[244:247], v[50:65]
	v_add_f32_e32 v27, v27, v173
	v_cvt_pk_bf16_f32 v166, v166, v167
	v_cvt_pk_bf16_f32 v167, v168, v169
	v_cvt_pk_bf16_f32 v168, v170, v171
	v_cvt_pk_bf16_f32 v169, v172, v173
	v_add_f32_e32 v236, v236, v27
	ds_read_b128 v[182:185], v2 offset:8704
	ds_read_b128 v[178:181], v2 offset:10240
	ds_read_b128 v[174:177], v2 offset:10752
	v_mfma_f32_32x32x16_bf16 v[34:49], v[158:161], v[122:125], v[34:49]
	v_max3_f32 v19, v82, v83, v84
	v_max3_f32 v26, v85, v86, v87
	v_max3_f32 v19, v19, v88, v89
	v_max3_f32 v26, v26, v90, v91
	v_mfma_f32_32x32x16_bf16 v[50:65], v[158:161], v[248:251], v[50:65]
	v_max3_f32 v19, v19, v92, v93
	v_max3_f32 v26, v26, v94, v95
	v_max3_f32 v19, v19, v96, v97
	v_max3_f32 v26, v26, v98, v99
	v_mfma_f32_32x32x16_bf16 v[34:49], v[166:169], v[126:129], v[34:49]
	v_max3_f32 v19, v19, v100, v101
	v_max3_f32 v26, v26, v102, v103
	v_max3_f32 v19, v19, v104, v105
	v_max3_f32 v26, v26, v106, v107
	v_mfma_f32_32x32x16_bf16 v[50:65], v[166:169], v[20:23], v[50:65]
	v_max3_f32 v19, v19, v108, v109
	v_max3_f32 v26, v26, v110, v111
	v_max3_f32 v19, v19, v112, v113
	v_max_f32_e32 v19, v19, v26
	v_cmp_lt_f32_e32 vcc, s41, v19
	s_cbranch_vccz .Lmy_nors_8
	s_nop 15
	s_nop 15
	v_mov_b32_e32 v26, v19
	s_nop 1
	v_permlane32_swap_b32_e32 v19, v26
	v_max_f32_e32 v19, v19, v26
	v_max_f32_e32 v19, v19, v19
	v_max_f32_e32 v150, 0, v19
	v_exp_f32_e64 v151, -v150
	v_add_f32_e32 v239, v239, v150
	v_xor_b32_e32 v66, 0x80000000, v239
	v_mov_b32_e32 v67, v66
	v_mov_b32_e32 v68, v66
	v_mov_b32_e32 v69, v66
	v_mov_b32_e32 v70, v66
	v_mov_b32_e32 v71, v66
	v_mov_b32_e32 v72, v66
	v_mov_b32_e32 v73, v66
	v_mov_b32_e32 v74, v66
	v_mov_b32_e32 v75, v66
	v_mov_b32_e32 v76, v66
	v_mov_b32_e32 v77, v66
	v_mov_b32_e32 v78, v66
	v_mov_b32_e32 v79, v66
	v_mov_b32_e32 v80, v66
	v_mov_b32_e32 v81, v66
	v_sub_f32_e32 v82, v82, v150
	v_sub_f32_e32 v83, v83, v150
	v_sub_f32_e32 v84, v84, v150
	v_sub_f32_e32 v85, v85, v150
	v_sub_f32_e32 v86, v86, v150
	v_sub_f32_e32 v87, v87, v150
	v_sub_f32_e32 v88, v88, v150
	v_sub_f32_e32 v89, v89, v150
	v_sub_f32_e32 v90, v90, v150
	v_sub_f32_e32 v91, v91, v150
	v_sub_f32_e32 v92, v92, v150
	v_sub_f32_e32 v93, v93, v150
	v_sub_f32_e32 v94, v94, v150
	v_sub_f32_e32 v95, v95, v150
	v_sub_f32_e32 v96, v96, v150
	v_sub_f32_e32 v97, v97, v150
	v_sub_f32_e32 v98, v98, v150
	v_sub_f32_e32 v99, v99, v150
	v_sub_f32_e32 v100, v100, v150
	v_sub_f32_e32 v101, v101, v150
	v_sub_f32_e32 v102, v102, v150
	v_sub_f32_e32 v103, v103, v150
	v_sub_f32_e32 v104, v104, v150
	v_sub_f32_e32 v105, v105, v150
	v_sub_f32_e32 v106, v106, v150
	v_sub_f32_e32 v107, v107, v150
	v_sub_f32_e32 v108, v108, v150
	v_sub_f32_e32 v109, v109, v150
	v_sub_f32_e32 v110, v110, v150
	v_sub_f32_e32 v111, v111, v150
	v_sub_f32_e32 v112, v112, v150
	v_sub_f32_e32 v113, v113, v150
	v_mul_f32_e32 v236, v236, v151
	s_mov_b64 s[96:97], exec
	s_and_b64 exec, exec, s[8:9]
	ds_write_b32 v235, v151
	s_mov_b64 exec, s[96:97]
	v_lshl_add_u32 v2, v228, 4, s47
	ds_read_b128 v[154:157], v2 offset:0
	s_waitcnt lgkmcnt(0)
	v_mul_f32_e32 v34, v34, v154
	v_mul_f32_e32 v50, v50, v154
	v_mul_f32_e32 v35, v35, v155
	v_mul_f32_e32 v51, v51, v155
	v_mul_f32_e32 v36, v36, v156
	v_mul_f32_e32 v52, v52, v156
	v_mul_f32_e32 v37, v37, v157
	v_mul_f32_e32 v53, v53, v157
	ds_read_b128 v[154:157], v2 offset:32
	s_waitcnt lgkmcnt(0)
	v_mul_f32_e32 v38, v38, v154
	v_mul_f32_e32 v54, v54, v154
	v_mul_f32_e32 v39, v39, v155
	v_mul_f32_e32 v55, v55, v155
	v_mul_f32_e32 v40, v40, v156
	v_mul_f32_e32 v56, v56, v156
	v_mul_f32_e32 v41, v41, v157
	v_mul_f32_e32 v57, v57, v157
	ds_read_b128 v[154:157], v2 offset:64
	s_waitcnt lgkmcnt(0)
	v_mul_f32_e32 v42, v42, v154
	v_mul_f32_e32 v58, v58, v154
	v_mul_f32_e32 v43, v43, v155
	v_mul_f32_e32 v59, v59, v155
	v_mul_f32_e32 v44, v44, v156
	v_mul_f32_e32 v60, v60, v156
	v_mul_f32_e32 v45, v45, v157
	v_mul_f32_e32 v61, v61, v157
	ds_read_b128 v[154:157], v2 offset:96
	s_waitcnt lgkmcnt(0)
	v_mul_f32_e32 v46, v46, v154
	v_mul_f32_e32 v62, v62, v154
	v_mul_f32_e32 v47, v47, v155
	v_mul_f32_e32 v63, v63, v155
	v_mul_f32_e32 v48, v48, v156
	v_mul_f32_e32 v64, v64, v156
	v_mul_f32_e32 v49, v49, v157
	v_mul_f32_e32 v65, v65, v157
.Lmy_nors_8:
	s_waitcnt lgkmcnt(6)
	v_add_u32_e32 v2, 0x4000, v237
	v_mfma_f32_32x32x16_bf16 v[142:157], v[218:221], v[4:7], v[66:81]
	v_exp_f32_e32 v82, v82
	v_exp_f32_e32 v83, v83
	v_exp_f32_e32 v84, v84
	v_add_f32_e32 v27, v82, v83
	v_exp_f32_e32 v85, v85
	v_mfma_f32_32x32x16_bf16 v[158:173], v[214:217], v[4:7], v[66:81]
	v_exp_f32_e32 v86, v86
	v_add_f32_e32 v27, v27, v84
	v_exp_f32_e32 v87, v87
	v_add_f32_e32 v27, v27, v85
	v_exp_f32_e32 v88, v88
	v_mfma_f32_32x32x16_bf16 v[142:157], v[210:213], v[8:11], v[142:157]
	v_add_f32_e32 v27, v27, v86
	v_exp_f32_e32 v89, v89
	v_add_f32_e32 v27, v27, v87
	v_add_f32_e32 v27, v27, v88
	v_add_f32_e32 v27, v27, v89
	v_mfma_f32_32x32x16_bf16 v[158:173], v[206:209], v[8:11], v[158:173]
	v_cvt_pk_bf16_f32 v82, v82, v83
	v_cvt_pk_bf16_f32 v83, v84, v85
	v_cvt_pk_bf16_f32 v84, v86, v87
	v_cvt_pk_bf16_f32 v85, v88, v89
	v_mfma_f32_32x32x16_bf16 v[142:157], v[202:205], v[12:15], v[142:157]
	v_exp_f32_e32 v90, v90
	v_exp_f32_e32 v91, v91
	v_exp_f32_e32 v92, v92
	v_add_f32_e32 v27, v27, v90
	v_exp_f32_e32 v93, v93
	v_mfma_f32_32x32x16_bf16 v[158:173], v[198:201], v[12:15], v[158:173]
	v_add_f32_e32 v27, v27, v91
	v_exp_f32_e32 v94, v94
	v_add_f32_e32 v27, v27, v92
	v_exp_f32_e32 v95, v95
	v_add_f32_e32 v27, v27, v93
	s_waitcnt lgkmcnt(0)
	s_waitcnt vmcnt(6)
	s_barrier
	v_mfma_f32_32x32x16_bf16 v[142:157], v[194:197], v[130:133], v[142:157]
	s_add_u32 m0, s57, 0x2000
	v_exp_f32_e32 v96, v96
	v_add_f32_e32 v27, v27, v94
	global_load_lds_dwordx4 v[28:29], off
	v_lshl_add_u64 v[28:29], v[28:29], 0, s[30:31]
	v_exp_f32_e32 v97, v97
	v_add_f32_e32 v27, v27, v95
	v_add_f32_e32 v27, v27, v96
	ds_read_b64_tr_b16 v[114:115], v2 offset:49152
	ds_read_b64_tr_b16 v[116:117], v2 offset:49664
	ds_read_b64_tr_b16 v[118:119], v2 offset:50176
	ds_read_b64_tr_b16 v[120:121], v2 offset:50688
	v_mfma_f32_32x32x16_bf16 v[158:173], v[190:193], v[130:133], v[158:173]
	s_add_u32 m0, s40, 0x9000
	v_add_f32_e32 v27, v27, v97
	v_cvt_pk_bf16_f32 v90, v90, v91
	global_load_lds_dwordx4 v[24:25], off
	v_lshl_add_u64 v[24:25], v[24:25], 0, s[30:31]
	v_cvt_pk_bf16_f32 v91, v92, v93
	v_cvt_pk_bf16_f32 v92, v94, v95
	v_cvt_pk_bf16_f32 v93, v96, v97
	ds_read_b64_tr_b16 v[122:123], v2 offset:51200
	ds_read_b64_tr_b16 v[124:125], v2 offset:51712
	ds_read_b64_tr_b16 v[126:127], v2 offset:52224
	ds_read_b64_tr_b16 v[128:129], v2 offset:52736
	v_mfma_f32_32x32x16_bf16 v[142:157], v[186:189], v[134:137], v[142:157]
	s_add_u32 m0, s43, 0x9000
	v_exp_f32_e32 v98, v98
	v_exp_f32_e32 v99, v99
	global_load_lds_dwordx4 v[30:31], off
	v_lshl_add_u64 v[30:31], v[30:31], 0, s[12:13]
	v_exp_f32_e32 v100, v100
	v_add_f32_e32 v27, v27, v98
	v_exp_f32_e32 v101, v101
	ds_read_b64_tr_b16 v[240:241], v2 offset:53248
	ds_read_b64_tr_b16 v[242:243], v2 offset:53760
	ds_read_b64_tr_b16 v[244:245], v2 offset:54272
	ds_read_b64_tr_b16 v[246:247], v2 offset:54784
	v_mfma_f32_32x32x16_bf16 v[158:173], v[182:185], v[134:137], v[158:173]
	v_add_f32_e32 v27, v27, v99
	v_exp_f32_e32 v102, v102
	v_add_f32_e32 v27, v27, v100
	v_exp_f32_e32 v103, v103
	v_add_f32_e32 v27, v27, v101
	ds_read_b64_tr_b16 v[248:249], v2 offset:55296
	ds_read_b64_tr_b16 v[250:251], v2 offset:55808
	ds_read_b64_tr_b16 v[20:21], v2 offset:56320
	ds_read_b64_tr_b16 v[22:23], v2 offset:56832
	v_mfma_f32_32x32x16_bf16 v[142:157], v[178:181], v[138:141], v[142:157]
	v_exp_f32_e32 v104, v104
	v_add_f32_e32 v27, v27, v102
	v_exp_f32_e32 v105, v105
	v_add_f32_e32 v27, v27, v103
	v_add_f32_e32 v27, v27, v104
	v_mfma_f32_32x32x16_bf16 v[158:173], v[174:177], v[138:141], v[158:173]
	v_add_f32_e32 v27, v27, v105
	v_cvt_pk_bf16_f32 v98, v98, v99
	v_cvt_pk_bf16_f32 v99, v100, v101
	v_cvt_pk_bf16_f32 v100, v102, v103
	v_cvt_pk_bf16_f32 v101, v104, v105
	s_waitcnt lgkmcnt(0)
	v_mov_b32_e32 v2, v238
	v_mfma_f32_32x32x16_bf16 v[34:49], v[82:85], v[114:117], v[34:49]
	v_exp_f32_e32 v106, v106
	v_exp_f32_e32 v107, v107
	v_exp_f32_e32 v108, v108
	v_add_f32_e32 v27, v27, v106
	v_exp_f32_e32 v109, v109
	ds_read_b128 v[218:221], v2
	ds_read_b128 v[214:217], v2 offset:512
	ds_read_b128 v[210:213], v2 offset:2048
	v_mfma_f32_32x32x16_bf16 v[50:65], v[82:85], v[240:243], v[50:65]
	v_add_f32_e32 v27, v27, v107
	v_exp_f32_e32 v110, v110
	v_add_f32_e32 v27, v27, v108
	v_exp_f32_e32 v111, v111
	v_add_f32_e32 v27, v27, v109
	ds_read_b128 v[206:209], v2 offset:2560
	ds_read_b128 v[202:205], v2 offset:4096
	ds_read_b128 v[198:201], v2 offset:4608
	v_mfma_f32_32x32x16_bf16 v[34:49], v[90:93], v[118:121], v[34:49]
	v_exp_f32_e32 v112, v112
	v_add_f32_e32 v27, v27, v110
	v_exp_f32_e32 v113, v113
	v_add_f32_e32 v27, v27, v111
	v_add_f32_e32 v27, v27, v112
	ds_read_b128 v[194:197], v2 offset:6144
	ds_read_b128 v[190:193], v2 offset:6656
	ds_read_b128 v[186:189], v2 offset:8192
	v_mfma_f32_32x32x16_bf16 v[50:65], v[90:93], v[244:247], v[50:65]
	v_add_f32_e32 v27, v27, v113
	v_cvt_pk_bf16_f32 v106, v106, v107
	v_cvt_pk_bf16_f32 v107, v108, v109
	v_cvt_pk_bf16_f32 v108, v110, v111
	v_cvt_pk_bf16_f32 v109, v112, v113
	v_add_f32_e32 v236, v236, v27
	ds_read_b128 v[182:185], v2 offset:8704
	ds_read_b128 v[178:181], v2 offset:10240
	ds_read_b128 v[174:177], v2 offset:10752
	v_mfma_f32_32x32x16_bf16 v[34:49], v[98:101], v[122:125], v[34:49]
	v_max3_f32 v19, v142, v143, v144
	v_max3_f32 v26, v145, v146, v147
	v_max3_f32 v19, v19, v148, v149
	v_max3_f32 v26, v26, v150, v151
	v_mfma_f32_32x32x16_bf16 v[50:65], v[98:101], v[248:251], v[50:65]
	v_max3_f32 v19, v19, v152, v153
	v_max3_f32 v26, v26, v154, v155
	v_max3_f32 v19, v19, v156, v157
	v_max3_f32 v26, v26, v158, v159
	v_mfma_f32_32x32x16_bf16 v[34:49], v[106:109], v[126:129], v[34:49]
	v_max3_f32 v19, v19, v160, v161
	v_max3_f32 v26, v26, v162, v163
	v_max3_f32 v19, v19, v164, v165
	v_max3_f32 v26, v26, v166, v167
	v_mfma_f32_32x32x16_bf16 v[50:65], v[106:109], v[20:23], v[50:65]
	v_max3_f32 v19, v19, v168, v169
	v_max3_f32 v26, v26, v170, v171
	v_max3_f32 v19, v19, v172, v173
	v_max_f32_e32 v19, v19, v26
	v_cmp_lt_f32_e32 vcc, s41, v19
	s_cbranch_vccz .Lmy_nors_9
	s_nop 15
	s_nop 15
	v_mov_b32_e32 v26, v19
	s_nop 1
	v_permlane32_swap_b32_e32 v19, v26
	v_max_f32_e32 v19, v19, v26
	v_max_f32_e32 v19, v19, v19
	v_max_f32_e32 v90, 0, v19
	v_exp_f32_e64 v91, -v90
	v_add_f32_e32 v239, v239, v90
	v_xor_b32_e32 v66, 0x80000000, v239
	v_mov_b32_e32 v67, v66
	v_mov_b32_e32 v68, v66
	v_mov_b32_e32 v69, v66
	v_mov_b32_e32 v70, v66
	v_mov_b32_e32 v71, v66
	v_mov_b32_e32 v72, v66
	v_mov_b32_e32 v73, v66
	v_mov_b32_e32 v74, v66
	v_mov_b32_e32 v75, v66
	v_mov_b32_e32 v76, v66
	v_mov_b32_e32 v77, v66
	v_mov_b32_e32 v78, v66
	v_mov_b32_e32 v79, v66
	v_mov_b32_e32 v80, v66
	v_mov_b32_e32 v81, v66
	v_sub_f32_e32 v142, v142, v90
	v_sub_f32_e32 v143, v143, v90
	v_sub_f32_e32 v144, v144, v90
	v_sub_f32_e32 v145, v145, v90
	v_sub_f32_e32 v146, v146, v90
	v_sub_f32_e32 v147, v147, v90
	v_sub_f32_e32 v148, v148, v90
	v_sub_f32_e32 v149, v149, v90
	v_sub_f32_e32 v150, v150, v90
	v_sub_f32_e32 v151, v151, v90
	v_sub_f32_e32 v152, v152, v90
	v_sub_f32_e32 v153, v153, v90
	v_sub_f32_e32 v154, v154, v90
	v_sub_f32_e32 v155, v155, v90
	v_sub_f32_e32 v156, v156, v90
	v_sub_f32_e32 v157, v157, v90
	v_sub_f32_e32 v158, v158, v90
	v_sub_f32_e32 v159, v159, v90
	v_sub_f32_e32 v160, v160, v90
	v_sub_f32_e32 v161, v161, v90
	v_sub_f32_e32 v162, v162, v90
	v_sub_f32_e32 v163, v163, v90
	v_sub_f32_e32 v164, v164, v90
	v_sub_f32_e32 v165, v165, v90
	v_sub_f32_e32 v166, v166, v90
	v_sub_f32_e32 v167, v167, v90
	v_sub_f32_e32 v168, v168, v90
	v_sub_f32_e32 v169, v169, v90
	v_sub_f32_e32 v170, v170, v90
	v_sub_f32_e32 v171, v171, v90
	v_sub_f32_e32 v172, v172, v90
	v_sub_f32_e32 v173, v173, v90
	v_mul_f32_e32 v236, v236, v91
	s_mov_b64 s[96:97], exec
	s_and_b64 exec, exec, s[8:9]
	ds_write_b32 v235, v91
	s_mov_b64 exec, s[96:97]
	v_lshl_add_u32 v2, v228, 4, s47
	ds_read_b128 v[94:97], v2 offset:0
	s_waitcnt lgkmcnt(0)
	v_mul_f32_e32 v34, v34, v94
	v_mul_f32_e32 v50, v50, v94
	v_mul_f32_e32 v35, v35, v95
	v_mul_f32_e32 v51, v51, v95
	v_mul_f32_e32 v36, v36, v96
	v_mul_f32_e32 v52, v52, v96
	v_mul_f32_e32 v37, v37, v97
	v_mul_f32_e32 v53, v53, v97
	ds_read_b128 v[94:97], v2 offset:32
	s_waitcnt lgkmcnt(0)
	v_mul_f32_e32 v38, v38, v94
	v_mul_f32_e32 v54, v54, v94
	v_mul_f32_e32 v39, v39, v95
	v_mul_f32_e32 v55, v55, v95
	v_mul_f32_e32 v40, v40, v96
	v_mul_f32_e32 v56, v56, v96
	v_mul_f32_e32 v41, v41, v97
	v_mul_f32_e32 v57, v57, v97
	ds_read_b128 v[94:97], v2 offset:64
	s_waitcnt lgkmcnt(0)
	v_mul_f32_e32 v42, v42, v94
	v_mul_f32_e32 v58, v58, v94
	v_mul_f32_e32 v43, v43, v95
	v_mul_f32_e32 v59, v59, v95
	v_mul_f32_e32 v44, v44, v96
	v_mul_f32_e32 v60, v60, v96
	v_mul_f32_e32 v45, v45, v97
	v_mul_f32_e32 v61, v61, v97
	ds_read_b128 v[94:97], v2 offset:96
	s_waitcnt lgkmcnt(0)
	v_mul_f32_e32 v46, v46, v94
	v_mul_f32_e32 v62, v62, v94
	v_mul_f32_e32 v47, v47, v95
	v_mul_f32_e32 v63, v63, v95
	v_mul_f32_e32 v48, v48, v96
	v_mul_f32_e32 v64, v64, v96
	v_mul_f32_e32 v49, v49, v97
	v_mul_f32_e32 v65, v65, v97

.Lmy_tf_13:
	s_waitcnt lgkmcnt(6)
	v_mov_b32_e32 v2, v237
	v_mfma_f32_32x32x16_bf16 v[142:157], v[218:221], v[4:7], v[66:81]
	v_exp_f32_e32 v82, v82
	v_exp_f32_e32 v83, v83
	v_exp_f32_e32 v84, v84
	v_add_f32_e32 v27, v82, v83
	v_exp_f32_e32 v85, v85
	v_mfma_f32_32x32x16_bf16 v[158:173], v[214:217], v[4:7], v[66:81]
	v_exp_f32_e32 v86, v86
	v_add_f32_e32 v27, v27, v84
	v_exp_f32_e32 v87, v87
	v_add_f32_e32 v27, v27, v85
	v_exp_f32_e32 v88, v88
	v_mfma_f32_32x32x16_bf16 v[142:157], v[210:213], v[8:11], v[142:157]
	v_add_f32_e32 v27, v27, v86
	v_exp_f32_e32 v89, v89
	v_add_f32_e32 v27, v27, v87
	v_add_f32_e32 v27, v27, v88
	v_add_f32_e32 v27, v27, v89
	v_mfma_f32_32x32x16_bf16 v[158:173], v[206:209], v[8:11], v[158:173]
	v_cvt_pk_bf16_f32 v82, v82, v83
	v_cvt_pk_bf16_f32 v83, v84, v85
	v_cvt_pk_bf16_f32 v84, v86, v87
	v_cvt_pk_bf16_f32 v85, v88, v89
	v_mfma_f32_32x32x16_bf16 v[142:157], v[202:205], v[12:15], v[142:157]
	v_exp_f32_e32 v90, v90
	v_exp_f32_e32 v91, v91
	v_exp_f32_e32 v92, v92
	v_add_f32_e32 v27, v27, v90
	v_exp_f32_e32 v93, v93
	v_mfma_f32_32x32x16_bf16 v[158:173], v[198:201], v[12:15], v[158:173]
	v_add_f32_e32 v27, v27, v91
	v_exp_f32_e32 v94, v94
	v_add_f32_e32 v27, v27, v92
	v_exp_f32_e32 v95, v95
	v_add_f32_e32 v27, v27, v93
	s_waitcnt lgkmcnt(0)
	s_waitcnt vmcnt(3)
	s_barrier
	v_mfma_f32_32x32x16_bf16 v[142:157], v[194:197], v[130:133], v[142:157]
	s_add_u32 m0, s57, 0x6000
	v_exp_f32_e32 v96, v96
	v_add_f32_e32 v27, v27, v94
	global_load_lds_dwordx4 v[28:29], off
	v_lshl_add_u64 v[28:29], v[28:29], 0, s[30:31]
	v_exp_f32_e32 v97, v97
	v_add_f32_e32 v27, v27, v95
	v_add_f32_e32 v27, v27, v96
	ds_read_b64_tr_b16 v[114:115], v2 offset:49152
	ds_read_b64_tr_b16 v[116:117], v2 offset:49664
	ds_read_b64_tr_b16 v[118:119], v2 offset:50176
	ds_read_b64_tr_b16 v[120:121], v2 offset:50688
	v_mfma_f32_32x32x16_bf16 v[158:173], v[190:193], v[130:133], v[158:173]
	v_add_f32_e32 v27, v27, v97
	v_cvt_pk_bf16_f32 v90, v90, v91
	v_cvt_pk_bf16_f32 v91, v92, v93
	v_cvt_pk_bf16_f32 v92, v94, v95
	v_cvt_pk_bf16_f32 v93, v96, v97
	ds_read_b64_tr_b16 v[122:123], v2 offset:51200
	ds_read_b64_tr_b16 v[124:125], v2 offset:51712
	ds_read_b64_tr_b16 v[126:127], v2 offset:52224
	ds_read_b64_tr_b16 v[128:129], v2 offset:52736
	v_mfma_f32_32x32x16_bf16 v[142:157], v[186:189], v[134:137], v[142:157]
	v_exp_f32_e32 v98, v98
	v_exp_f32_e32 v99, v99
	v_exp_f32_e32 v100, v100
	v_add_f32_e32 v27, v27, v98
	v_exp_f32_e32 v101, v101
	ds_read_b64_tr_b16 v[240:241], v2 offset:53248
	ds_read_b64_tr_b16 v[242:243], v2 offset:53760
	ds_read_b64_tr_b16 v[244:245], v2 offset:54272
	ds_read_b64_tr_b16 v[246:247], v2 offset:54784
	v_mfma_f32_32x32x16_bf16 v[158:173], v[182:185], v[134:137], v[158:173]
	v_add_f32_e32 v27, v27, v99
	v_exp_f32_e32 v102, v102
	v_add_f32_e32 v27, v27, v100
	v_exp_f32_e32 v103, v103
	v_add_f32_e32 v27, v27, v101
	ds_read_b64_tr_b16 v[248:249], v2 offset:55296
	ds_read_b64_tr_b16 v[250:251], v2 offset:55808
	ds_read_b64_tr_b16 v[20:21], v2 offset:56320
	ds_read_b64_tr_b16 v[22:23], v2 offset:56832
	v_mfma_f32_32x32x16_bf16 v[142:157], v[178:181], v[138:141], v[142:157]
	v_exp_f32_e32 v104, v104
	v_add_f32_e32 v27, v27, v102
	v_exp_f32_e32 v105, v105
	v_add_f32_e32 v27, v27, v103
	v_add_f32_e32 v27, v27, v104
	v_mfma_f32_32x32x16_bf16 v[158:173], v[174:177], v[138:141], v[158:173]
	v_add_f32_e32 v27, v27, v105
	v_cvt_pk_bf16_f32 v98, v98, v99
	v_cvt_pk_bf16_f32 v99, v100, v101
	v_cvt_pk_bf16_f32 v100, v102, v103
	v_cvt_pk_bf16_f32 v101, v104, v105
	s_waitcnt lgkmcnt(0)
	v_add_u32_e32 v2, 0x6000, v238
	v_mfma_f32_32x32x16_bf16 v[34:49], v[82:85], v[114:117], v[34:49]
	v_exp_f32_e32 v106, v106
	v_exp_f32_e32 v107, v107
	v_exp_f32_e32 v108, v108
	v_add_f32_e32 v27, v27, v106
	v_exp_f32_e32 v109, v109
	s_cmp_gt_u32 s71, 1
	s_cbranch_scc0 .Lmy_nok_16
	ds_read_b128 v[218:221], v2
	ds_read_b128 v[214:217], v2 offset:512
	ds_read_b128 v[210:213], v2 offset:2048
	ds_read_b128 v[206:209], v2 offset:2560
	ds_read_b128 v[202:205], v2 offset:4096
	ds_read_b128 v[198:201], v2 offset:4608
	ds_read_b128 v[194:197], v2 offset:6144
	ds_read_b128 v[190:193], v2 offset:6656
	ds_read_b128 v[186:189], v2 offset:8192
	ds_read_b128 v[182:185], v2 offset:8704
	ds_read_b128 v[178:181], v2 offset:10240
	ds_read_b128 v[174:177], v2 offset:10752

.Lmy_tf_18:
	s_waitcnt lgkmcnt(6)
	v_add_u32_e32 v2, 0x2000, v237
	v_mfma_f32_32x32x16_bf16 v[82:97], v[218:221], v[4:7], v[66:81]
	v_exp_f32_e32 v142, v142
	v_exp_f32_e32 v143, v143
	v_exp_f32_e32 v144, v144
	v_add_f32_e32 v27, v142, v143
	v_exp_f32_e32 v145, v145
	v_mfma_f32_32x32x16_bf16 v[98:113], v[214:217], v[4:7], v[66:81]
	v_exp_f32_e32 v146, v146
	v_add_f32_e32 v27, v27, v144
	v_exp_f32_e32 v147, v147
	v_add_f32_e32 v27, v27, v145
	v_exp_f32_e32 v148, v148
	v_mfma_f32_32x32x16_bf16 v[82:97], v[210:213], v[8:11], v[82:97]
	v_add_f32_e32 v27, v27, v146
	v_exp_f32_e32 v149, v149
	v_add_f32_e32 v27, v27, v147
	v_add_f32_e32 v27, v27, v148
	v_add_f32_e32 v27, v27, v149
	v_mfma_f32_32x32x16_bf16 v[98:113], v[206:209], v[8:11], v[98:113]
	v_cvt_pk_bf16_f32 v142, v142, v143
	v_cvt_pk_bf16_f32 v143, v144, v145
	v_cvt_pk_bf16_f32 v144, v146, v147
	v_cvt_pk_bf16_f32 v145, v148, v149
	v_mfma_f32_32x32x16_bf16 v[82:97], v[202:205], v[12:15], v[82:97]
	v_exp_f32_e32 v150, v150
	v_exp_f32_e32 v151, v151
	v_exp_f32_e32 v152, v152
	v_add_f32_e32 v27, v27, v150
	v_exp_f32_e32 v153, v153
	v_mfma_f32_32x32x16_bf16 v[98:113], v[198:201], v[12:15], v[98:113]
	v_add_f32_e32 v27, v27, v151
	v_exp_f32_e32 v154, v154
	v_add_f32_e32 v27, v27, v152
	v_exp_f32_e32 v155, v155
	v_add_f32_e32 v27, v27, v153
	s_waitcnt lgkmcnt(0)
	s_waitcnt vmcnt(1)
	s_barrier
	v_mfma_f32_32x32x16_bf16 v[82:97], v[194:197], v[130:133], v[82:97]
	v_exp_f32_e32 v156, v156
	v_add_f32_e32 v27, v27, v154
	v_exp_f32_e32 v157, v157
	v_add_f32_e32 v27, v27, v155
	v_add_f32_e32 v27, v27, v156
	ds_read_b64_tr_b16 v[114:115], v2 offset:49152
	ds_read_b64_tr_b16 v[116:117], v2 offset:49664
	ds_read_b64_tr_b16 v[118:119], v2 offset:50176
	ds_read_b64_tr_b16 v[120:121], v2 offset:50688
	v_mfma_f32_32x32x16_bf16 v[98:113], v[190:193], v[130:133], v[98:113]
	v_add_f32_e32 v27, v27, v157
	v_cvt_pk_bf16_f32 v150, v150, v151
	v_cvt_pk_bf16_f32 v151, v152, v153
	v_cvt_pk_bf16_f32 v152, v154, v155
	v_cvt_pk_bf16_f32 v153, v156, v157
	ds_read_b64_tr_b16 v[122:123], v2 offset:51200
	ds_read_b64_tr_b16 v[124:125], v2 offset:51712
	ds_read_b64_tr_b16 v[126:127], v2 offset:52224
	ds_read_b64_tr_b16 v[128:129], v2 offset:52736
	v_mfma_f32_32x32x16_bf16 v[82:97], v[186:189], v[134:137], v[82:97]
	v_exp_f32_e32 v158, v158
	v_exp_f32_e32 v159, v159
	v_exp_f32_e32 v160, v160
	v_add_f32_e32 v27, v27, v158
	v_exp_f32_e32 v161, v161
	ds_read_b64_tr_b16 v[240:241], v2 offset:53248
	ds_read_b64_tr_b16 v[242:243], v2 offset:53760
	ds_read_b64_tr_b16 v[244:245], v2 offset:54272
	ds_read_b64_tr_b16 v[246:247], v2 offset:54784
	v_mfma_f32_32x32x16_bf16 v[98:113], v[182:185], v[134:137], v[98:113]
	v_add_f32_e32 v27, v27, v159
	v_exp_f32_e32 v162, v162
	v_add_f32_e32 v27, v27, v160
	v_exp_f32_e32 v163, v163
	v_add_f32_e32 v27, v27, v161
	ds_read_b64_tr_b16 v[248:249], v2 offset:55296
	ds_read_b64_tr_b16 v[250:251], v2 offset:55808
	ds_read_b64_tr_b16 v[20:21], v2 offset:56320
	ds_read_b64_tr_b16 v[22:23], v2 offset:56832
	v_mfma_f32_32x32x16_bf16 v[82:97], v[178:181], v[138:141], v[82:97]
	v_exp_f32_e32 v164, v164
	v_add_f32_e32 v27, v27, v162
	v_exp_f32_e32 v165, v165
	v_add_f32_e32 v27, v27, v163
	v_add_f32_e32 v27, v27, v164
	v_mfma_f32_32x32x16_bf16 v[98:113], v[174:177], v[138:141], v[98:113]
	v_add_f32_e32 v27, v27, v165
	v_cvt_pk_bf16_f32 v158, v158, v159
	v_cvt_pk_bf16_f32 v159, v160, v161
	v_cvt_pk_bf16_f32 v160, v162, v163
	v_cvt_pk_bf16_f32 v161, v164, v165
	s_waitcnt lgkmcnt(0)
	v_add_u32_e32 v2, 0x9000, v238
	v_mfma_f32_32x32x16_bf16 v[34:49], v[142:145], v[114:117], v[34:49]
	v_exp_f32_e32 v166, v166
	v_exp_f32_e32 v167, v167
	v_exp_f32_e32 v168, v168
	v_add_f32_e32 v27, v27, v166
	v_exp_f32_e32 v169, v169
	s_cmp_gt_u32 s71, 2
	s_cbranch_scc0 .Lmy_nok_21
	ds_read_b128 v[218:221], v2
	ds_read_b128 v[214:217], v2 offset:512
	ds_read_b128 v[210:213], v2 offset:2048
	ds_read_b128 v[206:209], v2 offset:2560
	ds_read_b128 v[202:205], v2 offset:4096
	ds_read_b128 v[198:201], v2 offset:4608
	ds_read_b128 v[194:197], v2 offset:6144
	ds_read_b128 v[190:193], v2 offset:6656
	ds_read_b128 v[186:189], v2 offset:8192
	ds_read_b128 v[182:185], v2 offset:8704
	ds_read_b128 v[178:181], v2 offset:10240
	ds_read_b128 v[174:177], v2 offset:10752

.Lmy_tf_23:
	s_waitcnt lgkmcnt(6)
	v_add_u32_e32 v2, 0x4000, v237
	v_mfma_f32_32x32x16_bf16 v[142:157], v[218:221], v[4:7], v[66:81]
	v_exp_f32_e32 v82, v82
	v_exp_f32_e32 v83, v83
	v_exp_f32_e32 v84, v84
	v_add_f32_e32 v27, v82, v83
	v_exp_f32_e32 v85, v85
	v_mfma_f32_32x32x16_bf16 v[158:173], v[214:217], v[4:7], v[66:81]
	v_exp_f32_e32 v86, v86
	v_add_f32_e32 v27, v27, v84
	v_exp_f32_e32 v87, v87
	v_add_f32_e32 v27, v27, v85
	v_exp_f32_e32 v88, v88
	v_mfma_f32_32x32x16_bf16 v[142:157], v[210:213], v[8:11], v[142:157]
	v_add_f32_e32 v27, v27, v86
	v_exp_f32_e32 v89, v89
	v_add_f32_e32 v27, v27, v87
	v_add_f32_e32 v27, v27, v88
	v_add_f32_e32 v27, v27, v89
	v_mfma_f32_32x32x16_bf16 v[158:173], v[206:209], v[8:11], v[158:173]
	v_cvt_pk_bf16_f32 v82, v82, v83
	v_cvt_pk_bf16_f32 v83, v84, v85
	v_cvt_pk_bf16_f32 v84, v86, v87
	v_cvt_pk_bf16_f32 v85, v88, v89
	v_mfma_f32_32x32x16_bf16 v[142:157], v[202:205], v[12:15], v[142:157]
	v_exp_f32_e32 v90, v90
	v_exp_f32_e32 v91, v91
	v_exp_f32_e32 v92, v92
	v_add_f32_e32 v27, v27, v90
	v_exp_f32_e32 v93, v93
	v_mfma_f32_32x32x16_bf16 v[158:173], v[198:201], v[12:15], v[158:173]
	v_add_f32_e32 v27, v27, v91
	v_exp_f32_e32 v94, v94
	v_add_f32_e32 v27, v27, v92
	v_exp_f32_e32 v95, v95
	v_add_f32_e32 v27, v27, v93
	s_waitcnt lgkmcnt(0)
	s_waitcnt vmcnt(0)
	s_barrier
	v_mfma_f32_32x32x16_bf16 v[142:157], v[194:197], v[130:133], v[142:157]
	v_exp_f32_e32 v96, v96
	v_add_f32_e32 v27, v27, v94
	v_exp_f32_e32 v97, v97
	v_add_f32_e32 v27, v27, v95
	v_add_f32_e32 v27, v27, v96
	ds_read_b64_tr_b16 v[114:115], v2 offset:49152
	ds_read_b64_tr_b16 v[116:117], v2 offset:49664
	ds_read_b64_tr_b16 v[118:119], v2 offset:50176
	ds_read_b64_tr_b16 v[120:121], v2 offset:50688
	v_mfma_f32_32x32x16_bf16 v[158:173], v[190:193], v[130:133], v[158:173]
	v_add_f32_e32 v27, v27, v97
	v_cvt_pk_bf16_f32 v90, v90, v91
	v_cvt_pk_bf16_f32 v91, v92, v93
	v_cvt_pk_bf16_f32 v92, v94, v95
	v_cvt_pk_bf16_f32 v93, v96, v97
	ds_read_b64_tr_b16 v[122:123], v2 offset:51200
	ds_read_b64_tr_b16 v[124:125], v2 offset:51712
	ds_read_b64_tr_b16 v[126:127], v2 offset:52224
	ds_read_b64_tr_b16 v[128:129], v2 offset:52736
	v_mfma_f32_32x32x16_bf16 v[142:157], v[186:189], v[134:137], v[142:157]
	v_exp_f32_e32 v98, v98
	v_exp_f32_e32 v99, v99
	v_exp_f32_e32 v100, v100
	v_add_f32_e32 v27, v27, v98
	v_exp_f32_e32 v101, v101
	ds_read_b64_tr_b16 v[240:241], v2 offset:53248
	ds_read_b64_tr_b16 v[242:243], v2 offset:53760
	ds_read_b64_tr_b16 v[244:245], v2 offset:54272
	ds_read_b64_tr_b16 v[246:247], v2 offset:54784
	v_mfma_f32_32x32x16_bf16 v[158:173], v[182:185], v[134:137], v[158:173]
	v_add_f32_e32 v27, v27, v99
	v_exp_f32_e32 v102, v102
	v_add_f32_e32 v27, v27, v100
	v_exp_f32_e32 v103, v103
	v_add_f32_e32 v27, v27, v101
	ds_read_b64_tr_b16 v[248:249], v2 offset:55296
	ds_read_b64_tr_b16 v[250:251], v2 offset:55808
	ds_read_b64_tr_b16 v[20:21], v2 offset:56320
	ds_read_b64_tr_b16 v[22:23], v2 offset:56832
	v_mfma_f32_32x32x16_bf16 v[142:157], v[178:181], v[138:141], v[142:157]
	v_exp_f32_e32 v104, v104
	v_add_f32_e32 v27, v27, v102
	v_exp_f32_e32 v105, v105
	v_add_f32_e32 v27, v27, v103
	v_add_f32_e32 v27, v27, v104
	v_mfma_f32_32x32x16_bf16 v[158:173], v[174:177], v[138:141], v[158:173]
	v_add_f32_e32 v27, v27, v105
	v_cvt_pk_bf16_f32 v98, v98, v99
	v_cvt_pk_bf16_f32 v99, v100, v101
	v_cvt_pk_bf16_f32 v100, v102, v103
	v_cvt_pk_bf16_f32 v101, v104, v105
	s_waitcnt lgkmcnt(0)
	v_mov_b32_e32 v2, v238
	v_mfma_f32_32x32x16_bf16 v[34:49], v[82:85], v[114:117], v[34:49]
	v_exp_f32_e32 v106, v106
	v_exp_f32_e32 v107, v107
	v_exp_f32_e32 v108, v108
	v_add_f32_e32 v27, v27, v106
	v_exp_f32_e32 v109, v109
	s_cmp_gt_u32 s71, 3
	s_cbranch_scc0 .Lmy_nok_26
	ds_read_b128 v[218:221], v2
	ds_read_b128 v[214:217], v2 offset:512
	ds_read_b128 v[210:213], v2 offset:2048
	ds_read_b128 v[206:209], v2 offset:2560
	ds_read_b128 v[202:205], v2 offset:4096
	ds_read_b128 v[198:201], v2 offset:4608
	ds_read_b128 v[194:197], v2 offset:6144
	ds_read_b128 v[190:193], v2 offset:6656
	ds_read_b128 v[186:189], v2 offset:8192
	ds_read_b128 v[182:185], v2 offset:8704
	ds_read_b128 v[178:181], v2 offset:10240
	ds_read_b128 v[174:177], v2 offset:10752

.Lmy_B_entry:
	s_mov_b32 s30, 0x20000
	s_mov_b32 s31, 0
	s_mov_b32 s12, 0x1000
	s_mov_b32 s13, 0
	s_lshr_b32 s71, s24, 1
	s_lshr_b32 s79, s25, 2
	s_add_i32 s79, s79, -1
	s_mov_b32 s0, 0x80000
	s_mov_b32 s1, 0
	v_lshl_add_u64 v[24:25], v[16:17], 0, s[0:1]
	s_mov_b32 s0, 0x60000
	v_lshl_add_u64 v[28:29], v[224:225], 0, s[0:1]
	s_mov_b32 s0, 0x4000
	v_lshl_add_u64 v[30:31], v[222:223], 0, s[0:1]
	s_waitcnt lgkmcnt(0)
	v_mfma_f32_32x32x16_bf16 v[82:97], v[218:221], v[4:7], v[66:81]
	v_mfma_f32_32x32x16_bf16 v[98:113], v[214:217], v[4:7], v[66:81]
	v_mfma_f32_32x32x16_bf16 v[82:97], v[210:213], v[8:11], v[82:97]
	v_mfma_f32_32x32x16_bf16 v[98:113], v[206:209], v[8:11], v[98:113]
	v_mfma_f32_32x32x16_bf16 v[82:97], v[202:205], v[12:15], v[82:97]
	v_mfma_f32_32x32x16_bf16 v[98:113], v[198:201], v[12:15], v[98:113]
	v_mfma_f32_32x32x16_bf16 v[82:97], v[194:197], v[130:133], v[82:97]
	v_mfma_f32_32x32x16_bf16 v[98:113], v[190:193], v[130:133], v[98:113]
	v_mfma_f32_32x32x16_bf16 v[82:97], v[186:189], v[134:137], v[82:97]
	v_mfma_f32_32x32x16_bf16 v[98:113], v[182:185], v[134:137], v[98:113]
	v_mfma_f32_32x32x16_bf16 v[82:97], v[178:181], v[138:141], v[82:97]
	v_mfma_f32_32x32x16_bf16 v[98:113], v[174:177], v[138:141], v[98:113]
	v_add_u32_e32 v2, 0x3000, v238
	ds_read_b128 v[218:221], v2
	ds_read_b128 v[214:217], v2 offset:512
	ds_read_b128 v[210:213], v2 offset:2048
	ds_read_b128 v[206:209], v2 offset:2560
	ds_read_b128 v[202:205], v2 offset:4096
	ds_read_b128 v[198:201], v2 offset:4608
	ds_read_b128 v[194:197], v2 offset:6144
	ds_read_b128 v[190:193], v2 offset:6656
	ds_read_b128 v[186:189], v2 offset:8192
	ds_read_b128 v[182:185], v2 offset:8704
	ds_read_b128 v[178:181], v2 offset:10240
	ds_read_b128 v[174:177], v2 offset:10752
	s_nop 7
	v_max3_f32 v19, v82, v83, v84
	v_max3_f32 v26, v85, v86, v87
	v_max3_f32 v19, v19, v88, v89
	v_max3_f32 v26, v26, v90, v91
	v_max3_f32 v19, v19, v92, v93
	v_max3_f32 v26, v26, v94, v95
	v_max3_f32 v19, v19, v96, v97
	v_max3_f32 v26, v26, v98, v99
	v_max3_f32 v19, v19, v100, v101
	v_max3_f32 v26, v26, v102, v103
	v_max3_f32 v19, v19, v104, v105
	v_max3_f32 v26, v26, v106, v107
	v_max3_f32 v19, v19, v108, v109
	v_max3_f32 v26, v26, v110, v111
	v_max3_f32 v19, v19, v112, v113
	v_max_f32_e32 v19, v19, v26
	v_mov_b32_e32 v26, v19
	s_nop 1
	v_permlane32_swap_b32_e32 v19, v26
	v_max_f32_e32 v19, v19, v26
	v_max_f32_e32 v19, v19, v19
	v_mov_b32_e32 v239, v19
	v_xor_b32_e32 v66, 0x80000000, v19
	v_mov_b32_e32 v67, v66
	v_mov_b32_e32 v68, v66
	v_mov_b32_e32 v69, v66
	v_mov_b32_e32 v70, v66
	v_mov_b32_e32 v71, v66
	v_mov_b32_e32 v72, v66
	v_mov_b32_e32 v73, v66
	v_mov_b32_e32 v74, v66
	v_mov_b32_e32 v75, v66
	v_mov_b32_e32 v76, v66
	v_mov_b32_e32 v77, v66
	v_mov_b32_e32 v78, v66
	v_mov_b32_e32 v79, v66
	v_mov_b32_e32 v80, v66
	v_mov_b32_e32 v81, v66
	v_sub_f32_e32 v82, v82, v19
	v_sub_f32_e32 v83, v83, v19
	v_sub_f32_e32 v84, v84, v19
	v_sub_f32_e32 v85, v85, v19
	v_sub_f32_e32 v86, v86, v19
	v_sub_f32_e32 v87, v87, v19
	v_sub_f32_e32 v88, v88, v19
	v_sub_f32_e32 v89, v89, v19
	v_sub_f32_e32 v90, v90, v19
	v_sub_f32_e32 v91, v91, v19
	v_sub_f32_e32 v92, v92, v19
	v_sub_f32_e32 v93, v93, v19
	v_sub_f32_e32 v94, v94, v19
	v_sub_f32_e32 v95, v95, v19
	v_sub_f32_e32 v96, v96, v19
	v_sub_f32_e32 v97, v97, v19
	v_sub_f32_e32 v98, v98, v19
	v_sub_f32_e32 v99, v99, v19
	v_sub_f32_e32 v100, v100, v19
	v_sub_f32_e32 v101, v101, v19
	v_sub_f32_e32 v102, v102, v19
	v_sub_f32_e32 v103, v103, v19
	v_sub_f32_e32 v104, v104, v19
	v_sub_f32_e32 v105, v105, v19
	v_sub_f32_e32 v106, v106, v19
	v_sub_f32_e32 v107, v107, v19
	v_sub_f32_e32 v108, v108, v19
	v_sub_f32_e32 v109, v109, v19
	v_sub_f32_e32 v110, v110, v19
	v_sub_f32_e32 v111, v111, v19
	v_sub_f32_e32 v112, v112, v19
	v_sub_f32_e32 v113, v113, v19
	s_cmp_lt_i32 s79, 1
	s_cbranch_scc1 .Lmy_B_tail
	s_waitcnt lgkmcnt(6)
	v_mov_b32_e32 v2, v237
	v_mfma_f32_32x32x16_bf16 v[142:157], v[218:221], v[4:7], v[66:81]
	v_exp_f32_e32 v82, v82
	v_exp_f32_e32 v83, v83
	v_exp_f32_e32 v84, v84
	v_add_f32_e32 v27, v82, v83
	v_exp_f32_e32 v85, v85
	v_mfma_f32_32x32x16_bf16 v[158:173], v[214:217], v[4:7], v[66:81]
	v_exp_f32_e32 v86, v86
	v_add_f32_e32 v27, v27, v84
	v_exp_f32_e32 v87, v87
	v_add_f32_e32 v27, v27, v85
	v_exp_f32_e32 v88, v88
	v_mfma_f32_32x32x16_bf16 v[142:157], v[210:213], v[8:11], v[142:157]
	v_add_f32_e32 v27, v27, v86
	v_exp_f32_e32 v89, v89
	v_add_f32_e32 v27, v27, v87
	v_add_f32_e32 v27, v27, v88
	v_add_f32_e32 v27, v27, v89
	v_mfma_f32_32x32x16_bf16 v[158:173], v[206:209], v[8:11], v[158:173]
	v_cvt_pk_bf16_f32 v82, v82, v83
	v_cvt_pk_bf16_f32 v83, v84, v85
	v_cvt_pk_bf16_f32 v84, v86, v87
	v_cvt_pk_bf16_f32 v85, v88, v89
	v_mfma_f32_32x32x16_bf16 v[142:157], v[202:205], v[12:15], v[142:157]
	v_exp_f32_e32 v90, v90
	v_exp_f32_e32 v91, v91
	v_exp_f32_e32 v92, v92
	v_add_f32_e32 v27, v27, v90
	v_exp_f32_e32 v93, v93
	v_mfma_f32_32x32x16_bf16 v[158:173], v[198:201], v[12:15], v[158:173]
	v_add_f32_e32 v27, v27, v91
	v_exp_f32_e32 v94, v94
	v_add_f32_e32 v27, v27, v92
	v_exp_f32_e32 v95, v95
	v_add_f32_e32 v27, v27, v93
	s_waitcnt lgkmcnt(0)
	s_waitcnt vmcnt(2)
	s_barrier
	v_mfma_f32_32x32x16_bf16 v[142:157], v[194:197], v[130:133], v[142:157]
	s_add_u32 m0, s57, 0x6000
	v_exp_f32_e32 v96, v96
	v_add_f32_e32 v27, v27, v94
	global_load_lds_dwordx4 v[28:29], off
	v_lshl_add_u64 v[28:29], v[28:29], 0, s[30:31]
	v_exp_f32_e32 v97, v97
	v_add_f32_e32 v27, v27, v95
	v_add_f32_e32 v27, v27, v96
	ds_read_b64_tr_b16 v[114:115], v2 offset:49152
	ds_read_b64_tr_b16 v[116:117], v2 offset:49664
	ds_read_b64_tr_b16 v[118:119], v2 offset:50176
	ds_read_b64_tr_b16 v[120:121], v2 offset:50688
	v_mfma_f32_32x32x16_bf16 v[158:173], v[190:193], v[130:133], v[158:173]
	s_add_u32 m0, s40, 0x0
	v_add_f32_e32 v27, v27, v97
	v_cvt_pk_bf16_f32 v90, v90, v91
	global_load_lds_dwordx4 v[24:25], off
	v_lshl_add_u64 v[24:25], v[24:25], 0, s[30:31]
	v_cvt_pk_bf16_f32 v91, v92, v93
	v_cvt_pk_bf16_f32 v92, v94, v95
	v_cvt_pk_bf16_f32 v93, v96, v97
	ds_read_b64_tr_b16 v[122:123], v2 offset:51200
	ds_read_b64_tr_b16 v[124:125], v2 offset:51712
	ds_read_b64_tr_b16 v[126:127], v2 offset:52224
	ds_read_b64_tr_b16 v[128:129], v2 offset:52736
	v_mfma_f32_32x32x16_bf16 v[142:157], v[186:189], v[134:137], v[142:157]
	s_add_u32 m0, s40, 0x3000
	v_exp_f32_e32 v98, v98
	v_exp_f32_e32 v99, v99
	global_load_lds_dwordx4 v[24:25], off
	v_lshl_add_u64 v[24:25], v[24:25], 0, s[30:31]
	v_exp_f32_e32 v100, v100
	v_add_f32_e32 v27, v27, v98
	v_exp_f32_e32 v101, v101
	ds_read_b64_tr_b16 v[240:241], v2 offset:53248
	ds_read_b64_tr_b16 v[242:243], v2 offset:53760
	ds_read_b64_tr_b16 v[244:245], v2 offset:54272
	ds_read_b64_tr_b16 v[246:247], v2 offset:54784
	v_mfma_f32_32x32x16_bf16 v[158:173], v[182:185], v[134:137], v[158:173]
	v_add_f32_e32 v27, v27, v99
	v_exp_f32_e32 v102, v102
	v_add_f32_e32 v27, v27, v100
	v_exp_f32_e32 v103, v103
	v_add_f32_e32 v27, v27, v101
	ds_read_b64_tr_b16 v[248:249], v2 offset:55296
	ds_read_b64_tr_b16 v[250:251], v2 offset:55808
	ds_read_b64_tr_b16 v[20:21], v2 offset:56320
	ds_read_b64_tr_b16 v[22:23], v2 offset:56832
	v_mfma_f32_32x32x16_bf16 v[142:157], v[178:181], v[138:141], v[142:157]
	v_exp_f32_e32 v104, v104
	v_add_f32_e32 v27, v27, v102
	v_exp_f32_e32 v105, v105
	v_add_f32_e32 v27, v27, v103
	v_add_f32_e32 v27, v27, v104
	v_mfma_f32_32x32x16_bf16 v[158:173], v[174:177], v[138:141], v[158:173]
	v_add_f32_e32 v27, v27, v105
	v_cvt_pk_bf16_f32 v98, v98, v99
	v_cvt_pk_bf16_f32 v99, v100, v101
	v_cvt_pk_bf16_f32 v100, v102, v103
	v_cvt_pk_bf16_f32 v101, v104, v105
	s_waitcnt lgkmcnt(0)
	v_add_u32_e32 v2, 0x6000, v238
	v_mfma_f32_32x32x16_bf16 v[34:49], v[82:85], v[114:117], v[34:49]
	v_exp_f32_e32 v106, v106
	v_exp_f32_e32 v107, v107
	v_exp_f32_e32 v108, v108
	v_add_f32_e32 v27, v27, v106
	v_exp_f32_e32 v109, v109
	ds_read_b128 v[218:221], v2
	ds_read_b128 v[214:217], v2 offset:512
	ds_read_b128 v[210:213], v2 offset:2048
	v_mfma_f32_32x32x16_bf16 v[50:65], v[82:85], v[240:243], v[50:65]
	v_add_f32_e32 v27, v27, v107
	v_exp_f32_e32 v110, v110
	v_add_f32_e32 v27, v27, v108
	v_exp_f32_e32 v111, v111
	v_add_f32_e32 v27, v27, v109
	ds_read_b128 v[206:209], v2 offset:2560
	ds_read_b128 v[202:205], v2 offset:4096
	ds_read_b128 v[198:201], v2 offset:4608
	v_mfma_f32_32x32x16_bf16 v[34:49], v[90:93], v[118:121], v[34:49]
	v_exp_f32_e32 v112, v112
	v_add_f32_e32 v27, v27, v110
	v_exp_f32_e32 v113, v113
	v_add_f32_e32 v27, v27, v111
	v_add_f32_e32 v27, v27, v112
	ds_read_b128 v[194:197], v2 offset:6144
	ds_read_b128 v[190:193], v2 offset:6656
	ds_read_b128 v[186:189], v2 offset:8192
	v_mfma_f32_32x32x16_bf16 v[50:65], v[90:93], v[244:247], v[50:65]
	v_add_f32_e32 v27, v27, v113
	v_cvt_pk_bf16_f32 v106, v106, v107
	v_cvt_pk_bf16_f32 v107, v108, v109
	v_cvt_pk_bf16_f32 v108, v110, v111
	v_cvt_pk_bf16_f32 v109, v112, v113
	v_add_f32_e32 v236, v236, v27
	ds_read_b128 v[182:185], v2 offset:8704
	ds_read_b128 v[178:181], v2 offset:10240
	ds_read_b128 v[174:177], v2 offset:10752
	v_mfma_f32_32x32x16_bf16 v[34:49], v[98:101], v[122:125], v[34:49]
	v_max3_f32 v19, v142, v143, v144
	v_max3_f32 v26, v145, v146, v147
	v_max3_f32 v19, v19, v148, v149
	v_max3_f32 v26, v26, v150, v151
	v_mfma_f32_32x32x16_bf16 v[50:65], v[98:101], v[248:251], v[50:65]
	v_max3_f32 v19, v19, v152, v153
	v_max3_f32 v26, v26, v154, v155
	v_max3_f32 v19, v19, v156, v157
	v_max3_f32 v26, v26, v158, v159
	v_mfma_f32_32x32x16_bf16 v[34:49], v[106:109], v[126:129], v[34:49]
	v_max3_f32 v19, v19, v160, v161
	v_max3_f32 v26, v26, v162, v163
	v_max3_f32 v19, v19, v164, v165
	v_max3_f32 v26, v26, v166, v167
	v_mfma_f32_32x32x16_bf16 v[50:65], v[106:109], v[20:23], v[50:65]
	v_max3_f32 v19, v19, v168, v169
	v_max3_f32 v26, v26, v170, v171
	v_max3_f32 v19, v19, v172, v173
	v_max_f32_e32 v19, v19, v26
	v_cmp_lt_f32_e32 vcc, s41, v19
	s_cbranch_vccz .Lmy_nors_31
	s_nop 15
	s_nop 15
	v_mov_b32_e32 v26, v19
	s_nop 1
	v_permlane32_swap_b32_e32 v19, v26
	v_max_f32_e32 v19, v19, v26
	v_max_f32_e32 v19, v19, v19
	v_max_f32_e32 v90, 0, v19
	v_exp_f32_e64 v91, -v90
	v_add_f32_e32 v239, v239, v90
	v_xor_b32_e32 v66, 0x80000000, v239
	v_mov_b32_e32 v67, v66
	v_mov_b32_e32 v68, v66
	v_mov_b32_e32 v69, v66
	v_mov_b32_e32 v70, v66
	v_mov_b32_e32 v71, v66
	v_mov_b32_e32 v72, v66
	v_mov_b32_e32 v73, v66
	v_mov_b32_e32 v74, v66
	v_mov_b32_e32 v75, v66
	v_mov_b32_e32 v76, v66
	v_mov_b32_e32 v77, v66
	v_mov_b32_e32 v78, v66
	v_mov_b32_e32 v79, v66
	v_mov_b32_e32 v80, v66
	v_mov_b32_e32 v81, v66
	v_sub_f32_e32 v142, v142, v90
	v_sub_f32_e32 v143, v143, v90
	v_sub_f32_e32 v144, v144, v90
	v_sub_f32_e32 v145, v145, v90
	v_sub_f32_e32 v146, v146, v90
	v_sub_f32_e32 v147, v147, v90
	v_sub_f32_e32 v148, v148, v90
	v_sub_f32_e32 v149, v149, v90
	v_sub_f32_e32 v150, v150, v90
	v_sub_f32_e32 v151, v151, v90
	v_sub_f32_e32 v152, v152, v90
	v_sub_f32_e32 v153, v153, v90
	v_sub_f32_e32 v154, v154, v90
	v_sub_f32_e32 v155, v155, v90
	v_sub_f32_e32 v156, v156, v90
	v_sub_f32_e32 v157, v157, v90
	v_sub_f32_e32 v158, v158, v90
	v_sub_f32_e32 v159, v159, v90
	v_sub_f32_e32 v160, v160, v90
	v_sub_f32_e32 v161, v161, v90
	v_sub_f32_e32 v162, v162, v90
	v_sub_f32_e32 v163, v163, v90
	v_sub_f32_e32 v164, v164, v90
	v_sub_f32_e32 v165, v165, v90
	v_sub_f32_e32 v166, v166, v90
	v_sub_f32_e32 v167, v167, v90
	v_sub_f32_e32 v168, v168, v90
	v_sub_f32_e32 v169, v169, v90
	v_sub_f32_e32 v170, v170, v90
	v_sub_f32_e32 v171, v171, v90
	v_sub_f32_e32 v172, v172, v90
	v_sub_f32_e32 v173, v173, v90
	v_mul_f32_e32 v236, v236, v91
	s_mov_b64 s[96:97], exec
	s_and_b64 exec, exec, s[8:9]
	ds_write_b32 v235, v91
	s_mov_b64 exec, s[96:97]
	v_lshl_add_u32 v2, v228, 4, s47
	ds_read_b128 v[94:97], v2 offset:0
	s_waitcnt lgkmcnt(0)
	v_mul_f32_e32 v34, v34, v94
	v_mul_f32_e32 v50, v50, v94
	v_mul_f32_e32 v35, v35, v95
	v_mul_f32_e32 v51, v51, v95
	v_mul_f32_e32 v36, v36, v96
	v_mul_f32_e32 v52, v52, v96
	v_mul_f32_e32 v37, v37, v97
	v_mul_f32_e32 v53, v53, v97
	ds_read_b128 v[94:97], v2 offset:32
	s_waitcnt lgkmcnt(0)
	v_mul_f32_e32 v38, v38, v94
	v_mul_f32_e32 v54, v54, v94
	v_mul_f32_e32 v39, v39, v95
	v_mul_f32_e32 v55, v55, v95
	v_mul_f32_e32 v40, v40, v96
	v_mul_f32_e32 v56, v56, v96
	v_mul_f32_e32 v41, v41, v97
	v_mul_f32_e32 v57, v57, v97
	ds_read_b128 v[94:97], v2 offset:64
	s_waitcnt lgkmcnt(0)
	v_mul_f32_e32 v42, v42, v94
	v_mul_f32_e32 v58, v58, v94
	v_mul_f32_e32 v43, v43, v95
	v_mul_f32_e32 v59, v59, v95
	v_mul_f32_e32 v44, v44, v96
	v_mul_f32_e32 v60, v60, v96
	v_mul_f32_e32 v45, v45, v97
	v_mul_f32_e32 v61, v61, v97
	ds_read_b128 v[94:97], v2 offset:96
	s_waitcnt lgkmcnt(0)
	v_mul_f32_e32 v46, v46, v94
	v_mul_f32_e32 v62, v62, v94
	v_mul_f32_e32 v47, v47, v95
	v_mul_f32_e32 v63, v63, v95
	v_mul_f32_e32 v48, v48, v96
	v_mul_f32_e32 v64, v64, v96
	v_mul_f32_e32 v49, v49, v97
	v_mul_f32_e32 v65, v65, v97
.Lmy_nors_31:
	s_waitcnt lgkmcnt(6)
	v_add_u32_e32 v2, 0x2000, v237
	v_mfma_f32_32x32x16_bf16 v[82:97], v[218:221], v[4:7], v[66:81]
	v_exp_f32_e32 v142, v142
	v_exp_f32_e32 v143, v143
	v_exp_f32_e32 v144, v144
	v_add_f32_e32 v27, v142, v143
	v_exp_f32_e32 v145, v145
	v_mfma_f32_32x32x16_bf16 v[98:113], v[214:217], v[4:7], v[66:81]
	v_exp_f32_e32 v146, v146
	v_add_f32_e32 v27, v27, v144
	v_exp_f32_e32 v147, v147
	v_add_f32_e32 v27, v27, v145
	v_exp_f32_e32 v148, v148
	v_mfma_f32_32x32x16_bf16 v[82:97], v[210:213], v[8:11], v[82:97]
	v_add_f32_e32 v27, v27, v146
	v_exp_f32_e32 v149, v149
	v_add_f32_e32 v27, v27, v147
	v_add_f32_e32 v27, v27, v148
	v_add_f32_e32 v27, v27, v149
	v_mfma_f32_32x32x16_bf16 v[98:113], v[206:209], v[8:11], v[98:113]
	v_cvt_pk_bf16_f32 v142, v142, v143
	v_cvt_pk_bf16_f32 v143, v144, v145
	v_cvt_pk_bf16_f32 v144, v146, v147
	v_cvt_pk_bf16_f32 v145, v148, v149
	v_mfma_f32_32x32x16_bf16 v[82:97], v[202:205], v[12:15], v[82:97]
	v_exp_f32_e32 v150, v150
	v_exp_f32_e32 v151, v151
	v_exp_f32_e32 v152, v152
	v_add_f32_e32 v27, v27, v150
	v_exp_f32_e32 v153, v153
	v_mfma_f32_32x32x16_bf16 v[98:113], v[198:201], v[12:15], v[98:113]
	v_add_f32_e32 v27, v27, v151
	v_exp_f32_e32 v154, v154
	v_add_f32_e32 v27, v27, v152
	v_exp_f32_e32 v155, v155
	v_add_f32_e32 v27, v27, v153
	s_waitcnt lgkmcnt(0)
	s_waitcnt vmcnt(3)
	s_barrier
	v_mfma_f32_32x32x16_bf16 v[82:97], v[194:197], v[130:133], v[82:97]
	s_add_u32 m0, s57, 0x0
	v_exp_f32_e32 v156, v156
	v_add_f32_e32 v27, v27, v154
	global_load_lds_dwordx4 v[28:29], off
	v_lshl_add_u64 v[28:29], v[28:29], 0, s[30:31]
	v_exp_f32_e32 v157, v157
	v_add_f32_e32 v27, v27, v155
	v_add_f32_e32 v27, v27, v156
	ds_read_b64_tr_b16 v[114:115], v2 offset:49152
	ds_read_b64_tr_b16 v[116:117], v2 offset:49664
	ds_read_b64_tr_b16 v[118:119], v2 offset:50176
	ds_read_b64_tr_b16 v[120:121], v2 offset:50688
	v_mfma_f32_32x32x16_bf16 v[98:113], v[190:193], v[130:133], v[98:113]
	s_add_u32 m0, s40, 0x6000
	v_add_f32_e32 v27, v27, v157
	v_cvt_pk_bf16_f32 v150, v150, v151
	global_load_lds_dwordx4 v[24:25], off
	v_lshl_add_u64 v[24:25], v[24:25], 0, s[30:31]
	v_cvt_pk_bf16_f32 v151, v152, v153
	v_cvt_pk_bf16_f32 v152, v154, v155
	v_cvt_pk_bf16_f32 v153, v156, v157
	ds_read_b64_tr_b16 v[122:123], v2 offset:51200
	ds_read_b64_tr_b16 v[124:125], v2 offset:51712
	ds_read_b64_tr_b16 v[126:127], v2 offset:52224
	ds_read_b64_tr_b16 v[128:129], v2 offset:52736
	v_mfma_f32_32x32x16_bf16 v[82:97], v[186:189], v[134:137], v[82:97]
	v_exp_f32_e32 v158, v158
	v_exp_f32_e32 v159, v159
	v_exp_f32_e32 v160, v160
	v_add_f32_e32 v27, v27, v158
	v_exp_f32_e32 v161, v161
	ds_read_b64_tr_b16 v[240:241], v2 offset:53248
	ds_read_b64_tr_b16 v[242:243], v2 offset:53760
	ds_read_b64_tr_b16 v[244:245], v2 offset:54272
	ds_read_b64_tr_b16 v[246:247], v2 offset:54784
	v_mfma_f32_32x32x16_bf16 v[98:113], v[182:185], v[134:137], v[98:113]
	v_add_f32_e32 v27, v27, v159
	v_exp_f32_e32 v162, v162
	v_add_f32_e32 v27, v27, v160
	v_exp_f32_e32 v163, v163
	v_add_f32_e32 v27, v27, v161
	ds_read_b64_tr_b16 v[248:249], v2 offset:55296
	ds_read_b64_tr_b16 v[250:251], v2 offset:55808
	ds_read_b64_tr_b16 v[20:21], v2 offset:56320
	ds_read_b64_tr_b16 v[22:23], v2 offset:56832
	v_mfma_f32_32x32x16_bf16 v[82:97], v[178:181], v[138:141], v[82:97]
	v_exp_f32_e32 v164, v164
	v_add_f32_e32 v27, v27, v162
	v_exp_f32_e32 v165, v165
	v_add_f32_e32 v27, v27, v163
	v_add_f32_e32 v27, v27, v164
	v_mfma_f32_32x32x16_bf16 v[98:113], v[174:177], v[138:141], v[98:113]
	v_add_f32_e32 v27, v27, v165
	v_cvt_pk_bf16_f32 v158, v158, v159
	v_cvt_pk_bf16_f32 v159, v160, v161
	v_cvt_pk_bf16_f32 v160, v162, v163
	v_cvt_pk_bf16_f32 v161, v164, v165
	s_waitcnt lgkmcnt(0)
	v_add_u32_e32 v2, 0x9000, v238
	v_mfma_f32_32x32x16_bf16 v[34:49], v[142:145], v[114:117], v[34:49]
	v_exp_f32_e32 v166, v166
	v_exp_f32_e32 v167, v167
	v_exp_f32_e32 v168, v168
	v_add_f32_e32 v27, v27, v166
	v_exp_f32_e32 v169, v169
	ds_read_b128 v[218:221], v2
	ds_read_b128 v[214:217], v2 offset:512
	ds_read_b128 v[210:213], v2 offset:2048
	v_mfma_f32_32x32x16_bf16 v[50:65], v[142:145], v[240:243], v[50:65]
	v_add_f32_e32 v27, v27, v167
	v_exp_f32_e32 v170, v170
	v_add_f32_e32 v27, v27, v168
	v_exp_f32_e32 v171, v171
	v_add_f32_e32 v27, v27, v169
	ds_read_b128 v[206:209], v2 offset:2560
	ds_read_b128 v[202:205], v2 offset:4096
	ds_read_b128 v[198:201], v2 offset:4608
	v_mfma_f32_32x32x16_bf16 v[34:49], v[150:153], v[118:121], v[34:49]
	v_exp_f32_e32 v172, v172
	v_add_f32_e32 v27, v27, v170
	v_exp_f32_e32 v173, v173
	v_add_f32_e32 v27, v27, v171
	v_add_f32_e32 v27, v27, v172
	ds_read_b128 v[194:197], v2 offset:6144
	ds_read_b128 v[190:193], v2 offset:6656
	ds_read_b128 v[186:189], v2 offset:8192
	v_mfma_f32_32x32x16_bf16 v[50:65], v[150:153], v[244:247], v[50:65]
	v_add_f32_e32 v27, v27, v173
	v_cvt_pk_bf16_f32 v166, v166, v167
	v_cvt_pk_bf16_f32 v167, v168, v169
	v_cvt_pk_bf16_f32 v168, v170, v171
	v_cvt_pk_bf16_f32 v169, v172, v173
	v_add_f32_e32 v236, v236, v27
	ds_read_b128 v[182:185], v2 offset:8704
	ds_read_b128 v[178:181], v2 offset:10240
	ds_read_b128 v[174:177], v2 offset:10752
	v_mfma_f32_32x32x16_bf16 v[34:49], v[158:161], v[122:125], v[34:49]
	v_max3_f32 v19, v82, v83, v84
	v_max3_f32 v26, v85, v86, v87
	v_max3_f32 v19, v19, v88, v89
	v_max3_f32 v26, v26, v90, v91
	v_mfma_f32_32x32x16_bf16 v[50:65], v[158:161], v[248:251], v[50:65]
	v_max3_f32 v19, v19, v92, v93
	v_max3_f32 v26, v26, v94, v95
	v_max3_f32 v19, v19, v96, v97
	v_max3_f32 v26, v26, v98, v99
	v_mfma_f32_32x32x16_bf16 v[34:49], v[166:169], v[126:129], v[34:49]
	v_max3_f32 v19, v19, v100, v101
	v_max3_f32 v26, v26, v102, v103
	v_max3_f32 v19, v19, v104, v105
	v_max3_f32 v26, v26, v106, v107
	v_mfma_f32_32x32x16_bf16 v[50:65], v[166:169], v[20:23], v[50:65]
	v_max3_f32 v19, v19, v108, v109
	v_max3_f32 v26, v26, v110, v111
	v_max3_f32 v19, v19, v112, v113
	v_max_f32_e32 v19, v19, v26
	v_cmp_lt_f32_e32 vcc, s41, v19
	s_cbranch_vccz .Lmy_nors_32
	s_nop 15
	s_nop 15
	v_mov_b32_e32 v26, v19
	s_nop 1
	v_permlane32_swap_b32_e32 v19, v26
	v_max_f32_e32 v19, v19, v26
	v_max_f32_e32 v19, v19, v19
	v_max_f32_e32 v150, 0, v19
	v_exp_f32_e64 v151, -v150
	v_add_f32_e32 v239, v239, v150
	v_xor_b32_e32 v66, 0x80000000, v239
	v_mov_b32_e32 v67, v66
	v_mov_b32_e32 v68, v66
	v_mov_b32_e32 v69, v66
	v_mov_b32_e32 v70, v66
	v_mov_b32_e32 v71, v66
	v_mov_b32_e32 v72, v66
	v_mov_b32_e32 v73, v66
	v_mov_b32_e32 v74, v66
	v_mov_b32_e32 v75, v66
	v_mov_b32_e32 v76, v66
	v_mov_b32_e32 v77, v66
	v_mov_b32_e32 v78, v66
	v_mov_b32_e32 v79, v66
	v_mov_b32_e32 v80, v66
	v_mov_b32_e32 v81, v66
	v_sub_f32_e32 v82, v82, v150
	v_sub_f32_e32 v83, v83, v150
	v_sub_f32_e32 v84, v84, v150
	v_sub_f32_e32 v85, v85, v150
	v_sub_f32_e32 v86, v86, v150
	v_sub_f32_e32 v87, v87, v150
	v_sub_f32_e32 v88, v88, v150
	v_sub_f32_e32 v89, v89, v150
	v_sub_f32_e32 v90, v90, v150
	v_sub_f32_e32 v91, v91, v150
	v_sub_f32_e32 v92, v92, v150
	v_sub_f32_e32 v93, v93, v150
	v_sub_f32_e32 v94, v94, v150
	v_sub_f32_e32 v95, v95, v150
	v_sub_f32_e32 v96, v96, v150
	v_sub_f32_e32 v97, v97, v150
	v_sub_f32_e32 v98, v98, v150
	v_sub_f32_e32 v99, v99, v150
	v_sub_f32_e32 v100, v100, v150
	v_sub_f32_e32 v101, v101, v150
	v_sub_f32_e32 v102, v102, v150
	v_sub_f32_e32 v103, v103, v150
	v_sub_f32_e32 v104, v104, v150
	v_sub_f32_e32 v105, v105, v150
	v_sub_f32_e32 v106, v106, v150
	v_sub_f32_e32 v107, v107, v150
	v_sub_f32_e32 v108, v108, v150
	v_sub_f32_e32 v109, v109, v150
	v_sub_f32_e32 v110, v110, v150
	v_sub_f32_e32 v111, v111, v150
	v_sub_f32_e32 v112, v112, v150
	v_sub_f32_e32 v113, v113, v150
	v_mul_f32_e32 v236, v236, v151
	s_mov_b64 s[96:97], exec
	s_and_b64 exec, exec, s[8:9]
	ds_write_b32 v235, v151
	s_mov_b64 exec, s[96:97]
	v_lshl_add_u32 v2, v228, 4, s47
	ds_read_b128 v[154:157], v2 offset:0
	s_waitcnt lgkmcnt(0)
	v_mul_f32_e32 v34, v34, v154
	v_mul_f32_e32 v50, v50, v154
	v_mul_f32_e32 v35, v35, v155
	v_mul_f32_e32 v51, v51, v155
	v_mul_f32_e32 v36, v36, v156
	v_mul_f32_e32 v52, v52, v156
	v_mul_f32_e32 v37, v37, v157
	v_mul_f32_e32 v53, v53, v157
	ds_read_b128 v[154:157], v2 offset:32
	s_waitcnt lgkmcnt(0)
	v_mul_f32_e32 v38, v38, v154
	v_mul_f32_e32 v54, v54, v154
	v_mul_f32_e32 v39, v39, v155
	v_mul_f32_e32 v55, v55, v155
	v_mul_f32_e32 v40, v40, v156
	v_mul_f32_e32 v56, v56, v156
	v_mul_f32_e32 v41, v41, v157
	v_mul_f32_e32 v57, v57, v157
	ds_read_b128 v[154:157], v2 offset:64
	s_waitcnt lgkmcnt(0)
	v_mul_f32_e32 v42, v42, v154
	v_mul_f32_e32 v58, v58, v154
	v_mul_f32_e32 v43, v43, v155
	v_mul_f32_e32 v59, v59, v155
	v_mul_f32_e32 v44, v44, v156
	v_mul_f32_e32 v60, v60, v156
	v_mul_f32_e32 v45, v45, v157
	v_mul_f32_e32 v61, v61, v157
	ds_read_b128 v[154:157], v2 offset:96
	s_waitcnt lgkmcnt(0)
	v_mul_f32_e32 v46, v46, v154
	v_mul_f32_e32 v62, v62, v154
	v_mul_f32_e32 v47, v47, v155
	v_mul_f32_e32 v63, v63, v155
	v_mul_f32_e32 v48, v48, v156
	v_mul_f32_e32 v64, v64, v156
	v_mul_f32_e32 v49, v49, v157
	v_mul_f32_e32 v65, v65, v157
.Lmy_nors_32:
	s_waitcnt lgkmcnt(6)
	v_add_u32_e32 v2, 0x4000, v237
	v_mfma_f32_32x32x16_bf16 v[142:157], v[218:221], v[4:7], v[66:81]
	v_exp_f32_e32 v82, v82
	v_exp_f32_e32 v83, v83
	v_exp_f32_e32 v84, v84
	v_add_f32_e32 v27, v82, v83
	v_exp_f32_e32 v85, v85
	v_mfma_f32_32x32x16_bf16 v[158:173], v[214:217], v[4:7], v[66:81]
	v_exp_f32_e32 v86, v86
	v_add_f32_e32 v27, v27, v84
	v_exp_f32_e32 v87, v87
	v_add_f32_e32 v27, v27, v85
	v_exp_f32_e32 v88, v88
	v_mfma_f32_32x32x16_bf16 v[142:157], v[210:213], v[8:11], v[142:157]
	v_add_f32_e32 v27, v27, v86
	v_exp_f32_e32 v89, v89
	v_add_f32_e32 v27, v27, v87
	v_add_f32_e32 v27, v27, v88
	v_add_f32_e32 v27, v27, v89
	v_mfma_f32_32x32x16_bf16 v[158:173], v[206:209], v[8:11], v[158:173]
	v_cvt_pk_bf16_f32 v82, v82, v83
	v_cvt_pk_bf16_f32 v83, v84, v85
	v_cvt_pk_bf16_f32 v84, v86, v87
	v_cvt_pk_bf16_f32 v85, v88, v89
	v_mfma_f32_32x32x16_bf16 v[142:157], v[202:205], v[12:15], v[142:157]
	v_exp_f32_e32 v90, v90
	v_exp_f32_e32 v91, v91
	v_exp_f32_e32 v92, v92
	v_add_f32_e32 v27, v27, v90
	v_exp_f32_e32 v93, v93
	v_mfma_f32_32x32x16_bf16 v[158:173], v[198:201], v[12:15], v[158:173]
	v_add_f32_e32 v27, v27, v91
	v_exp_f32_e32 v94, v94
	v_add_f32_e32 v27, v27, v92
	v_exp_f32_e32 v95, v95
	v_add_f32_e32 v27, v27, v93
	s_waitcnt lgkmcnt(0)
	s_waitcnt vmcnt(3)
	s_barrier
	v_mfma_f32_32x32x16_bf16 v[142:157], v[194:197], v[130:133], v[142:157]
	s_add_u32 m0, s57, 0x2000
	v_exp_f32_e32 v96, v96
	v_add_f32_e32 v27, v27, v94
	global_load_lds_dwordx4 v[28:29], off
	v_lshl_add_u64 v[28:29], v[28:29], 0, s[30:31]
	v_exp_f32_e32 v97, v97
	v_add_f32_e32 v27, v27, v95
	v_add_f32_e32 v27, v27, v96
	ds_read_b64_tr_b16 v[114:115], v2 offset:49152
	ds_read_b64_tr_b16 v[116:117], v2 offset:49664
	ds_read_b64_tr_b16 v[118:119], v2 offset:50176
	ds_read_b64_tr_b16 v[120:121], v2 offset:50688
	v_mfma_f32_32x32x16_bf16 v[158:173], v[190:193], v[130:133], v[158:173]
	s_add_u32 m0, s40, 0x9000
	v_add_f32_e32 v27, v27, v97
	v_cvt_pk_bf16_f32 v90, v90, v91
	global_load_lds_dwordx4 v[24:25], off
	v_lshl_add_u64 v[24:25], v[24:25], 0, s[30:31]
	v_cvt_pk_bf16_f32 v91, v92, v93
	v_cvt_pk_bf16_f32 v92, v94, v95
	v_cvt_pk_bf16_f32 v93, v96, v97
	ds_read_b64_tr_b16 v[122:123], v2 offset:51200
	ds_read_b64_tr_b16 v[124:125], v2 offset:51712
	ds_read_b64_tr_b16 v[126:127], v2 offset:52224
	ds_read_b64_tr_b16 v[128:129], v2 offset:52736
	v_mfma_f32_32x32x16_bf16 v[142:157], v[186:189], v[134:137], v[142:157]
	v_exp_f32_e32 v98, v98
	v_exp_f32_e32 v99, v99
	v_exp_f32_e32 v100, v100
	v_add_f32_e32 v27, v27, v98
	v_exp_f32_e32 v101, v101
	ds_read_b64_tr_b16 v[240:241], v2 offset:53248
	ds_read_b64_tr_b16 v[242:243], v2 offset:53760
	ds_read_b64_tr_b16 v[244:245], v2 offset:54272
	ds_read_b64_tr_b16 v[246:247], v2 offset:54784
	v_mfma_f32_32x32x16_bf16 v[158:173], v[182:185], v[134:137], v[158:173]
	v_add_f32_e32 v27, v27, v99
	v_exp_f32_e32 v102, v102
	v_add_f32_e32 v27, v27, v100
	v_exp_f32_e32 v103, v103
	v_add_f32_e32 v27, v27, v101
	ds_read_b64_tr_b16 v[248:249], v2 offset:55296
	ds_read_b64_tr_b16 v[250:251], v2 offset:55808
	ds_read_b64_tr_b16 v[20:21], v2 offset:56320
	ds_read_b64_tr_b16 v[22:23], v2 offset:56832
	v_mfma_f32_32x32x16_bf16 v[142:157], v[178:181], v[138:141], v[142:157]
	v_exp_f32_e32 v104, v104
	v_add_f32_e32 v27, v27, v102
	v_exp_f32_e32 v105, v105
	v_add_f32_e32 v27, v27, v103
	v_add_f32_e32 v27, v27, v104
	v_mfma_f32_32x32x16_bf16 v[158:173], v[174:177], v[138:141], v[158:173]
	v_add_f32_e32 v27, v27, v105
	v_cvt_pk_bf16_f32 v98, v98, v99
	v_cvt_pk_bf16_f32 v99, v100, v101
	v_cvt_pk_bf16_f32 v100, v102, v103
	v_cvt_pk_bf16_f32 v101, v104, v105
	s_waitcnt lgkmcnt(0)
	v_mov_b32_e32 v2, v238
	v_mfma_f32_32x32x16_bf16 v[34:49], v[82:85], v[114:117], v[34:49]
	v_exp_f32_e32 v106, v106
	v_exp_f32_e32 v107, v107
	v_exp_f32_e32 v108, v108
	v_add_f32_e32 v27, v27, v106
	v_exp_f32_e32 v109, v109
	ds_read_b128 v[218:221], v2
	ds_read_b128 v[214:217], v2 offset:512
	ds_read_b128 v[210:213], v2 offset:2048
	v_mfma_f32_32x32x16_bf16 v[50:65], v[82:85], v[240:243], v[50:65]
	v_add_f32_e32 v27, v27, v107
	v_exp_f32_e32 v110, v110
	v_add_f32_e32 v27, v27, v108
	v_exp_f32_e32 v111, v111
	v_add_f32_e32 v27, v27, v109
	ds_read_b128 v[206:209], v2 offset:2560
	ds_read_b128 v[202:205], v2 offset:4096
	ds_read_b128 v[198:201], v2 offset:4608
	v_mfma_f32_32x32x16_bf16 v[34:49], v[90:93], v[118:121], v[34:49]
	v_exp_f32_e32 v112, v112
	v_add_f32_e32 v27, v27, v110
	v_exp_f32_e32 v113, v113
	v_add_f32_e32 v27, v27, v111
	v_add_f32_e32 v27, v27, v112
	ds_read_b128 v[194:197], v2 offset:6144
	ds_read_b128 v[190:193], v2 offset:6656
	ds_read_b128 v[186:189], v2 offset:8192
	v_mfma_f32_32x32x16_bf16 v[50:65], v[90:93], v[244:247], v[50:65]
	v_add_f32_e32 v27, v27, v113
	v_cvt_pk_bf16_f32 v106, v106, v107
	v_cvt_pk_bf16_f32 v107, v108, v109
	v_cvt_pk_bf16_f32 v108, v110, v111
	v_cvt_pk_bf16_f32 v109, v112, v113
	v_add_f32_e32 v236, v236, v27
	ds_read_b128 v[182:185], v2 offset:8704
	ds_read_b128 v[178:181], v2 offset:10240
	ds_read_b128 v[174:177], v2 offset:10752
	v_mfma_f32_32x32x16_bf16 v[34:49], v[98:101], v[122:125], v[34:49]
	v_max3_f32 v19, v142, v143, v144
	v_max3_f32 v26, v145, v146, v147
	v_max3_f32 v19, v19, v148, v149
	v_max3_f32 v26, v26, v150, v151
	v_mfma_f32_32x32x16_bf16 v[50:65], v[98:101], v[248:251], v[50:65]
	v_max3_f32 v19, v19, v152, v153
	v_max3_f32 v26, v26, v154, v155
	v_max3_f32 v19, v19, v156, v157
	v_max3_f32 v26, v26, v158, v159
	v_mfma_f32_32x32x16_bf16 v[34:49], v[106:109], v[126:129], v[34:49]
	v_max3_f32 v19, v19, v160, v161
	v_max3_f32 v26, v26, v162, v163
	v_max3_f32 v19, v19, v164, v165
	v_max3_f32 v26, v26, v166, v167
	v_mfma_f32_32x32x16_bf16 v[50:65], v[106:109], v[20:23], v[50:65]
	v_max3_f32 v19, v19, v168, v169
	v_max3_f32 v26, v26, v170, v171
	v_max3_f32 v19, v19, v172, v173
	v_max_f32_e32 v19, v19, v26
	v_cmp_lt_f32_e32 vcc, s41, v19
	s_cbranch_vccz .Lmy_nors_33
	s_nop 15
	s_nop 15
	v_mov_b32_e32 v26, v19
	s_nop 1
	v_permlane32_swap_b32_e32 v19, v26
	v_max_f32_e32 v19, v19, v26
	v_max_f32_e32 v19, v19, v19
	v_max_f32_e32 v90, 0, v19
	v_exp_f32_e64 v91, -v90
	v_add_f32_e32 v239, v239, v90
	v_xor_b32_e32 v66, 0x80000000, v239
	v_mov_b32_e32 v67, v66
	v_mov_b32_e32 v68, v66
	v_mov_b32_e32 v69, v66
	v_mov_b32_e32 v70, v66
	v_mov_b32_e32 v71, v66
	v_mov_b32_e32 v72, v66
	v_mov_b32_e32 v73, v66
	v_mov_b32_e32 v74, v66
	v_mov_b32_e32 v75, v66
	v_mov_b32_e32 v76, v66
	v_mov_b32_e32 v77, v66
	v_mov_b32_e32 v78, v66
	v_mov_b32_e32 v79, v66
	v_mov_b32_e32 v80, v66
	v_mov_b32_e32 v81, v66
	v_sub_f32_e32 v142, v142, v90
	v_sub_f32_e32 v143, v143, v90
	v_sub_f32_e32 v144, v144, v90
	v_sub_f32_e32 v145, v145, v90
	v_sub_f32_e32 v146, v146, v90
	v_sub_f32_e32 v147, v147, v90
	v_sub_f32_e32 v148, v148, v90
	v_sub_f32_e32 v149, v149, v90
	v_sub_f32_e32 v150, v150, v90
	v_sub_f32_e32 v151, v151, v90
	v_sub_f32_e32 v152, v152, v90
	v_sub_f32_e32 v153, v153, v90
	v_sub_f32_e32 v154, v154, v90
	v_sub_f32_e32 v155, v155, v90
	v_sub_f32_e32 v156, v156, v90
	v_sub_f32_e32 v157, v157, v90
	v_sub_f32_e32 v158, v158, v90
	v_sub_f32_e32 v159, v159, v90
	v_sub_f32_e32 v160, v160, v90
	v_sub_f32_e32 v161, v161, v90
	v_sub_f32_e32 v162, v162, v90
	v_sub_f32_e32 v163, v163, v90
	v_sub_f32_e32 v164, v164, v90
	v_sub_f32_e32 v165, v165, v90
	v_sub_f32_e32 v166, v166, v90
	v_sub_f32_e32 v167, v167, v90
	v_sub_f32_e32 v168, v168, v90
	v_sub_f32_e32 v169, v169, v90
	v_sub_f32_e32 v170, v170, v90
	v_sub_f32_e32 v171, v171, v90
	v_sub_f32_e32 v172, v172, v90
	v_sub_f32_e32 v173, v173, v90
	v_mul_f32_e32 v236, v236, v91
	s_mov_b64 s[96:97], exec
	s_and_b64 exec, exec, s[8:9]
	ds_write_b32 v235, v91
	s_mov_b64 exec, s[96:97]
	v_lshl_add_u32 v2, v228, 4, s47
	ds_read_b128 v[94:97], v2 offset:0
	s_waitcnt lgkmcnt(0)
	v_mul_f32_e32 v34, v34, v94
	v_mul_f32_e32 v50, v50, v94
	v_mul_f32_e32 v35, v35, v95
	v_mul_f32_e32 v51, v51, v95
	v_mul_f32_e32 v36, v36, v96
	v_mul_f32_e32 v52, v52, v96
	v_mul_f32_e32 v37, v37, v97
	v_mul_f32_e32 v53, v53, v97
	ds_read_b128 v[94:97], v2 offset:32
	s_waitcnt lgkmcnt(0)
	v_mul_f32_e32 v38, v38, v94
	v_mul_f32_e32 v54, v54, v94
	v_mul_f32_e32 v39, v39, v95
	v_mul_f32_e32 v55, v55, v95
	v_mul_f32_e32 v40, v40, v96
	v_mul_f32_e32 v56, v56, v96
	v_mul_f32_e32 v41, v41, v97
	v_mul_f32_e32 v57, v57, v97
	ds_read_b128 v[94:97], v2 offset:64
	s_waitcnt lgkmcnt(0)
	v_mul_f32_e32 v42, v42, v94
	v_mul_f32_e32 v58, v58, v94
	v_mul_f32_e32 v43, v43, v95
	v_mul_f32_e32 v59, v59, v95
	v_mul_f32_e32 v44, v44, v96
	v_mul_f32_e32 v60, v60, v96
	v_mul_f32_e32 v45, v45, v97
	v_mul_f32_e32 v61, v61, v97
	ds_read_b128 v[94:97], v2 offset:96
	s_waitcnt lgkmcnt(0)
	v_mul_f32_e32 v46, v46, v94
	v_mul_f32_e32 v62, v62, v94
	v_mul_f32_e32 v47, v47, v95
	v_mul_f32_e32 v63, v63, v95
	v_mul_f32_e32 v48, v48, v96
	v_mul_f32_e32 v64, v64, v96
	v_mul_f32_e32 v49, v49, v97
	v_mul_f32_e32 v65, v65, v97
.Lmy_nors_33:
	s_waitcnt lgkmcnt(6)
	v_add_u32_e32 v2, 0x6000, v237
	v_mfma_f32_32x32x16_bf16 v[82:97], v[218:221], v[4:7], v[66:81]
	v_exp_f32_e32 v142, v142
	v_exp_f32_e32 v143, v143
	v_exp_f32_e32 v144, v144
	v_add_f32_e32 v27, v142, v143
	v_exp_f32_e32 v145, v145
	v_mfma_f32_32x32x16_bf16 v[98:113], v[214:217], v[4:7], v[66:81]
	v_exp_f32_e32 v146, v146
	v_add_f32_e32 v27, v27, v144
	v_exp_f32_e32 v147, v147
	v_add_f32_e32 v27, v27, v145
	v_exp_f32_e32 v148, v148
	v_mfma_f32_32x32x16_bf16 v[82:97], v[210:213], v[8:11], v[82:97]
	v_add_f32_e32 v27, v27, v146
	v_exp_f32_e32 v149, v149
	v_add_f32_e32 v27, v27, v147
	v_add_f32_e32 v27, v27, v148
	v_add_f32_e32 v27, v27, v149
	v_mfma_f32_32x32x16_bf16 v[98:113], v[206:209], v[8:11], v[98:113]
	v_cvt_pk_bf16_f32 v142, v142, v143
	v_cvt_pk_bf16_f32 v143, v144, v145
	v_cvt_pk_bf16_f32 v144, v146, v147
	v_cvt_pk_bf16_f32 v145, v148, v149
	v_mfma_f32_32x32x16_bf16 v[82:97], v[202:205], v[12:15], v[82:97]
	v_exp_f32_e32 v150, v150
	v_exp_f32_e32 v151, v151
	v_exp_f32_e32 v152, v152
	v_add_f32_e32 v27, v27, v150
	v_exp_f32_e32 v153, v153
	v_mfma_f32_32x32x16_bf16 v[98:113], v[198:201], v[12:15], v[98:113]
	v_add_f32_e32 v27, v27, v151
	v_exp_f32_e32 v154, v154
	v_add_f32_e32 v27, v27, v152
	v_exp_f32_e32 v155, v155
	v_add_f32_e32 v27, v27, v153
	s_waitcnt lgkmcnt(0)
	s_waitcnt vmcnt(4)
	s_barrier
	v_mfma_f32_32x32x16_bf16 v[82:97], v[194:197], v[130:133], v[82:97]
	s_add_u32 m0, s57, 0x4000
	v_exp_f32_e32 v156, v156
	v_add_f32_e32 v27, v27, v154
	global_load_lds_dwordx4 v[28:29], off
	v_lshl_add_u64 v[28:29], v[28:29], 0, s[30:31]
	v_exp_f32_e32 v157, v157
	v_add_f32_e32 v27, v27, v155
	v_add_f32_e32 v27, v27, v156
	ds_read_b64_tr_b16 v[114:115], v2 offset:49152
	ds_read_b64_tr_b16 v[116:117], v2 offset:49664
	ds_read_b64_tr_b16 v[118:119], v2 offset:50176
	ds_read_b64_tr_b16 v[120:121], v2 offset:50688
	v_mfma_f32_32x32x16_bf16 v[98:113], v[190:193], v[130:133], v[98:113]
	s_cmp_eq_u32 s79, 1
	s_cbranch_scc1 .Lmy_gl_34
	s_add_u32 m0, s40, 0x0
	s_nop 0
	global_load_lds_dwordx4 v[24:25], off
	v_lshl_add_u64 v[24:25], v[24:25], 0, s[30:31]

.Lmy_B_loop:
	s_waitcnt lgkmcnt(6)
	v_mov_b32_e32 v2, v237
	v_mfma_f32_32x32x16_bf16 v[142:157], v[218:221], v[4:7], v[66:81]
	v_exp_f32_e32 v82, v82
	v_exp_f32_e32 v83, v83
	v_exp_f32_e32 v84, v84
	v_add_f32_e32 v27, v82, v83
	v_exp_f32_e32 v85, v85
	v_mfma_f32_32x32x16_bf16 v[158:173], v[214:217], v[4:7], v[66:81]
	v_exp_f32_e32 v86, v86
	v_add_f32_e32 v27, v27, v84
	v_exp_f32_e32 v87, v87
	v_add_f32_e32 v27, v27, v85
	v_exp_f32_e32 v88, v88
	v_mfma_f32_32x32x16_bf16 v[142:157], v[210:213], v[8:11], v[142:157]
	v_add_f32_e32 v27, v27, v86
	v_exp_f32_e32 v89, v89
	v_add_f32_e32 v27, v27, v87
	v_add_f32_e32 v27, v27, v88
	v_add_f32_e32 v27, v27, v89
	v_mfma_f32_32x32x16_bf16 v[158:173], v[206:209], v[8:11], v[158:173]
	v_cvt_pk_bf16_f32 v82, v82, v83
	v_cvt_pk_bf16_f32 v83, v84, v85
	v_cvt_pk_bf16_f32 v84, v86, v87
	v_cvt_pk_bf16_f32 v85, v88, v89
	v_mfma_f32_32x32x16_bf16 v[142:157], v[202:205], v[12:15], v[142:157]
	v_exp_f32_e32 v90, v90
	v_exp_f32_e32 v91, v91
	v_exp_f32_e32 v92, v92
	v_add_f32_e32 v27, v27, v90
	v_exp_f32_e32 v93, v93
	v_mfma_f32_32x32x16_bf16 v[158:173], v[198:201], v[12:15], v[158:173]
	v_add_f32_e32 v27, v27, v91
	v_exp_f32_e32 v94, v94
	v_add_f32_e32 v27, v27, v92
	v_exp_f32_e32 v95, v95
	v_add_f32_e32 v27, v27, v93
	s_waitcnt lgkmcnt(0)
	s_waitcnt vmcnt(4)
	s_barrier
	v_mfma_f32_32x32x16_bf16 v[142:157], v[194:197], v[130:133], v[142:157]
	s_add_u32 m0, s57, 0x6000
	v_exp_f32_e32 v96, v96
	v_add_f32_e32 v27, v27, v94
	global_load_lds_dwordx4 v[28:29], off
	v_lshl_add_u64 v[28:29], v[28:29], 0, s[30:31]
	v_exp_f32_e32 v97, v97
	v_add_f32_e32 v27, v27, v95
	v_add_f32_e32 v27, v27, v96
	ds_read_b64_tr_b16 v[114:115], v2 offset:49152
	ds_read_b64_tr_b16 v[116:117], v2 offset:49664
	ds_read_b64_tr_b16 v[118:119], v2 offset:50176
	ds_read_b64_tr_b16 v[120:121], v2 offset:50688
	v_mfma_f32_32x32x16_bf16 v[158:173], v[190:193], v[130:133], v[158:173]
	s_add_u32 m0, s40, 0x3000
	v_add_f32_e32 v27, v27, v97
	v_cvt_pk_bf16_f32 v90, v90, v91
	global_load_lds_dwordx4 v[24:25], off
	v_lshl_add_u64 v[24:25], v[24:25], 0, s[30:31]
	v_cvt_pk_bf16_f32 v91, v92, v93
	v_cvt_pk_bf16_f32 v92, v94, v95
	v_cvt_pk_bf16_f32 v93, v96, v97
	ds_read_b64_tr_b16 v[122:123], v2 offset:51200
	ds_read_b64_tr_b16 v[124:125], v2 offset:51712
	ds_read_b64_tr_b16 v[126:127], v2 offset:52224
	ds_read_b64_tr_b16 v[128:129], v2 offset:52736
	v_mfma_f32_32x32x16_bf16 v[142:157], v[186:189], v[134:137], v[142:157]
	v_exp_f32_e32 v98, v98
	v_exp_f32_e32 v99, v99
	v_exp_f32_e32 v100, v100
	v_add_f32_e32 v27, v27, v98
	v_exp_f32_e32 v101, v101
	ds_read_b64_tr_b16 v[240:241], v2 offset:53248
	ds_read_b64_tr_b16 v[242:243], v2 offset:53760
	ds_read_b64_tr_b16 v[244:245], v2 offset:54272
	ds_read_b64_tr_b16 v[246:247], v2 offset:54784
	v_mfma_f32_32x32x16_bf16 v[158:173], v[182:185], v[134:137], v[158:173]
	v_add_f32_e32 v27, v27, v99
	v_exp_f32_e32 v102, v102
	v_add_f32_e32 v27, v27, v100
	v_exp_f32_e32 v103, v103
	v_add_f32_e32 v27, v27, v101
	ds_read_b64_tr_b16 v[248:249], v2 offset:55296
	ds_read_b64_tr_b16 v[250:251], v2 offset:55808
	ds_read_b64_tr_b16 v[20:21], v2 offset:56320
	ds_read_b64_tr_b16 v[22:23], v2 offset:56832
	v_mfma_f32_32x32x16_bf16 v[142:157], v[178:181], v[138:141], v[142:157]
	v_exp_f32_e32 v104, v104
	v_add_f32_e32 v27, v27, v102
	v_exp_f32_e32 v105, v105
	v_add_f32_e32 v27, v27, v103
	v_add_f32_e32 v27, v27, v104
	v_mfma_f32_32x32x16_bf16 v[158:173], v[174:177], v[138:141], v[158:173]
	v_add_f32_e32 v27, v27, v105
	v_cvt_pk_bf16_f32 v98, v98, v99
	v_cvt_pk_bf16_f32 v99, v100, v101
	v_cvt_pk_bf16_f32 v100, v102, v103
	v_cvt_pk_bf16_f32 v101, v104, v105
	s_waitcnt lgkmcnt(0)
	v_add_u32_e32 v2, 0x6000, v238
	v_mfma_f32_32x32x16_bf16 v[34:49], v[82:85], v[114:117], v[34:49]
	v_exp_f32_e32 v106, v106
	v_exp_f32_e32 v107, v107
	v_exp_f32_e32 v108, v108
	v_add_f32_e32 v27, v27, v106
	v_exp_f32_e32 v109, v109
	ds_read_b128 v[218:221], v2
	ds_read_b128 v[214:217], v2 offset:512
	ds_read_b128 v[210:213], v2 offset:2048
	v_mfma_f32_32x32x16_bf16 v[50:65], v[82:85], v[240:243], v[50:65]
	v_add_f32_e32 v27, v27, v107
	v_exp_f32_e32 v110, v110
	v_add_f32_e32 v27, v27, v108
	v_exp_f32_e32 v111, v111
	v_add_f32_e32 v27, v27, v109
	ds_read_b128 v[206:209], v2 offset:2560
	ds_read_b128 v[202:205], v2 offset:4096
	ds_read_b128 v[198:201], v2 offset:4608
	v_mfma_f32_32x32x16_bf16 v[34:49], v[90:93], v[118:121], v[34:49]
	v_exp_f32_e32 v112, v112
	v_add_f32_e32 v27, v27, v110
	v_exp_f32_e32 v113, v113
	v_add_f32_e32 v27, v27, v111
	v_add_f32_e32 v27, v27, v112
	ds_read_b128 v[194:197], v2 offset:6144
	ds_read_b128 v[190:193], v2 offset:6656
	ds_read_b128 v[186:189], v2 offset:8192
	v_mfma_f32_32x32x16_bf16 v[50:65], v[90:93], v[244:247], v[50:65]
	v_add_f32_e32 v27, v27, v113
	v_cvt_pk_bf16_f32 v106, v106, v107
	v_cvt_pk_bf16_f32 v107, v108, v109
	v_cvt_pk_bf16_f32 v108, v110, v111
	v_cvt_pk_bf16_f32 v109, v112, v113
	v_add_f32_e32 v236, v236, v27
	ds_read_b128 v[182:185], v2 offset:8704
	ds_read_b128 v[178:181], v2 offset:10240
	ds_read_b128 v[174:177], v2 offset:10752
	v_mfma_f32_32x32x16_bf16 v[34:49], v[98:101], v[122:125], v[34:49]
	v_max3_f32 v19, v142, v143, v144
	v_max3_f32 v26, v145, v146, v147
	v_max3_f32 v19, v19, v148, v149
	v_max3_f32 v26, v26, v150, v151
	v_mfma_f32_32x32x16_bf16 v[50:65], v[98:101], v[248:251], v[50:65]
	v_max3_f32 v19, v19, v152, v153
	v_max3_f32 v26, v26, v154, v155
	v_max3_f32 v19, v19, v156, v157
	v_max3_f32 v26, v26, v158, v159
	v_mfma_f32_32x32x16_bf16 v[34:49], v[106:109], v[126:129], v[34:49]
	v_max3_f32 v19, v19, v160, v161
	v_max3_f32 v26, v26, v162, v163
	v_max3_f32 v19, v19, v164, v165
	v_max3_f32 v26, v26, v166, v167
	v_mfma_f32_32x32x16_bf16 v[50:65], v[106:109], v[20:23], v[50:65]
	v_max3_f32 v19, v19, v168, v169
	v_max3_f32 v26, v26, v170, v171
	v_max3_f32 v19, v19, v172, v173
	v_max_f32_e32 v19, v19, v26
	v_cmp_lt_f32_e32 vcc, s41, v19
	s_cbranch_vccz .Lmy_nors_36
	s_nop 15
	s_nop 15
	v_mov_b32_e32 v26, v19
	s_nop 1
	v_permlane32_swap_b32_e32 v19, v26
	v_max_f32_e32 v19, v19, v26
	v_max_f32_e32 v19, v19, v19
	v_max_f32_e32 v90, 0, v19
	v_exp_f32_e64 v91, -v90
	v_add_f32_e32 v239, v239, v90
	v_xor_b32_e32 v66, 0x80000000, v239
	v_mov_b32_e32 v67, v66
	v_mov_b32_e32 v68, v66
	v_mov_b32_e32 v69, v66
	v_mov_b32_e32 v70, v66
	v_mov_b32_e32 v71, v66
	v_mov_b32_e32 v72, v66
	v_mov_b32_e32 v73, v66
	v_mov_b32_e32 v74, v66
	v_mov_b32_e32 v75, v66
	v_mov_b32_e32 v76, v66
	v_mov_b32_e32 v77, v66
	v_mov_b32_e32 v78, v66
	v_mov_b32_e32 v79, v66
	v_mov_b32_e32 v80, v66
	v_mov_b32_e32 v81, v66
	v_sub_f32_e32 v142, v142, v90
	v_sub_f32_e32 v143, v143, v90
	v_sub_f32_e32 v144, v144, v90
	v_sub_f32_e32 v145, v145, v90
	v_sub_f32_e32 v146, v146, v90
	v_sub_f32_e32 v147, v147, v90
	v_sub_f32_e32 v148, v148, v90
	v_sub_f32_e32 v149, v149, v90
	v_sub_f32_e32 v150, v150, v90
	v_sub_f32_e32 v151, v151, v90
	v_sub_f32_e32 v152, v152, v90
	v_sub_f32_e32 v153, v153, v90
	v_sub_f32_e32 v154, v154, v90
	v_sub_f32_e32 v155, v155, v90
	v_sub_f32_e32 v156, v156, v90
	v_sub_f32_e32 v157, v157, v90
	v_sub_f32_e32 v158, v158, v90
	v_sub_f32_e32 v159, v159, v90
	v_sub_f32_e32 v160, v160, v90
	v_sub_f32_e32 v161, v161, v90
	v_sub_f32_e32 v162, v162, v90
	v_sub_f32_e32 v163, v163, v90
	v_sub_f32_e32 v164, v164, v90
	v_sub_f32_e32 v165, v165, v90
	v_sub_f32_e32 v166, v166, v90
	v_sub_f32_e32 v167, v167, v90
	v_sub_f32_e32 v168, v168, v90
	v_sub_f32_e32 v169, v169, v90
	v_sub_f32_e32 v170, v170, v90
	v_sub_f32_e32 v171, v171, v90
	v_sub_f32_e32 v172, v172, v90
	v_sub_f32_e32 v173, v173, v90
	v_mul_f32_e32 v236, v236, v91
	s_mov_b64 s[96:97], exec
	s_and_b64 exec, exec, s[8:9]
	ds_write_b32 v235, v91
	s_mov_b64 exec, s[96:97]
	v_lshl_add_u32 v2, v228, 4, s47
	ds_read_b128 v[94:97], v2 offset:0
	s_waitcnt lgkmcnt(0)
	v_mul_f32_e32 v34, v34, v94
	v_mul_f32_e32 v50, v50, v94
	v_mul_f32_e32 v35, v35, v95
	v_mul_f32_e32 v51, v51, v95
	v_mul_f32_e32 v36, v36, v96
	v_mul_f32_e32 v52, v52, v96
	v_mul_f32_e32 v37, v37, v97
	v_mul_f32_e32 v53, v53, v97
	ds_read_b128 v[94:97], v2 offset:32
	s_waitcnt lgkmcnt(0)
	v_mul_f32_e32 v38, v38, v94
	v_mul_f32_e32 v54, v54, v94
	v_mul_f32_e32 v39, v39, v95
	v_mul_f32_e32 v55, v55, v95
	v_mul_f32_e32 v40, v40, v96
	v_mul_f32_e32 v56, v56, v96
	v_mul_f32_e32 v41, v41, v97
	v_mul_f32_e32 v57, v57, v97
	ds_read_b128 v[94:97], v2 offset:64
	s_waitcnt lgkmcnt(0)
	v_mul_f32_e32 v42, v42, v94
	v_mul_f32_e32 v58, v58, v94
	v_mul_f32_e32 v43, v43, v95
	v_mul_f32_e32 v59, v59, v95
	v_mul_f32_e32 v44, v44, v96
	v_mul_f32_e32 v60, v60, v96
	v_mul_f32_e32 v45, v45, v97
	v_mul_f32_e32 v61, v61, v97
	ds_read_b128 v[94:97], v2 offset:96
	s_waitcnt lgkmcnt(0)
	v_mul_f32_e32 v46, v46, v94
	v_mul_f32_e32 v62, v62, v94
	v_mul_f32_e32 v47, v47, v95
	v_mul_f32_e32 v63, v63, v95
	v_mul_f32_e32 v48, v48, v96
	v_mul_f32_e32 v64, v64, v96
	v_mul_f32_e32 v49, v49, v97
	v_mul_f32_e32 v65, v65, v97
.Lmy_nors_36:
	s_waitcnt lgkmcnt(6)
	v_add_u32_e32 v2, 0x2000, v237
	v_mfma_f32_32x32x16_bf16 v[82:97], v[218:221], v[4:7], v[66:81]
	v_exp_f32_e32 v142, v142
	v_exp_f32_e32 v143, v143
	v_exp_f32_e32 v144, v144
	v_add_f32_e32 v27, v142, v143
	v_exp_f32_e32 v145, v145
	v_mfma_f32_32x32x16_bf16 v[98:113], v[214:217], v[4:7], v[66:81]
	v_exp_f32_e32 v146, v146
	v_add_f32_e32 v27, v27, v144
	v_exp_f32_e32 v147, v147
	v_add_f32_e32 v27, v27, v145
	v_exp_f32_e32 v148, v148
	v_mfma_f32_32x32x16_bf16 v[82:97], v[210:213], v[8:11], v[82:97]
	v_add_f32_e32 v27, v27, v146
	v_exp_f32_e32 v149, v149
	v_add_f32_e32 v27, v27, v147
	v_add_f32_e32 v27, v27, v148
	v_add_f32_e32 v27, v27, v149
	v_mfma_f32_32x32x16_bf16 v[98:113], v[206:209], v[8:11], v[98:113]
	v_cvt_pk_bf16_f32 v142, v142, v143
	v_cvt_pk_bf16_f32 v143, v144, v145
	v_cvt_pk_bf16_f32 v144, v146, v147
	v_cvt_pk_bf16_f32 v145, v148, v149
	v_mfma_f32_32x32x16_bf16 v[82:97], v[202:205], v[12:15], v[82:97]
	v_exp_f32_e32 v150, v150
	v_exp_f32_e32 v151, v151
	v_exp_f32_e32 v152, v152
	v_add_f32_e32 v27, v27, v150
	v_exp_f32_e32 v153, v153
	v_mfma_f32_32x32x16_bf16 v[98:113], v[198:201], v[12:15], v[98:113]
	v_add_f32_e32 v27, v27, v151
	v_exp_f32_e32 v154, v154
	v_add_f32_e32 v27, v27, v152
	v_exp_f32_e32 v155, v155
	v_add_f32_e32 v27, v27, v153
	s_waitcnt lgkmcnt(0)
	s_waitcnt vmcnt(4)
	s_barrier
	v_mfma_f32_32x32x16_bf16 v[82:97], v[194:197], v[130:133], v[82:97]
	s_add_u32 m0, s57, 0x0
	v_exp_f32_e32 v156, v156
	v_add_f32_e32 v27, v27, v154
	global_load_lds_dwordx4 v[28:29], off
	v_lshl_add_u64 v[28:29], v[28:29], 0, s[30:31]
	v_exp_f32_e32 v157, v157
	v_add_f32_e32 v27, v27, v155
	v_add_f32_e32 v27, v27, v156
	ds_read_b64_tr_b16 v[114:115], v2 offset:49152
	ds_read_b64_tr_b16 v[116:117], v2 offset:49664
	ds_read_b64_tr_b16 v[118:119], v2 offset:50176
	ds_read_b64_tr_b16 v[120:121], v2 offset:50688
	v_mfma_f32_32x32x16_bf16 v[98:113], v[190:193], v[130:133], v[98:113]
	s_add_u32 m0, s40, 0x6000
	v_add_f32_e32 v27, v27, v157
	v_cvt_pk_bf16_f32 v150, v150, v151
	global_load_lds_dwordx4 v[24:25], off
	v_lshl_add_u64 v[24:25], v[24:25], 0, s[30:31]
	v_cvt_pk_bf16_f32 v151, v152, v153
	v_cvt_pk_bf16_f32 v152, v154, v155
	v_cvt_pk_bf16_f32 v153, v156, v157
	ds_read_b64_tr_b16 v[122:123], v2 offset:51200
	ds_read_b64_tr_b16 v[124:125], v2 offset:51712
	ds_read_b64_tr_b16 v[126:127], v2 offset:52224
	ds_read_b64_tr_b16 v[128:129], v2 offset:52736
	v_mfma_f32_32x32x16_bf16 v[82:97], v[186:189], v[134:137], v[82:97]
	v_exp_f32_e32 v158, v158
	v_exp_f32_e32 v159, v159
	v_exp_f32_e32 v160, v160
	v_add_f32_e32 v27, v27, v158
	v_exp_f32_e32 v161, v161
	ds_read_b64_tr_b16 v[240:241], v2 offset:53248
	ds_read_b64_tr_b16 v[242:243], v2 offset:53760
	ds_read_b64_tr_b16 v[244:245], v2 offset:54272
	ds_read_b64_tr_b16 v[246:247], v2 offset:54784
	v_mfma_f32_32x32x16_bf16 v[98:113], v[182:185], v[134:137], v[98:113]
	v_add_f32_e32 v27, v27, v159
	v_exp_f32_e32 v162, v162
	v_add_f32_e32 v27, v27, v160
	v_exp_f32_e32 v163, v163
	v_add_f32_e32 v27, v27, v161
	ds_read_b64_tr_b16 v[248:249], v2 offset:55296
	ds_read_b64_tr_b16 v[250:251], v2 offset:55808
	ds_read_b64_tr_b16 v[20:21], v2 offset:56320
	ds_read_b64_tr_b16 v[22:23], v2 offset:56832
	v_mfma_f32_32x32x16_bf16 v[82:97], v[178:181], v[138:141], v[82:97]
	v_exp_f32_e32 v164, v164
	v_add_f32_e32 v27, v27, v162
	v_exp_f32_e32 v165, v165
	v_add_f32_e32 v27, v27, v163
	v_add_f32_e32 v27, v27, v164
	v_mfma_f32_32x32x16_bf16 v[98:113], v[174:177], v[138:141], v[98:113]
	v_add_f32_e32 v27, v27, v165
	v_cvt_pk_bf16_f32 v158, v158, v159
	v_cvt_pk_bf16_f32 v159, v160, v161
	v_cvt_pk_bf16_f32 v160, v162, v163
	v_cvt_pk_bf16_f32 v161, v164, v165
	s_waitcnt lgkmcnt(0)
	v_add_u32_e32 v2, 0x9000, v238
	v_mfma_f32_32x32x16_bf16 v[34:49], v[142:145], v[114:117], v[34:49]
	v_exp_f32_e32 v166, v166
	v_exp_f32_e32 v167, v167
	v_exp_f32_e32 v168, v168
	v_add_f32_e32 v27, v27, v166
	v_exp_f32_e32 v169, v169
	ds_read_b128 v[218:221], v2
	ds_read_b128 v[214:217], v2 offset:512
	ds_read_b128 v[210:213], v2 offset:2048
	v_mfma_f32_32x32x16_bf16 v[50:65], v[142:145], v[240:243], v[50:65]
	v_add_f32_e32 v27, v27, v167
	v_exp_f32_e32 v170, v170
	v_add_f32_e32 v27, v27, v168
	v_exp_f32_e32 v171, v171
	v_add_f32_e32 v27, v27, v169
	ds_read_b128 v[206:209], v2 offset:2560
	ds_read_b128 v[202:205], v2 offset:4096
	ds_read_b128 v[198:201], v2 offset:4608
	v_mfma_f32_32x32x16_bf16 v[34:49], v[150:153], v[118:121], v[34:49]
	v_exp_f32_e32 v172, v172
	v_add_f32_e32 v27, v27, v170
	v_exp_f32_e32 v173, v173
	v_add_f32_e32 v27, v27, v171
	v_add_f32_e32 v27, v27, v172
	ds_read_b128 v[194:197], v2 offset:6144
	ds_read_b128 v[190:193], v2 offset:6656
	ds_read_b128 v[186:189], v2 offset:8192
	v_mfma_f32_32x32x16_bf16 v[50:65], v[150:153], v[244:247], v[50:65]
	v_add_f32_e32 v27, v27, v173
	v_cvt_pk_bf16_f32 v166, v166, v167
	v_cvt_pk_bf16_f32 v167, v168, v169
	v_cvt_pk_bf16_f32 v168, v170, v171
	v_cvt_pk_bf16_f32 v169, v172, v173
	v_add_f32_e32 v236, v236, v27
	ds_read_b128 v[182:185], v2 offset:8704
	ds_read_b128 v[178:181], v2 offset:10240
	ds_read_b128 v[174:177], v2 offset:10752
	v_mfma_f32_32x32x16_bf16 v[34:49], v[158:161], v[122:125], v[34:49]
	v_max3_f32 v19, v82, v83, v84
	v_max3_f32 v26, v85, v86, v87
	v_max3_f32 v19, v19, v88, v89
	v_max3_f32 v26, v26, v90, v91
	v_mfma_f32_32x32x16_bf16 v[50:65], v[158:161], v[248:251], v[50:65]
	v_max3_f32 v19, v19, v92, v93
	v_max3_f32 v26, v26, v94, v95
	v_max3_f32 v19, v19, v96, v97
	v_max3_f32 v26, v26, v98, v99
	v_mfma_f32_32x32x16_bf16 v[34:49], v[166:169], v[126:129], v[34:49]
	v_max3_f32 v19, v19, v100, v101
	v_max3_f32 v26, v26, v102, v103
	v_max3_f32 v19, v19, v104, v105
	v_max3_f32 v26, v26, v106, v107
	v_mfma_f32_32x32x16_bf16 v[50:65], v[166:169], v[20:23], v[50:65]
	v_max3_f32 v19, v19, v108, v109
	v_max3_f32 v26, v26, v110, v111
	v_max3_f32 v19, v19, v112, v113
	v_max_f32_e32 v19, v19, v26
	v_cmp_lt_f32_e32 vcc, s41, v19
	s_cbranch_vccz .Lmy_nors_37
	s_nop 15
	s_nop 15
	v_mov_b32_e32 v26, v19
	s_nop 1
	v_permlane32_swap_b32_e32 v19, v26
	v_max_f32_e32 v19, v19, v26
	v_max_f32_e32 v19, v19, v19
	v_max_f32_e32 v150, 0, v19
	v_exp_f32_e64 v151, -v150
	v_add_f32_e32 v239, v239, v150
	v_xor_b32_e32 v66, 0x80000000, v239
	v_mov_b32_e32 v67, v66
	v_mov_b32_e32 v68, v66
	v_mov_b32_e32 v69, v66
	v_mov_b32_e32 v70, v66
	v_mov_b32_e32 v71, v66
	v_mov_b32_e32 v72, v66
	v_mov_b32_e32 v73, v66
	v_mov_b32_e32 v74, v66
	v_mov_b32_e32 v75, v66
	v_mov_b32_e32 v76, v66
	v_mov_b32_e32 v77, v66
	v_mov_b32_e32 v78, v66
	v_mov_b32_e32 v79, v66
	v_mov_b32_e32 v80, v66
	v_mov_b32_e32 v81, v66
	v_sub_f32_e32 v82, v82, v150
	v_sub_f32_e32 v83, v83, v150
	v_sub_f32_e32 v84, v84, v150
	v_sub_f32_e32 v85, v85, v150
	v_sub_f32_e32 v86, v86, v150
	v_sub_f32_e32 v87, v87, v150
	v_sub_f32_e32 v88, v88, v150
	v_sub_f32_e32 v89, v89, v150
	v_sub_f32_e32 v90, v90, v150
	v_sub_f32_e32 v91, v91, v150
	v_sub_f32_e32 v92, v92, v150
	v_sub_f32_e32 v93, v93, v150
	v_sub_f32_e32 v94, v94, v150
	v_sub_f32_e32 v95, v95, v150
	v_sub_f32_e32 v96, v96, v150
	v_sub_f32_e32 v97, v97, v150
	v_sub_f32_e32 v98, v98, v150
	v_sub_f32_e32 v99, v99, v150
	v_sub_f32_e32 v100, v100, v150
	v_sub_f32_e32 v101, v101, v150
	v_sub_f32_e32 v102, v102, v150
	v_sub_f32_e32 v103, v103, v150
	v_sub_f32_e32 v104, v104, v150
	v_sub_f32_e32 v105, v105, v150
	v_sub_f32_e32 v106, v106, v150
	v_sub_f32_e32 v107, v107, v150
	v_sub_f32_e32 v108, v108, v150
	v_sub_f32_e32 v109, v109, v150
	v_sub_f32_e32 v110, v110, v150
	v_sub_f32_e32 v111, v111, v150
	v_sub_f32_e32 v112, v112, v150
	v_sub_f32_e32 v113, v113, v150
	v_mul_f32_e32 v236, v236, v151
	s_mov_b64 s[96:97], exec
	s_and_b64 exec, exec, s[8:9]
	ds_write_b32 v235, v151
	s_mov_b64 exec, s[96:97]
	v_lshl_add_u32 v2, v228, 4, s47
	ds_read_b128 v[154:157], v2 offset:0
	s_waitcnt lgkmcnt(0)
	v_mul_f32_e32 v34, v34, v154
	v_mul_f32_e32 v50, v50, v154
	v_mul_f32_e32 v35, v35, v155
	v_mul_f32_e32 v51, v51, v155
	v_mul_f32_e32 v36, v36, v156
	v_mul_f32_e32 v52, v52, v156
	v_mul_f32_e32 v37, v37, v157
	v_mul_f32_e32 v53, v53, v157
	ds_read_b128 v[154:157], v2 offset:32
	s_waitcnt lgkmcnt(0)
	v_mul_f32_e32 v38, v38, v154
	v_mul_f32_e32 v54, v54, v154
	v_mul_f32_e32 v39, v39, v155
	v_mul_f32_e32 v55, v55, v155
	v_mul_f32_e32 v40, v40, v156
	v_mul_f32_e32 v56, v56, v156
	v_mul_f32_e32 v41, v41, v157
	v_mul_f32_e32 v57, v57, v157
	ds_read_b128 v[154:157], v2 offset:64
	s_waitcnt lgkmcnt(0)
	v_mul_f32_e32 v42, v42, v154
	v_mul_f32_e32 v58, v58, v154
	v_mul_f32_e32 v43, v43, v155
	v_mul_f32_e32 v59, v59, v155
	v_mul_f32_e32 v44, v44, v156
	v_mul_f32_e32 v60, v60, v156
	v_mul_f32_e32 v45, v45, v157
	v_mul_f32_e32 v61, v61, v157
	ds_read_b128 v[154:157], v2 offset:96
	s_waitcnt lgkmcnt(0)
	v_mul_f32_e32 v46, v46, v154
	v_mul_f32_e32 v62, v62, v154
	v_mul_f32_e32 v47, v47, v155
	v_mul_f32_e32 v63, v63, v155
	v_mul_f32_e32 v48, v48, v156
	v_mul_f32_e32 v64, v64, v156
	v_mul_f32_e32 v49, v49, v157
	v_mul_f32_e32 v65, v65, v157
.Lmy_nors_37:
	s_waitcnt lgkmcnt(6)
	v_add_u32_e32 v2, 0x4000, v237
	v_mfma_f32_32x32x16_bf16 v[142:157], v[218:221], v[4:7], v[66:81]
	v_exp_f32_e32 v82, v82
	v_exp_f32_e32 v83, v83
	v_exp_f32_e32 v84, v84
	v_add_f32_e32 v27, v82, v83
	v_exp_f32_e32 v85, v85
	v_mfma_f32_32x32x16_bf16 v[158:173], v[214:217], v[4:7], v[66:81]
	v_exp_f32_e32 v86, v86
	v_add_f32_e32 v27, v27, v84
	v_exp_f32_e32 v87, v87
	v_add_f32_e32 v27, v27, v85
	v_exp_f32_e32 v88, v88
	v_mfma_f32_32x32x16_bf16 v[142:157], v[210:213], v[8:11], v[142:157]
	v_add_f32_e32 v27, v27, v86
	v_exp_f32_e32 v89, v89
	v_add_f32_e32 v27, v27, v87
	v_add_f32_e32 v27, v27, v88
	v_add_f32_e32 v27, v27, v89
	v_mfma_f32_32x32x16_bf16 v[158:173], v[206:209], v[8:11], v[158:173]
	v_cvt_pk_bf16_f32 v82, v82, v83
	v_cvt_pk_bf16_f32 v83, v84, v85
	v_cvt_pk_bf16_f32 v84, v86, v87
	v_cvt_pk_bf16_f32 v85, v88, v89
	v_mfma_f32_32x32x16_bf16 v[142:157], v[202:205], v[12:15], v[142:157]
	v_exp_f32_e32 v90, v90
	v_exp_f32_e32 v91, v91
	v_exp_f32_e32 v92, v92
	v_add_f32_e32 v27, v27, v90
	v_exp_f32_e32 v93, v93
	v_mfma_f32_32x32x16_bf16 v[158:173], v[198:201], v[12:15], v[158:173]
	v_add_f32_e32 v27, v27, v91
	v_exp_f32_e32 v94, v94
	v_add_f32_e32 v27, v27, v92
	v_exp_f32_e32 v95, v95
	v_add_f32_e32 v27, v27, v93
	s_waitcnt lgkmcnt(0)
	s_waitcnt vmcnt(4)
	s_barrier
	v_mfma_f32_32x32x16_bf16 v[142:157], v[194:197], v[130:133], v[142:157]
	s_add_u32 m0, s57, 0x2000
	v_exp_f32_e32 v96, v96
	v_add_f32_e32 v27, v27, v94
	global_load_lds_dwordx4 v[28:29], off
	v_lshl_add_u64 v[28:29], v[28:29], 0, s[30:31]
	v_exp_f32_e32 v97, v97
	v_add_f32_e32 v27, v27, v95
	v_add_f32_e32 v27, v27, v96
	ds_read_b64_tr_b16 v[114:115], v2 offset:49152
	ds_read_b64_tr_b16 v[116:117], v2 offset:49664
	ds_read_b64_tr_b16 v[118:119], v2 offset:50176
	ds_read_b64_tr_b16 v[120:121], v2 offset:50688
	v_mfma_f32_32x32x16_bf16 v[158:173], v[190:193], v[130:133], v[158:173]
	s_add_u32 m0, s40, 0x9000
	v_add_f32_e32 v27, v27, v97
	v_cvt_pk_bf16_f32 v90, v90, v91
	global_load_lds_dwordx4 v[24:25], off
	v_lshl_add_u64 v[24:25], v[24:25], 0, s[30:31]
	v_cvt_pk_bf16_f32 v91, v92, v93
	v_cvt_pk_bf16_f32 v92, v94, v95
	v_cvt_pk_bf16_f32 v93, v96, v97
	ds_read_b64_tr_b16 v[122:123], v2 offset:51200
	ds_read_b64_tr_b16 v[124:125], v2 offset:51712
	ds_read_b64_tr_b16 v[126:127], v2 offset:52224
	ds_read_b64_tr_b16 v[128:129], v2 offset:52736
	v_mfma_f32_32x32x16_bf16 v[142:157], v[186:189], v[134:137], v[142:157]
	v_exp_f32_e32 v98, v98
	v_exp_f32_e32 v99, v99
	v_exp_f32_e32 v100, v100
	v_add_f32_e32 v27, v27, v98
	v_exp_f32_e32 v101, v101
	ds_read_b64_tr_b16 v[240:241], v2 offset:53248
	ds_read_b64_tr_b16 v[242:243], v2 offset:53760
	ds_read_b64_tr_b16 v[244:245], v2 offset:54272
	ds_read_b64_tr_b16 v[246:247], v2 offset:54784
	v_mfma_f32_32x32x16_bf16 v[158:173], v[182:185], v[134:137], v[158:173]
	v_add_f32_e32 v27, v27, v99
	v_exp_f32_e32 v102, v102
	v_add_f32_e32 v27, v27, v100
	v_exp_f32_e32 v103, v103
	v_add_f32_e32 v27, v27, v101
	ds_read_b64_tr_b16 v[248:249], v2 offset:55296
	ds_read_b64_tr_b16 v[250:251], v2 offset:55808
	ds_read_b64_tr_b16 v[20:21], v2 offset:56320
	ds_read_b64_tr_b16 v[22:23], v2 offset:56832
	v_mfma_f32_32x32x16_bf16 v[142:157], v[178:181], v[138:141], v[142:157]
	v_exp_f32_e32 v104, v104
	v_add_f32_e32 v27, v27, v102
	v_exp_f32_e32 v105, v105
	v_add_f32_e32 v27, v27, v103
	v_add_f32_e32 v27, v27, v104
	v_mfma_f32_32x32x16_bf16 v[158:173], v[174:177], v[138:141], v[158:173]
	v_add_f32_e32 v27, v27, v105
	v_cvt_pk_bf16_f32 v98, v98, v99
	v_cvt_pk_bf16_f32 v99, v100, v101
	v_cvt_pk_bf16_f32 v100, v102, v103
	v_cvt_pk_bf16_f32 v101, v104, v105
	s_waitcnt lgkmcnt(0)
	v_mov_b32_e32 v2, v238
	v_mfma_f32_32x32x16_bf16 v[34:49], v[82:85], v[114:117], v[34:49]
	v_exp_f32_e32 v106, v106
	v_exp_f32_e32 v107, v107
	v_exp_f32_e32 v108, v108
	v_add_f32_e32 v27, v27, v106
	v_exp_f32_e32 v109, v109
	ds_read_b128 v[218:221], v2
	ds_read_b128 v[214:217], v2 offset:512
	ds_read_b128 v[210:213], v2 offset:2048
	v_mfma_f32_32x32x16_bf16 v[50:65], v[82:85], v[240:243], v[50:65]
	v_add_f32_e32 v27, v27, v107
	v_exp_f32_e32 v110, v110
	v_add_f32_e32 v27, v27, v108
	v_exp_f32_e32 v111, v111
	v_add_f32_e32 v27, v27, v109
	ds_read_b128 v[206:209], v2 offset:2560
	ds_read_b128 v[202:205], v2 offset:4096
	ds_read_b128 v[198:201], v2 offset:4608
	v_mfma_f32_32x32x16_bf16 v[34:49], v[90:93], v[118:121], v[34:49]
	v_exp_f32_e32 v112, v112
	v_add_f32_e32 v27, v27, v110
	v_exp_f32_e32 v113, v113
	v_add_f32_e32 v27, v27, v111
	v_add_f32_e32 v27, v27, v112
	ds_read_b128 v[194:197], v2 offset:6144
	ds_read_b128 v[190:193], v2 offset:6656
	ds_read_b128 v[186:189], v2 offset:8192
	v_mfma_f32_32x32x16_bf16 v[50:65], v[90:93], v[244:247], v[50:65]
	v_add_f32_e32 v27, v27, v113
	v_cvt_pk_bf16_f32 v106, v106, v107
	v_cvt_pk_bf16_f32 v107, v108, v109
	v_cvt_pk_bf16_f32 v108, v110, v111
	v_cvt_pk_bf16_f32 v109, v112, v113
	v_add_f32_e32 v236, v236, v27
	ds_read_b128 v[182:185], v2 offset:8704
	ds_read_b128 v[178:181], v2 offset:10240
	ds_read_b128 v[174:177], v2 offset:10752
	v_mfma_f32_32x32x16_bf16 v[34:49], v[98:101], v[122:125], v[34:49]
	v_max3_f32 v19, v142, v143, v144
	v_max3_f32 v26, v145, v146, v147
	v_max3_f32 v19, v19, v148, v149
	v_max3_f32 v26, v26, v150, v151
	v_mfma_f32_32x32x16_bf16 v[50:65], v[98:101], v[248:251], v[50:65]
	v_max3_f32 v19, v19, v152, v153
	v_max3_f32 v26, v26, v154, v155
	v_max3_f32 v19, v19, v156, v157
	v_max3_f32 v26, v26, v158, v159
	v_mfma_f32_32x32x16_bf16 v[34:49], v[106:109], v[126:129], v[34:49]
	v_max3_f32 v19, v19, v160, v161
	v_max3_f32 v26, v26, v162, v163
	v_max3_f32 v19, v19, v164, v165
	v_max3_f32 v26, v26, v166, v167
	v_mfma_f32_32x32x16_bf16 v[50:65], v[106:109], v[20:23], v[50:65]
	v_max3_f32 v19, v19, v168, v169
	v_max3_f32 v26, v26, v170, v171
	v_max3_f32 v19, v19, v172, v173
	v_max_f32_e32 v19, v19, v26
	v_cmp_lt_f32_e32 vcc, s41, v19
	s_cbranch_vccz .Lmy_nors_38
	s_nop 15
	s_nop 15
	v_mov_b32_e32 v26, v19
	s_nop 1
	v_permlane32_swap_b32_e32 v19, v26
	v_max_f32_e32 v19, v19, v26
	v_max_f32_e32 v19, v19, v19
	v_max_f32_e32 v90, 0, v19
	v_exp_f32_e64 v91, -v90
	v_add_f32_e32 v239, v239, v90
	v_xor_b32_e32 v66, 0x80000000, v239
	v_mov_b32_e32 v67, v66
	v_mov_b32_e32 v68, v66
	v_mov_b32_e32 v69, v66
	v_mov_b32_e32 v70, v66
	v_mov_b32_e32 v71, v66
	v_mov_b32_e32 v72, v66
	v_mov_b32_e32 v73, v66
	v_mov_b32_e32 v74, v66
	v_mov_b32_e32 v75, v66
	v_mov_b32_e32 v76, v66
	v_mov_b32_e32 v77, v66
	v_mov_b32_e32 v78, v66
	v_mov_b32_e32 v79, v66
	v_mov_b32_e32 v80, v66
	v_mov_b32_e32 v81, v66
	v_sub_f32_e32 v142, v142, v90
	v_sub_f32_e32 v143, v143, v90
	v_sub_f32_e32 v144, v144, v90
	v_sub_f32_e32 v145, v145, v90
	v_sub_f32_e32 v146, v146, v90
	v_sub_f32_e32 v147, v147, v90
	v_sub_f32_e32 v148, v148, v90
	v_sub_f32_e32 v149, v149, v90
	v_sub_f32_e32 v150, v150, v90
	v_sub_f32_e32 v151, v151, v90
	v_sub_f32_e32 v152, v152, v90
	v_sub_f32_e32 v153, v153, v90
	v_sub_f32_e32 v154, v154, v90
	v_sub_f32_e32 v155, v155, v90
	v_sub_f32_e32 v156, v156, v90
	v_sub_f32_e32 v157, v157, v90
	v_sub_f32_e32 v158, v158, v90
	v_sub_f32_e32 v159, v159, v90
	v_sub_f32_e32 v160, v160, v90
	v_sub_f32_e32 v161, v161, v90
	v_sub_f32_e32 v162, v162, v90
	v_sub_f32_e32 v163, v163, v90
	v_sub_f32_e32 v164, v164, v90
	v_sub_f32_e32 v165, v165, v90
	v_sub_f32_e32 v166, v166, v90
	v_sub_f32_e32 v167, v167, v90
	v_sub_f32_e32 v168, v168, v90
	v_sub_f32_e32 v169, v169, v90
	v_sub_f32_e32 v170, v170, v90
	v_sub_f32_e32 v171, v171, v90
	v_sub_f32_e32 v172, v172, v90
	v_sub_f32_e32 v173, v173, v90
	v_mul_f32_e32 v236, v236, v91
	s_mov_b64 s[96:97], exec
	s_and_b64 exec, exec, s[8:9]
	ds_write_b32 v235, v91
	s_mov_b64 exec, s[96:97]
	v_lshl_add_u32 v2, v228, 4, s47
	ds_read_b128 v[94:97], v2 offset:0
	s_waitcnt lgkmcnt(0)
	v_mul_f32_e32 v34, v34, v94
	v_mul_f32_e32 v50, v50, v94
	v_mul_f32_e32 v35, v35, v95
	v_mul_f32_e32 v51, v51, v95
	v_mul_f32_e32 v36, v36, v96
	v_mul_f32_e32 v52, v52, v96
	v_mul_f32_e32 v37, v37, v97
	v_mul_f32_e32 v53, v53, v97
	ds_read_b128 v[94:97], v2 offset:32
	s_waitcnt lgkmcnt(0)
	v_mul_f32_e32 v38, v38, v94
	v_mul_f32_e32 v54, v54, v94
	v_mul_f32_e32 v39, v39, v95
	v_mul_f32_e32 v55, v55, v95
	v_mul_f32_e32 v40, v40, v96
	v_mul_f32_e32 v56, v56, v96
	v_mul_f32_e32 v41, v41, v97
	v_mul_f32_e32 v57, v57, v97
	ds_read_b128 v[94:97], v2 offset:64
	s_waitcnt lgkmcnt(0)
	v_mul_f32_e32 v42, v42, v94
	v_mul_f32_e32 v58, v58, v94
	v_mul_f32_e32 v43, v43, v95
	v_mul_f32_e32 v59, v59, v95
	v_mul_f32_e32 v44, v44, v96
	v_mul_f32_e32 v60, v60, v96
	v_mul_f32_e32 v45, v45, v97
	v_mul_f32_e32 v61, v61, v97
	ds_read_b128 v[94:97], v2 offset:96
	s_waitcnt lgkmcnt(0)
	v_mul_f32_e32 v46, v46, v94
	v_mul_f32_e32 v62, v62, v94
	v_mul_f32_e32 v47, v47, v95
	v_mul_f32_e32 v63, v63, v95
	v_mul_f32_e32 v48, v48, v96
	v_mul_f32_e32 v64, v64, v96
	v_mul_f32_e32 v49, v49, v97
	v_mul_f32_e32 v65, v65, v97

.Lmy_tf_41:
	s_waitcnt lgkmcnt(6)
	v_mov_b32_e32 v2, v237
	v_mfma_f32_32x32x16_bf16 v[142:157], v[218:221], v[4:7], v[66:81]
	v_exp_f32_e32 v82, v82
	v_exp_f32_e32 v83, v83
	v_exp_f32_e32 v84, v84
	v_add_f32_e32 v27, v82, v83
	v_exp_f32_e32 v85, v85
	v_mfma_f32_32x32x16_bf16 v[158:173], v[214:217], v[4:7], v[66:81]
	v_exp_f32_e32 v86, v86
	v_add_f32_e32 v27, v27, v84
	v_exp_f32_e32 v87, v87
	v_add_f32_e32 v27, v27, v85
	v_exp_f32_e32 v88, v88
	v_mfma_f32_32x32x16_bf16 v[142:157], v[210:213], v[8:11], v[142:157]
	v_add_f32_e32 v27, v27, v86
	v_exp_f32_e32 v89, v89
	v_add_f32_e32 v27, v27, v87
	v_add_f32_e32 v27, v27, v88
	v_add_f32_e32 v27, v27, v89
	v_mfma_f32_32x32x16_bf16 v[158:173], v[206:209], v[8:11], v[158:173]
	v_cvt_pk_bf16_f32 v82, v82, v83
	v_cvt_pk_bf16_f32 v83, v84, v85
	v_cvt_pk_bf16_f32 v84, v86, v87
	v_cvt_pk_bf16_f32 v85, v88, v89
	v_mfma_f32_32x32x16_bf16 v[142:157], v[202:205], v[12:15], v[142:157]
	v_exp_f32_e32 v90, v90
	v_exp_f32_e32 v91, v91
	v_exp_f32_e32 v92, v92
	v_add_f32_e32 v27, v27, v90
	v_exp_f32_e32 v93, v93
	v_mfma_f32_32x32x16_bf16 v[158:173], v[198:201], v[12:15], v[158:173]
	v_add_f32_e32 v27, v27, v91
	v_exp_f32_e32 v94, v94
	v_add_f32_e32 v27, v27, v92
	v_exp_f32_e32 v95, v95
	v_add_f32_e32 v27, v27, v93
	s_waitcnt lgkmcnt(0)
	s_waitcnt vmcnt(2)
	s_barrier
	v_mfma_f32_32x32x16_bf16 v[142:157], v[194:197], v[130:133], v[142:157]
	s_add_u32 m0, s57, 0x6000
	v_exp_f32_e32 v96, v96
	v_add_f32_e32 v27, v27, v94
	global_load_lds_dwordx4 v[28:29], off
	v_lshl_add_u64 v[28:29], v[28:29], 0, s[30:31]
	v_exp_f32_e32 v97, v97
	v_add_f32_e32 v27, v27, v95
	v_add_f32_e32 v27, v27, v96
	ds_read_b64_tr_b16 v[114:115], v2 offset:49152
	ds_read_b64_tr_b16 v[116:117], v2 offset:49664
	ds_read_b64_tr_b16 v[118:119], v2 offset:50176
	ds_read_b64_tr_b16 v[120:121], v2 offset:50688
	v_mfma_f32_32x32x16_bf16 v[158:173], v[190:193], v[130:133], v[158:173]
	v_add_f32_e32 v27, v27, v97
	v_cvt_pk_bf16_f32 v90, v90, v91
	v_cvt_pk_bf16_f32 v91, v92, v93
	v_cvt_pk_bf16_f32 v92, v94, v95
	v_cvt_pk_bf16_f32 v93, v96, v97
	ds_read_b64_tr_b16 v[122:123], v2 offset:51200
	ds_read_b64_tr_b16 v[124:125], v2 offset:51712
	ds_read_b64_tr_b16 v[126:127], v2 offset:52224
	ds_read_b64_tr_b16 v[128:129], v2 offset:52736
	v_mfma_f32_32x32x16_bf16 v[142:157], v[186:189], v[134:137], v[142:157]
	v_exp_f32_e32 v98, v98
	v_exp_f32_e32 v99, v99
	v_exp_f32_e32 v100, v100
	v_add_f32_e32 v27, v27, v98
	v_exp_f32_e32 v101, v101
	ds_read_b64_tr_b16 v[240:241], v2 offset:53248
	ds_read_b64_tr_b16 v[242:243], v2 offset:53760
	ds_read_b64_tr_b16 v[244:245], v2 offset:54272
	ds_read_b64_tr_b16 v[246:247], v2 offset:54784
	v_mfma_f32_32x32x16_bf16 v[158:173], v[182:185], v[134:137], v[158:173]
	v_add_f32_e32 v27, v27, v99
	v_exp_f32_e32 v102, v102
	v_add_f32_e32 v27, v27, v100
	v_exp_f32_e32 v103, v103
	v_add_f32_e32 v27, v27, v101
	ds_read_b64_tr_b16 v[248:249], v2 offset:55296
	ds_read_b64_tr_b16 v[250:251], v2 offset:55808
	ds_read_b64_tr_b16 v[20:21], v2 offset:56320
	ds_read_b64_tr_b16 v[22:23], v2 offset:56832
	v_mfma_f32_32x32x16_bf16 v[142:157], v[178:181], v[138:141], v[142:157]
	v_exp_f32_e32 v104, v104
	v_add_f32_e32 v27, v27, v102
	v_exp_f32_e32 v105, v105
	v_add_f32_e32 v27, v27, v103
	v_add_f32_e32 v27, v27, v104
	v_mfma_f32_32x32x16_bf16 v[158:173], v[174:177], v[138:141], v[158:173]
	v_add_f32_e32 v27, v27, v105
	v_cvt_pk_bf16_f32 v98, v98, v99
	v_cvt_pk_bf16_f32 v99, v100, v101
	v_cvt_pk_bf16_f32 v100, v102, v103
	v_cvt_pk_bf16_f32 v101, v104, v105
	s_waitcnt lgkmcnt(0)
	v_add_u32_e32 v2, 0x6000, v238
	v_mfma_f32_32x32x16_bf16 v[34:49], v[82:85], v[114:117], v[34:49]
	v_exp_f32_e32 v106, v106
	v_exp_f32_e32 v107, v107
	v_exp_f32_e32 v108, v108
	v_add_f32_e32 v27, v27, v106
	v_exp_f32_e32 v109, v109
	s_cmp_gt_u32 s71, 1
	s_cbranch_scc0 .Lmy_nok_44
	ds_read_b128 v[218:221], v2
	ds_read_b128 v[214:217], v2 offset:512
	ds_read_b128 v[210:213], v2 offset:2048
	ds_read_b128 v[206:209], v2 offset:2560
	ds_read_b128 v[202:205], v2 offset:4096
	ds_read_b128 v[198:201], v2 offset:4608
	ds_read_b128 v[194:197], v2 offset:6144
	ds_read_b128 v[190:193], v2 offset:6656
	ds_read_b128 v[186:189], v2 offset:8192
	ds_read_b128 v[182:185], v2 offset:8704
	ds_read_b128 v[178:181], v2 offset:10240
	ds_read_b128 v[174:177], v2 offset:10752
